# P6 back-substitution: v_fmac_f32_e32 with pre-negated L tiles (4-byte encodings) and removal of inter-asm-block nop padding; on top of P5 load batching
# baseline (speedup 1.0000x reference)
.LBB0_685:
	s_or_b64 exec, exec, s[62:63]
	s_waitcnt lgkmcnt(0)
	v_sub_f32_e32 v43, v131, v43
	v_mul_f32_e32 v43, 0x3fb8aa3b, v43
	v_sub_f32_e32 v42, v131, v42
	v_exp_f32_e32 v43, v43
	v_mul_f32_e32 v42, 0x3fb8aa3b, v42
	v_sub_f32_e32 v41, v131, v41
	v_exp_f32_e32 v42, v42
	v_mul_f32_e32 v41, 0x3fb8aa3b, v41
	v_sub_f32_e32 v40, v131, v40
	v_exp_f32_e32 v41, v41
	v_mul_f32_e32 v40, 0x3fb8aa3b, v40
	v_mul_f32_e32 v44, 0x3db504f3, v49
	v_exp_f32_e32 v40, v40
	v_mul_f32_e32 v43, v44, v43
	v_mul_f32_e32 v44, 0x3db504f3, v48
	v_mul_f32_e32 v42, v44, v42
	v_mul_f32_e32 v44, 0x3db504f3, v47
	v_mul_f32_e32 v41, v44, v41
	v_mul_f32_e32 v44, 0x3db504f3, v46
	v_sub_f32_e32 v45, v162, v131
	v_mul_f32_e32 v40, v44, v40
	v_sub_f32_e32 v44, v162, v130
	v_mul_f32_e32 v45, 0x3fb8aa3b, v45
	v_mul_f32_e32 v44, 0x3fb8aa3b, v44
	v_exp_f32_e32 v45, v45
	v_exp_f32_e32 v44, v44
	v_mul_f32_e32 v17, v17, v163
	v_mul_f32_e32 v33, v33, v163
	v_mul_f32_e32 v17, v17, v45
	v_mul_f32_e32 v211, v33, v44
	v_cndmask_b32_e64 v62, 0, v17, s[60:61]
	v_sub_f32_e32 v17, v160, v130
	v_sub_f32_e32 v33, v160, v131
	v_mul_f32_e32 v17, 0x3fb8aa3b, v17
	v_mul_f32_e32 v33, 0x3fb8aa3b, v33
	v_exp_f32_e32 v17, v17
	v_exp_f32_e32 v33, v33
	v_mul_f32_e32 v32, v32, v161
	v_mul_f32_e32 v16, v16, v161
	v_mul_f32_e32 v212, v32, v17
	v_mul_f32_e32 v16, v16, v33
	v_sub_f32_e32 v17, v158, v131
	v_cndmask_b32_e64 v66, 0, v16, s[58:59]
	v_sub_f32_e32 v16, v158, v130
	v_mul_f32_e32 v17, 0x3fb8aa3b, v17
	v_mul_f32_e32 v16, 0x3fb8aa3b, v16
	v_exp_f32_e32 v17, v17
	v_exp_f32_e32 v16, v16
	v_mul_f32_e32 v15, v15, v159
	v_mul_f32_e32 v31, v31, v159
	v_mul_f32_e32 v15, v15, v17
	v_mul_f32_e32 v213, v31, v16
	v_cndmask_b32_e64 v70, 0, v15, s[56:57]
	v_sub_f32_e32 v15, v156, v130
	v_sub_f32_e32 v16, v156, v131
	v_mul_f32_e32 v15, 0x3fb8aa3b, v15
	v_mul_f32_e32 v16, 0x3fb8aa3b, v16
	v_exp_f32_e32 v15, v15
	v_exp_f32_e32 v16, v16
	v_mul_f32_e32 v17, v30, v157
	v_mul_f32_e32 v14, v14, v157
	v_mul_f32_e32 v214, v17, v15
	v_mul_f32_e32 v14, v14, v16
	v_sub_f32_e32 v15, v154, v130
	v_sub_f32_e32 v16, v154, v131
	v_mul_f32_e32 v15, 0x3fb8aa3b, v15
	v_mul_f32_e32 v16, 0x3fb8aa3b, v16
	v_exp_f32_e32 v15, v15
	v_exp_f32_e32 v16, v16
	v_mul_f32_e32 v17, v29, v155
	v_mul_f32_e32 v13, v13, v155
	v_mul_f32_e32 v215, v17, v15
	v_mul_f32_e32 v13, v13, v16
	v_sub_f32_e32 v15, v152, v131
	v_cndmask_b32_e64 v74, 0, v13, s[52:53]
	v_sub_f32_e32 v13, v152, v130
	v_mul_f32_e32 v15, 0x3fb8aa3b, v15
	v_mul_f32_e32 v13, 0x3fb8aa3b, v13
	v_exp_f32_e32 v15, v15
	v_exp_f32_e32 v13, v13
	v_mul_f32_e32 v12, v12, v153
	v_mul_f32_e32 v16, v28, v153
	v_mul_f32_e32 v12, v12, v15
	v_mul_f32_e32 v216, v16, v13
	v_cndmask_b32_e64 v28, 0, v12, s[50:51]
	v_sub_f32_e32 v12, v150, v130
	v_sub_f32_e32 v13, v150, v131
	v_mul_f32_e32 v12, 0x3fb8aa3b, v12
	v_mul_f32_e32 v13, 0x3fb8aa3b, v13
	v_exp_f32_e32 v12, v12
	v_exp_f32_e32 v13, v13
	v_mul_f32_e32 v15, v27, v151
	v_mul_f32_e32 v11, v11, v151
	v_mul_f32_e32 v217, v15, v12
	v_mul_f32_e32 v11, v11, v13
	v_sub_f32_e32 v12, v148, v131
	v_cndmask_b32_e64 v78, 0, v11, s[48:49]
	v_sub_f32_e32 v11, v148, v130
	v_mul_f32_e32 v12, 0x3fb8aa3b, v12
	v_mul_f32_e32 v11, 0x3fb8aa3b, v11
	v_exp_f32_e32 v12, v12
	v_exp_f32_e32 v11, v11
	v_mul_f32_e32 v10, v10, v149
	v_mul_f32_e32 v13, v26, v149
	v_mul_f32_e32 v10, v10, v12
	v_mul_f32_e32 v218, v13, v11
	v_cndmask_b32_e64 v82, 0, v10, s[46:47]
	v_sub_f32_e32 v10, v146, v130
	v_sub_f32_e32 v11, v146, v131
	v_mul_f32_e32 v10, 0x3fb8aa3b, v10
	v_mul_f32_e32 v11, 0x3fb8aa3b, v11
	v_exp_f32_e32 v10, v10
	v_exp_f32_e32 v11, v11
	v_mul_f32_e32 v12, v25, v147
	v_mul_f32_e32 v9, v9, v147
	v_mul_f32_e32 v219, v12, v10
	v_mul_f32_e32 v9, v9, v11
	v_sub_f32_e32 v10, v144, v131
	v_cndmask_b32_e64 v84, 0, v9, s[44:45]
	v_sub_f32_e32 v9, v144, v130
	v_mul_f32_e32 v10, 0x3fb8aa3b, v10
	v_mul_f32_e32 v9, 0x3fb8aa3b, v9
	v_exp_f32_e32 v10, v10
	v_exp_f32_e32 v9, v9
	v_mul_f32_e32 v8, v8, v145
	v_mul_f32_e32 v11, v24, v145
	v_mul_f32_e32 v8, v8, v10
	v_mul_f32_e32 v220, v11, v9
	v_cndmask_b32_e64 v24, 0, v8, s[42:43]
	v_sub_f32_e32 v8, v142, v130
	v_sub_f32_e32 v9, v142, v131
	v_mul_f32_e32 v8, 0x3fb8aa3b, v8
	v_mul_f32_e32 v9, 0x3fb8aa3b, v9
	v_exp_f32_e32 v8, v8
	v_exp_f32_e32 v9, v9
	v_mul_f32_e32 v10, v23, v143
	v_mul_f32_e32 v7, v7, v143
	v_mul_f32_e32 v221, v10, v8
	v_mul_f32_e32 v7, v7, v9
	v_sub_f32_e32 v8, v140, v131
	v_cndmask_b32_e64 v142, 0, v7, s[40:41]
	v_sub_f32_e32 v7, v140, v130
	v_mul_f32_e32 v8, 0x3fb8aa3b, v8
	v_mul_f32_e32 v7, 0x3fb8aa3b, v7
	v_exp_f32_e32 v8, v8
	v_exp_f32_e32 v7, v7
	v_mul_f32_e32 v6, v6, v141
	v_mul_f32_e32 v9, v22, v141
	v_mul_f32_e32 v6, v6, v8
	v_sub_f32_e32 v8, v138, v131
	v_mul_f32_e32 v222, v9, v7
	v_sub_f32_e32 v7, v138, v130
	v_mul_f32_e32 v8, 0x3fb8aa3b, v8
	v_mul_f32_e32 v7, 0x3fb8aa3b, v7
	v_exp_f32_e32 v8, v8
	v_exp_f32_e32 v7, v7
	v_mul_f32_e32 v5, v5, v139
	v_mul_f32_e32 v9, v21, v139
	v_mul_f32_e32 v5, v5, v8
	v_mul_f32_e32 v223, v9, v7
	v_cndmask_b32_e64 v140, 0, v5, s[8:9]
	v_sub_f32_e32 v5, v136, v130
	v_sub_f32_e32 v7, v136, v131
	v_mul_f32_e32 v5, 0x3fb8aa3b, v5
	v_mul_f32_e32 v7, 0x3fb8aa3b, v7
	v_exp_f32_e32 v5, v5
	v_exp_f32_e32 v7, v7
	v_mul_f32_e32 v8, v20, v137
	v_mul_f32_e32 v4, v4, v137
	v_mul_f32_e32 v224, v8, v5
	v_mul_f32_e32 v4, v4, v7
	v_sub_f32_e32 v5, v134, v131
	v_cndmask_b32_e64 v144, 0, v4, s[6:7]
	v_sub_f32_e32 v4, v134, v130
	v_mul_f32_e32 v5, 0x3fb8aa3b, v5
	v_mul_f32_e32 v4, 0x3fb8aa3b, v4
	v_exp_f32_e32 v5, v5
	v_exp_f32_e32 v4, v4
	v_mul_f32_e32 v3, v3, v135
	v_mul_f32_e32 v7, v19, v135
	v_mul_f32_e32 v3, v3, v5
	v_mul_f32_e32 v225, v7, v4
	v_cndmask_b32_e64 v146, v3, 0, s[4:5]
	v_sub_f32_e32 v3, v132, v130
	v_sub_f32_e32 v4, v132, v131
	v_mul_f32_e32 v3, 0x3fb8aa3b, v3
	v_mul_f32_e32 v4, 0x3fb8aa3b, v4
	v_exp_f32_e32 v3, v3
	v_exp_f32_e32 v4, v4
	v_mul_f32_e32 v5, v18, v133
	v_mul_f32_e32 v2, v2, v133
	v_mul_f32_e32 v226, v5, v3
	v_mul_f32_e32 v2, v2, v4
	v_cvt_pk_bf16_f32 v4, v40, v41
	v_cvt_pk_bf16_f32 v5, v42, v43
	global_store_dwordx2 v[34:35], v[4:5], off offset:48
	v_cvt_pk_bf16_f32 v4, v36, v38
	v_cvt_pk_bf16_f32 v5, v37, v39
	global_store_dwordx2 v[34:35], v[4:5], off offset:112
	v_cndmask_b32_e64 v14, 0, v14, s[54:55]
	v_cndmask_b32_e64 v6, 0, v6, s[38:39]
	v_cndmask_b32_e64 v2, 0, v2, s[0:1]
	v_lshlrev_b64 v[86:87], 1, v[128:129]
	s_add_u32 s0, s94, s28
	v_lshl_add_u64 v[4:5], v[122:123], 0, v[86:87]
	s_addc_u32 s1, s95, s29
	v_lshl_add_u64 v[98:99], s[0:1], 0, v[4:5]
	s_mov_b32 s4, 0x9000000
	v_add_co_u32_e32 v4, vcc, s4, v98
	s_mov_b32 s4, 0x9001000
	s_nop 0
	v_addc_co_u32_e32 v5, vcc, 0, v99, vcc
	v_add_co_u32_e32 v8, vcc, s4, v98
	v_lshlrev_b32_e32 v90, 4, v126
	s_nop 0
	v_addc_co_u32_e32 v9, vcc, 0, v99, vcc
	v_cmp_eq_u32_e32 vcc, 63, v126
	global_load_dwordx4 v[58:61], v[4:5], off offset:32
	global_load_dwordx4 v[54:57], v[4:5], off offset:64
	global_load_dwordx4 v[18:21], v[8:9], off offset:-4096
	global_load_dwordx4 v[50:53], v[4:5], off offset:96
	global_load_dwordx4 v[46:49], v[8:9], off
	global_load_dwordx4 v[42:45], v[8:9], off offset:32
	global_load_dwordx4 v[38:41], v[8:9], off offset:64
	global_load_dwordx4 v[34:37], v[8:9], off offset:96
	v_cndmask_b32_e64 v89, 0, 1.0, vcc
	v_cmp_eq_u32_e32 vcc, 62, v126
	v_add_u32_e32 v92, 0x1000, v90
	v_ashrrev_i32_e32 v93, 31, v92
	v_cndmask_b32_e64 v3, 0, 1.0, vcc
	v_cmp_eq_u32_e32 vcc, 61, v126
	v_lshl_add_u64 v[120:121], v[92:93], 1, s[0:1]
	v_add_u32_e32 v92, 0x1400, v90
	v_cndmask_b32_e64 v4, 0, 1.0, vcc
	v_cmp_eq_u32_e32 vcc, 60, v126
	v_ashrrev_i32_e32 v93, 31, v92
	v_lshl_add_u64 v[112:113], v[92:93], 1, s[0:1]
	v_cndmask_b32_e64 v8, 0, 1.0, vcc
	v_cmp_eq_u32_e32 vcc, 59, v126
	v_add_u32_e32 v92, 0x800, v90
	v_ashrrev_i32_e32 v91, 31, v90
	v_cndmask_b32_e64 v5, 0, 1.0, vcc
	v_cmp_eq_u32_e32 vcc, 58, v126
	v_ashrrev_i32_e32 v93, 31, v92
	v_add_u32_e32 v100, 0x1800, v90
	v_cndmask_b32_e64 v9, 0, 1.0, vcc
	v_cmp_eq_u32_e32 vcc, 57, v126
	v_lshl_add_u64 v[108:109], v[92:93], 1, s[0:1]
	v_add_u32_e32 v92, 0xc00, v90
	v_cndmask_b32_e64 v95, 0, 1.0, vcc
	v_cmp_eq_u32_e32 vcc, 56, v126
	s_nop 7
	s_mov_b32 s98, 0x80000000
	v_xor_b32_e32 v62, s98, v62
	v_xor_b32_e32 v66, s98, v66
	v_xor_b32_e32 v70, s98, v70
	v_xor_b32_e32 v14, s98, v14
	v_xor_b32_e32 v74, s98, v74
	v_xor_b32_e32 v28, s98, v28
	v_xor_b32_e32 v78, s98, v78
	v_xor_b32_e32 v82, s98, v82
	v_xor_b32_e32 v84, s98, v84
	v_xor_b32_e32 v24, s98, v24
	v_xor_b32_e32 v142, s98, v142
	v_xor_b32_e32 v6, s98, v6
	v_xor_b32_e32 v140, s98, v140
	v_xor_b32_e32 v144, s98, v144
	v_xor_b32_e32 v146, s98, v146
	v_xor_b32_e32 v2, s98, v2
	v_xor_b32_e32 v226, s98, v226
	v_xor_b32_e32 v225, s98, v225
	v_xor_b32_e32 v224, s98, v224
	v_xor_b32_e32 v223, s98, v223
	v_xor_b32_e32 v222, s98, v222
	v_xor_b32_e32 v221, s98, v221
	v_xor_b32_e32 v220, s98, v220
	v_xor_b32_e32 v219, s98, v219
	v_xor_b32_e32 v218, s98, v218
	v_xor_b32_e32 v217, s98, v217
	v_xor_b32_e32 v216, s98, v216
	v_xor_b32_e32 v215, s98, v215
	v_xor_b32_e32 v214, s98, v214
	v_xor_b32_e32 v213, s98, v213
	v_xor_b32_e32 v212, s98, v212
	v_xor_b32_e32 v211, s98, v211
	v_xor_b32_e32 v209, s98, v209
	v_xor_b32_e32 v207, s98, v207
	v_xor_b32_e32 v208, s98, v208
	v_xor_b32_e32 v205, s98, v205
	v_xor_b32_e32 v206, s98, v206
	v_xor_b32_e32 v203, s98, v203
	v_xor_b32_e32 v204, s98, v204
	v_xor_b32_e32 v201, s98, v201
	v_xor_b32_e32 v202, s98, v202
	v_xor_b32_e32 v199, s98, v199
	v_xor_b32_e32 v200, s98, v200
	v_xor_b32_e32 v197, s98, v197
	v_xor_b32_e32 v198, s98, v198
	v_xor_b32_e32 v195, s98, v195
	v_xor_b32_e32 v196, s98, v196
	v_xor_b32_e32 v194, s98, v194
	s_mov_b32 s54, 62
	v_readlane_b32 s4, v62, s54
	s_nop 1
	v_fmac_f32_e32 v3, s4, v89
	s_mov_b32 s55, 61
	v_cndmask_b32_e64 v181, 0, 1.0, vcc
	v_cmp_eq_u32_e32 vcc, 55, v126
	v_add_f32_e32 v88, 0, v3
	v_readlane_b32 s4, v66, s55
	s_nop 1
	v_fmac_f32_e32 v4, s4, v88
	v_ashrrev_i32_e32 v101, 31, v100
	v_cndmask_b32_e64 v11, 0, 1.0, vcc
	v_cmp_eq_u32_e32 vcc, 54, v126
	v_readlane_b32 s4, v62, s55
	s_nop 1
	v_fmac_f32_e32 v4, s4, v89
	v_lshl_add_u64 v[106:107], v[100:101], 1, s[0:1]
	v_ashrrev_i32_e32 v93, 31, v92
	v_cndmask_b32_e64 v97, 0, 1.0, vcc
	v_cmp_eq_u32_e32 vcc, 53, v126
	s_mov_b32 s56, 60
	v_lshl_add_u64 v[102:103], v[92:93], 1, s[0:1]
	v_cndmask_b32_e64 v13, 0, 1.0, vcc
	v_cmp_eq_u32_e32 vcc, 52, v126
	v_mov_b32_e32 v93, v123
	v_mov_b32_e32 v92, v123
	v_cndmask_b32_e64 v105, 0, 1.0, vcc
	v_cmp_eq_u32_e32 vcc, 51, v126
	s_mov_b32 s57, 59
	s_mov_b32 s53, 26
	v_cndmask_b32_e64 v17, 0, 1.0, vcc
	v_cmp_eq_u32_e32 vcc, 50, v126
	s_mov_b32 s58, 58
	v_mov_b32_e32 v94, v123
	v_cndmask_b32_e64 v111, 0, 1.0, vcc
	v_cmp_eq_u32_e32 vcc, 49, v126
	s_mov_b32 s52, 25
	s_mov_b32 s59, 57
	v_cndmask_b32_e64 v23, 0, 1.0, vcc
	v_cmp_eq_u32_e32 vcc, 48, v126
	v_mul_f32_e32 v10, 0x3fb8aa3b, v166
	v_mov_b32_e32 v180, v123
	v_cndmask_b32_e64 v115, 0, 1.0, vcc
	v_cmp_eq_u32_e32 vcc, 47, v126
	v_exp_f32_e32 v10, v10
	s_mov_b32 s51, 24
	v_cndmask_b32_e64 v27, 0, 1.0, vcc
	v_cmp_eq_u32_e32 vcc, 46, v126
	s_mov_b32 s60, 56
	v_mul_f32_e32 v210, v193, v10
	v_cndmask_b32_e64 v117, 0, 1.0, vcc
	v_cmp_eq_u32_e32 vcc, 45, v126
	v_mov_b32_e32 v10, v123
	s_mov_b32 s70, 23
	v_cndmask_b32_e64 v31, 0, 1.0, vcc
	v_cmp_eq_u32_e32 vcc, 44, v126
	s_mov_b32 s61, 55
	v_mov_b32_e32 v96, v123
	v_cndmask_b32_e64 v119, 0, 1.0, vcc
	v_cmp_eq_u32_e32 vcc, 43, v126
	s_mov_b32 s62, 54
	s_mov_b32 s71, 22
	v_cndmask_b32_e64 v33, 0, 1.0, vcc
	v_cmp_eq_u32_e32 vcc, 42, v126
	v_mov_b32_e32 v12, v123
	s_mov_b32 s63, 53
	v_cndmask_b32_e64 v129, 0, 1.0, vcc
	v_cmp_eq_u32_e32 vcc, 41, v126
	s_mov_b32 s72, 21
	v_mov_b32_e32 v104, v123
	v_cndmask_b32_e64 v65, 0, 1.0, vcc
	v_cmp_eq_u32_e32 vcc, 40, v126
	s_mov_b32 s73, 20
	v_mov_b32_e32 v16, v123
	v_cndmask_b32_e64 v131, 0, 1.0, vcc
	v_cmp_eq_u32_e32 vcc, 39, v126
	s_mov_b32 s64, 51
	s_mov_b32 s50, 19
	v_cndmask_b32_e64 v69, 0, 1.0, vcc
	v_cmp_eq_u32_e32 vcc, 38, v126
	v_mov_b32_e32 v110, v123
	s_mov_b32 s49, 18
	v_cndmask_b32_e64 v133, 0, 1.0, vcc
	v_cmp_eq_u32_e32 vcc, 37, v126
	s_mov_b32 s65, 50
	v_mov_b32_e32 v22, v123
	v_cndmask_b32_e64 v73, 0, 1.0, vcc
	v_cmp_eq_u32_e32 vcc, 36, v126
	s_mov_b32 s48, 17
	v_mov_b32_e32 v114, v123
	v_cndmask_b32_e64 v135, 0, 1.0, vcc
	v_cmp_eq_u32_e32 vcc, 35, v126
	s_mov_b32 s47, 16
	v_mov_b32_e32 v26, v123
	v_cndmask_b32_e64 v77, 0, 1.0, vcc
	v_cmp_eq_u32_e32 vcc, 34, v126
	s_mov_b32 s45, 15
	s_mov_b32 s66, 47
	v_cndmask_b32_e64 v137, 0, 1.0, vcc
	v_cmp_eq_u32_e32 vcc, 33, v126
	v_mov_b32_e32 v116, v123
	s_mov_b32 s39, 14
	v_cndmask_b32_e64 v81, 0, 1.0, vcc
	v_cmp_eq_u32_e32 vcc, 32, v126
	v_mov_b32_e32 v30, v123
	s_mov_b32 s38, 13
	v_cndmask_b32_e64 v139, 0, 1.0, vcc
	v_cmp_eq_u32_e32 vcc, 31, v126
	v_mov_b32_e32 v118, v123
	s_mov_b32 s43, 12
	v_cndmask_b32_e64 v153, 0, 1.0, vcc
	v_cmp_eq_u32_e32 vcc, 30, v126
	v_mov_b32_e32 v32, v123
	s_mov_b32 s67, 43
	v_cndmask_b32_e64 v141, 0, 1.0, vcc
	v_cmp_eq_u32_e32 vcc, 29, v126
	s_mov_b32 s42, 11
	v_mov_b32_e32 v128, v123
	v_cndmask_b32_e64 v159, 0, 1.0, vcc
	v_cmp_eq_u32_e32 vcc, 28, v126
	s_mov_b32 s46, 10
	s_lshl_b32 s4, s20, 4
	v_cndmask_b32_e64 v143, 0, 1.0, vcc
	v_cmp_eq_u32_e32 vcc, 27, v126
	v_mov_b32_e32 v64, v123
	s_or_b32 s4, s37, s4
	v_cndmask_b32_e64 v167, 0, 1.0, vcc
	v_cmp_eq_u32_e32 vcc, 26, v126
	s_mov_b32 s37, 9
	v_mov_b32_e32 v130, v123
	v_cndmask_b32_e64 v145, 0, 1.0, vcc
	v_cmp_eq_u32_e32 vcc, 25, v126
	s_mov_b32 s40, 8
	v_mov_b32_e32 v68, v123
	v_cndmask_b32_e64 v171, 0, 1.0, vcc
	v_cmp_eq_u32_e32 vcc, 24, v126
	s_mov_b32 s44, 7
	s_mov_b32 s68, 39
	v_cndmask_b32_e64 v147, 0, 1.0, vcc
	v_cmp_eq_u32_e32 vcc, 23, v126
	v_mov_b32_e32 v132, v123
	v_mov_b32_e32 v72, v123
	v_cndmask_b32_e64 v175, 0, 1.0, vcc
	v_cmp_eq_u32_e32 vcc, 22, v126
	v_mov_b32_e32 v134, v123
	v_mov_b32_e32 v76, v123
	v_cndmask_b32_e64 v149, 0, 1.0, vcc
	v_cmp_eq_u32_e32 vcc, 21, v126
	s_mov_b32 s69, 35
	s_mov_b32 s12, 3
	v_cndmask_b32_e64 v179, 0, 1.0, vcc
	v_cmp_eq_u32_e32 vcc, 20, v126
	v_mov_b32_e32 v136, v123
	v_mov_b32_e32 v80, v123
	v_cndmask_b32_e64 v151, 0, 1.0, vcc
	v_cmp_eq_u32_e32 vcc, 19, v126
	v_mov_b32_e32 v138, v123
	v_mov_b32_e32 v152, v123
	v_cndmask_b32_e64 v177, 0, 1.0, vcc
	v_cmp_eq_u32_e32 vcc, 18, v126
	s_mov_b32 s41, 31
	s_mov_b32 s20, 63
	v_cndmask_b32_e64 v157, 0, 1.0, vcc
	v_cmp_eq_u32_e32 vcc, 17, v126
	v_mov_b32_e32 v158, v123
	v_mov_b32_e32 v166, v123
	v_cndmask_b32_e64 v173, 0, 1.0, vcc
	v_cmp_eq_u32_e32 vcc, 16, v126
	v_mov_b32_e32 v170, v123
	v_mov_b32_e32 v174, v123
	v_cndmask_b32_e64 v165, 0, 1.0, vcc
	v_cmp_eq_u32_e32 vcc, 15, v126
	v_mov_b32_e32 v148, v123
	v_mov_b32_e32 v178, v123
	v_cndmask_b32_e64 v169, 0, 1.0, vcc
	v_cmp_eq_u32_e32 vcc, 14, v126
	v_mov_b32_e32 v150, v123
	v_mov_b32_e32 v176, v123
	v_cndmask_b32_e64 v163, 0, 1.0, vcc
	v_cmp_eq_u32_e32 vcc, 13, v126
	v_mov_b32_e32 v156, v123
	v_mov_b32_e32 v172, v123
	v_cndmask_b32_e64 v161, 0, 1.0, vcc
	v_cmp_eq_u32_e32 vcc, 12, v126
	v_mov_b32_e32 v164, v123
	v_mov_b32_e32 v168, v123
	v_cndmask_b32_e64 v155, 0, 1.0, vcc
	v_cmp_eq_u32_e32 vcc, 11, v126
	v_mov_b32_e32 v162, v123
	v_mov_b32_e32 v160, v123
	v_cndmask_b32_e64 v85, 0, 1.0, vcc
	v_cmp_eq_u32_e32 vcc, 10, v126
	v_mov_b32_e32 v154, v123
	s_ashr_i32 s5, s4, 31
	v_cndmask_b32_e64 v83, 0, 1.0, vcc
	v_cmp_eq_u32_e32 vcc, 9, v126
	s_nop 1
	v_cndmask_b32_e64 v79, 0, 1.0, vcc
	v_cmp_eq_u32_e32 vcc, 8, v126
	s_nop 1
	v_cndmask_b32_e64 v75, 0, 1.0, vcc
	v_cmp_eq_u32_e32 vcc, 7, v126
	s_nop 1
	v_cndmask_b32_e64 v71, 0, 1.0, vcc
	v_cmp_eq_u32_e32 vcc, 6, v126
	s_nop 1
	v_cndmask_b32_e64 v67, 0, 1.0, vcc
	v_cmp_eq_u32_e32 vcc, 5, v126
	s_nop 1
	v_cndmask_b32_e64 v63, 0, 1.0, vcc
	v_cmp_eq_u32_e32 vcc, 4, v126
	s_nop 1
	v_cndmask_b32_e64 v29, 0, 1.0, vcc
	v_cmp_eq_u32_e32 vcc, 3, v126
	s_nop 1
	v_cndmask_b32_e64 v25, 0, 1.0, vcc
	v_cmp_eq_u32_e32 vcc, 2, v126
	s_nop 1
	v_cndmask_b32_e64 v15, 0, 1.0, vcc
	v_cmp_eq_u32_e32 vcc, 1, v126
	s_nop 1
	v_cndmask_b32_e64 v7, 0, 1.0, vcc
	v_cmp_eq_u32_e32 vcc, 0, v126
	v_lshl_add_u64 v[126:127], v[90:91], 1, s[0:1]
	v_add_u32_e32 v90, 0x1c00, v90
	v_ashrrev_i32_e32 v91, 31, v90
	v_lshl_add_u64 v[100:101], v[90:91], 1, s[0:1]
	v_add_f32_e32 v91, 0, v4
	v_readlane_b32 s6, v70, s56
	s_nop 1
	v_fmac_f32_e32 v8, s6, v91
	v_mov_b32_e32 v4, v123
	v_readlane_b32 s6, v66, s56
	s_nop 1
	v_fmac_f32_e32 v8, s6, v88
	v_cndmask_b32_e64 v3, 0, 1.0, vcc
	v_readlane_b32 s6, v62, s56
	s_nop 1
	v_fmac_f32_e32 v8, s6, v89
	v_add_f32_e32 v90, 0, v8
	v_readlane_b32 s6, v14, s57
	v_readlane_b32 s7, v70, s57
	v_readlane_b32 s8, v66, s57
	v_readlane_b32 s9, v62, s57
	v_fmac_f32_e32 v5, s6, v90
	v_fmac_f32_e32 v93, s7, v91
	v_fmac_f32_e32 v92, s8, v88
	v_fmac_f32_e32 v4, s9, v89
	v_mov_b32_e32 v8, v123
	v_pk_add_f32 v[4:5], v[92:93], v[4:5]
	v_mov_b32_e32 v93, v123
	v_mov_b32_e32 v92, v123
	v_pk_add_f32 v[4:5], v[4:5], v[4:5] op_sel:[0,1] op_sel_hi:[1,0]
	s_nop 0
	v_readlane_b32 s6, v62, s53
	v_readlane_b32 s7, v14, s58
	v_readlane_b32 s8, v70, s58
	v_readlane_b32 s9, v66, s58
	v_fmac_f32_e32 v9, s6, v4
	v_fmac_f32_e32 v93, s7, v90
	v_fmac_f32_e32 v92, s8, v91
	v_fmac_f32_e32 v8, s9, v88
	v_readlane_b32 s6, v62, s58
	s_nop 1
	v_fmac_f32_e32 v9, s6, v89
	v_pk_add_f32 v[8:9], v[92:93], v[8:9]
	s_nop 0
	v_pk_add_f32 v[92:93], v[8:9], v[8:9] op_sel:[0,1] op_sel_hi:[1,0]
	v_mov_b32_e32 v9, v123
	v_mov_b32_e32 v8, v123
	v_readlane_b32 s6, v66, s52
	v_readlane_b32 s7, v62, s52
	v_readlane_b32 s8, v14, s59
	v_readlane_b32 s9, v70, s59
	v_fmac_f32_e32 v95, s6, v92
	v_fmac_f32_e32 v9, s7, v4
	v_fmac_f32_e32 v8, s8, v90
	v_fmac_f32_e32 v94, s9, v91
	v_mov_b32_e32 v93, v4
	v_readlane_b32 s6, v66, s59
	s_nop 1
	v_fmac_f32_e32 v95, s6, v88
	v_readlane_b32 s6, v62, s59
	s_nop 1
	v_fmac_f32_e32 v95, s6, v89
	v_pk_add_f32 v[8:9], v[8:9], v[94:95]
	v_mov_b32_e32 v95, v123
	v_mov_b32_e32 v94, v123
	v_pk_add_f32 v[8:9], v[8:9], v[8:9] op_sel:[0,1] op_sel_hi:[1,0]
	s_nop 0
	v_readlane_b32 s6, v70, s51
	v_readlane_b32 s7, v66, s51
	v_readlane_b32 s8, v62, s51
	v_readlane_b32 s9, v14, s60
	v_fmac_f32_e32 v181, s6, v8
	v_fmac_f32_e32 v95, s7, v92
	v_fmac_f32_e32 v94, s8, v4
	v_fmac_f32_e32 v180, s9, v90
	v_readlane_b32 s6, v70, s60
	s_nop 1
	v_fmac_f32_e32 v181, s6, v91
	v_readlane_b32 s6, v66, s60
	s_nop 1
	v_fmac_f32_e32 v181, s6, v88
	v_readlane_b32 s6, v62, s60
	s_nop 1
	v_fmac_f32_e32 v181, s6, v89
	v_pk_add_f32 v[94:95], v[94:95], v[180:181]
	v_mov_b32_e32 v181, v123
	v_mov_b32_e32 v180, v123
	v_pk_add_f32 v[94:95], v[94:95], v[94:95] op_sel:[0,1] op_sel_hi:[1,0]
	s_nop 0
	v_readlane_b32 s6, v14, s70
	v_readlane_b32 s7, v70, s70
	v_readlane_b32 s8, v66, s70
	v_readlane_b32 s9, v62, s70
	v_fmac_f32_e32 v11, s6, v94
	v_fmac_f32_e32 v181, s7, v8
	v_fmac_f32_e32 v180, s8, v92
	v_fmac_f32_e32 v10, s9, v4
	v_mov_b32_e32 v95, v8
	v_readlane_b32 s6, v14, s61
	v_readlane_b32 s7, v70, s61
	v_readlane_b32 s8, v66, s61
	v_readlane_b32 s9, v62, s61
	v_fmac_f32_e32 v11, s6, v90
	v_fmac_f32_e32 v181, s7, v91
	v_fmac_f32_e32 v180, s8, v88
	v_fmac_f32_e32 v10, s9, v89
	v_pk_add_f32 v[10:11], v[180:181], v[10:11]
	v_mov_b32_e32 v181, v123
	v_mov_b32_e32 v180, v123
	v_pk_add_f32 v[10:11], v[10:11], v[10:11] op_sel:[0,1] op_sel_hi:[1,0]
	s_nop 0
	v_readlane_b32 s6, v74, s62
	v_readlane_b32 s7, v14, s71
	v_readlane_b32 s8, v70, s71
	v_readlane_b32 s9, v66, s71
	v_fmac_f32_e32 v97, s6, v10
	v_fmac_f32_e32 v181, s7, v94
	v_fmac_f32_e32 v180, s8, v8
	v_fmac_f32_e32 v96, s9, v92
	v_readlane_b32 s6, v62, s71
	v_readlane_b32 s7, v14, s62
	v_readlane_b32 s8, v70, s62
	v_readlane_b32 s9, v66, s62
	v_fmac_f32_e32 v97, s6, v4
	v_fmac_f32_e32 v181, s7, v90
	v_fmac_f32_e32 v180, s8, v91
	v_fmac_f32_e32 v96, s9, v88
	v_readlane_b32 s6, v62, s62
	s_nop 1
	v_fmac_f32_e32 v97, s6, v89
	v_pk_add_f32 v[96:97], v[180:181], v[96:97]
	v_mov_b32_e32 v181, v123
	v_mov_b32_e32 v180, v123
	v_pk_add_f32 v[96:97], v[96:97], v[96:97] op_sel:[0,1] op_sel_hi:[1,0]
	s_nop 0
	v_readlane_b32 s6, v28, s63
	v_readlane_b32 s7, v74, s63
	v_readlane_b32 s8, v14, s72
	v_readlane_b32 s9, v70, s72
	v_fmac_f32_e32 v13, s6, v96
	v_fmac_f32_e32 v181, s7, v10
	v_fmac_f32_e32 v180, s8, v94
	v_fmac_f32_e32 v12, s9, v8
	v_mov_b32_e32 v97, v10
	v_readlane_b32 s6, v66, s72
	v_readlane_b32 s7, v62, s72
	v_readlane_b32 s8, v14, s63
	v_readlane_b32 s9, v70, s63
	v_fmac_f32_e32 v13, s6, v92
	v_fmac_f32_e32 v181, s7, v4
	v_fmac_f32_e32 v180, s8, v90
	v_fmac_f32_e32 v12, s9, v91
	v_readlane_b32 s6, v66, s63
	s_nop 1
	v_fmac_f32_e32 v13, s6, v88
	v_readlane_b32 s6, v62, s63
	s_nop 1
	v_fmac_f32_e32 v13, s6, v89
	v_pk_add_f32 v[12:13], v[180:181], v[12:13]
	v_mov_b32_e32 v181, v123
	v_mov_b32_e32 v180, v123
	v_pk_add_f32 v[12:13], v[12:13], v[12:13] op_sel:[0,1] op_sel_hi:[1,0]
	s_nop 0
	v_readlane_b32 s6, v78, s22
	v_readlane_b32 s7, v28, s22
	v_readlane_b32 s8, v74, s22
	v_readlane_b32 s9, v14, s73
	v_fmac_f32_e32 v105, s6, v12
	v_fmac_f32_e32 v181, s7, v96
	v_fmac_f32_e32 v180, s8, v10
	v_fmac_f32_e32 v104, s9, v94
	v_readlane_b32 s6, v70, s73
	v_readlane_b32 s7, v66, s73
	v_readlane_b32 s8, v62, s73
	v_readlane_b32 s9, v14, s22
	v_fmac_f32_e32 v105, s6, v8
	v_fmac_f32_e32 v181, s7, v92
	v_fmac_f32_e32 v180, s8, v4
	v_fmac_f32_e32 v104, s9, v90
	v_readlane_b32 s6, v70, s22
	s_nop 1
	v_fmac_f32_e32 v105, s6, v91
	v_readlane_b32 s6, v66, s22
	s_nop 1
	v_fmac_f32_e32 v105, s6, v88
	v_readlane_b32 s6, v62, s22
	s_nop 1
	v_fmac_f32_e32 v105, s6, v89
	v_pk_add_f32 v[104:105], v[180:181], v[104:105]
	v_mov_b32_e32 v181, v123
	v_mov_b32_e32 v180, v123
	v_pk_add_f32 v[104:105], v[104:105], v[104:105] op_sel:[0,1] op_sel_hi:[1,0]
	s_nop 0
	v_readlane_b32 s6, v82, s64
	v_readlane_b32 s7, v78, s64
	v_readlane_b32 s8, v28, s64
	v_readlane_b32 s9, v74, s64
	v_fmac_f32_e32 v17, s6, v104
	v_fmac_f32_e32 v181, s7, v12
	v_fmac_f32_e32 v180, s8, v96
	v_fmac_f32_e32 v16, s9, v10
	v_mov_b32_e32 v105, v12
	v_readlane_b32 s6, v14, s50
	v_readlane_b32 s7, v70, s50
	v_readlane_b32 s8, v66, s50
	v_readlane_b32 s9, v62, s50
	v_fmac_f32_e32 v17, s6, v94
	v_fmac_f32_e32 v181, s7, v8
	v_fmac_f32_e32 v180, s8, v92
	v_fmac_f32_e32 v16, s9, v4
	v_readlane_b32 s6, v14, s64
	v_readlane_b32 s7, v70, s64
	v_readlane_b32 s8, v66, s64
	v_readlane_b32 s9, v62, s64
	v_fmac_f32_e32 v17, s6, v90
	v_fmac_f32_e32 v181, s7, v91
	v_fmac_f32_e32 v180, s8, v88
	v_fmac_f32_e32 v16, s9, v89
	v_pk_add_f32 v[16:17], v[180:181], v[16:17]
	v_mov_b32_e32 v181, v123
	v_mov_b32_e32 v180, v123
	v_pk_add_f32 v[16:17], v[16:17], v[16:17] op_sel:[0,1] op_sel_hi:[1,0]
	s_nop 0
	v_readlane_b32 s6, v74, s49
	v_readlane_b32 s7, v82, s65
	v_readlane_b32 s8, v78, s65
	v_readlane_b32 s9, v28, s65
	v_fmac_f32_e32 v111, s6, v16
	v_fmac_f32_e32 v181, s7, v104
	v_fmac_f32_e32 v180, s8, v12
	v_fmac_f32_e32 v110, s9, v96
	v_readlane_b32 s6, v74, s65
	v_readlane_b32 s7, v14, s49
	v_readlane_b32 s8, v70, s49
	v_readlane_b32 s9, v66, s49
	v_fmac_f32_e32 v111, s6, v10
	v_fmac_f32_e32 v181, s7, v94
	v_fmac_f32_e32 v180, s8, v8
	v_fmac_f32_e32 v110, s9, v92
	v_readlane_b32 s6, v62, s49
	v_readlane_b32 s7, v14, s65
	v_readlane_b32 s8, v70, s65
	v_readlane_b32 s9, v66, s65
	v_fmac_f32_e32 v111, s6, v4
	v_fmac_f32_e32 v181, s7, v90
	v_fmac_f32_e32 v180, s8, v91
	v_fmac_f32_e32 v110, s9, v88
	v_readlane_b32 s6, v62, s65
	s_nop 1
	v_fmac_f32_e32 v111, s6, v89
	v_pk_add_f32 v[110:111], v[180:181], v[110:111]
	v_mov_b32_e32 v181, v123
	v_mov_b32_e32 v180, v123
	v_pk_add_f32 v[110:111], v[110:111], v[110:111] op_sel:[0,1] op_sel_hi:[1,0]
	s_nop 0
	v_readlane_b32 s6, v28, s48
	v_readlane_b32 s7, v74, s48
	v_readlane_b32 s8, v82, s21
	v_readlane_b32 s9, v78, s21
	v_fmac_f32_e32 v23, s6, v110
	v_fmac_f32_e32 v181, s7, v16
	v_fmac_f32_e32 v180, s8, v104
	v_fmac_f32_e32 v22, s9, v12
	v_mov_b32_e32 v111, v16
	v_readlane_b32 s6, v28, s21
	v_readlane_b32 s7, v74, s21
	v_readlane_b32 s8, v14, s48
	v_readlane_b32 s9, v70, s48
	v_fmac_f32_e32 v23, s6, v96
	v_fmac_f32_e32 v181, s7, v10
	v_fmac_f32_e32 v180, s8, v94
	v_fmac_f32_e32 v22, s9, v8
	v_readlane_b32 s6, v66, s48
	v_readlane_b32 s7, v62, s48
	v_readlane_b32 s8, v14, s21
	v_readlane_b32 s9, v70, s21
	v_fmac_f32_e32 v23, s6, v92
	v_fmac_f32_e32 v181, s7, v4
	v_fmac_f32_e32 v180, s8, v90
	v_fmac_f32_e32 v22, s9, v91
	v_readlane_b32 s6, v66, s21
	s_nop 1
	v_fmac_f32_e32 v23, s6, v88
	v_readlane_b32 s6, v62, s21
	s_nop 1
	v_fmac_f32_e32 v23, s6, v89
	v_pk_add_f32 v[22:23], v[180:181], v[22:23]
	v_mov_b32_e32 v181, v123
	v_mov_b32_e32 v180, v123
	v_pk_add_f32 v[22:23], v[22:23], v[22:23] op_sel:[0,1] op_sel_hi:[1,0]
	s_nop 0
	v_readlane_b32 s6, v78, s47
	v_readlane_b32 s7, v28, s47
	v_readlane_b32 s8, v74, s47
	v_readlane_b32 s9, v82, s34
	v_fmac_f32_e32 v115, s6, v22
	v_fmac_f32_e32 v181, s7, v110
	v_fmac_f32_e32 v180, s8, v16
	v_fmac_f32_e32 v114, s9, v104
	v_readlane_b32 s6, v78, s34
	v_readlane_b32 s7, v28, s34
	v_readlane_b32 s8, v74, s34
	v_readlane_b32 s9, v14, s47
	v_fmac_f32_e32 v115, s6, v12
	v_fmac_f32_e32 v181, s7, v96
	v_fmac_f32_e32 v180, s8, v10
	v_fmac_f32_e32 v114, s9, v94
	v_readlane_b32 s6, v70, s47
	v_readlane_b32 s7, v66, s47
	v_readlane_b32 s8, v62, s47
	v_readlane_b32 s9, v14, s34
	v_fmac_f32_e32 v115, s6, v8
	v_fmac_f32_e32 v181, s7, v92
	v_fmac_f32_e32 v180, s8, v4
	v_fmac_f32_e32 v114, s9, v90
	v_readlane_b32 s6, v70, s34
	s_nop 1
	v_fmac_f32_e32 v115, s6, v91
	v_readlane_b32 s6, v66, s34
	s_nop 1
	v_fmac_f32_e32 v115, s6, v88
	v_readlane_b32 s6, v62, s34
	s_nop 1
	v_fmac_f32_e32 v115, s6, v89
	v_pk_add_f32 v[114:115], v[180:181], v[114:115]
	v_mov_b32_e32 v181, v123
	v_mov_b32_e32 v180, v123
	v_pk_add_f32 v[114:115], v[114:115], v[114:115] op_sel:[0,1] op_sel_hi:[1,0]
	s_nop 0
	v_readlane_b32 s6, v82, s45
	v_readlane_b32 s7, v78, s45
	v_readlane_b32 s8, v28, s45
	v_readlane_b32 s9, v74, s45
	v_fmac_f32_e32 v27, s6, v114
	v_fmac_f32_e32 v181, s7, v22
	v_fmac_f32_e32 v180, s8, v110
	v_fmac_f32_e32 v26, s9, v16
	v_mov_b32_e32 v115, v22
	v_readlane_b32 s6, v82, s66
	v_readlane_b32 s7, v78, s66
	v_readlane_b32 s8, v28, s66
	v_readlane_b32 s9, v74, s66
	v_fmac_f32_e32 v27, s6, v104
	v_fmac_f32_e32 v181, s7, v12
	v_fmac_f32_e32 v180, s8, v96
	v_fmac_f32_e32 v26, s9, v10
	v_readlane_b32 s6, v14, s45
	v_readlane_b32 s7, v70, s45
	v_readlane_b32 s8, v66, s45
	v_readlane_b32 s9, v62, s45
	v_fmac_f32_e32 v27, s6, v94
	v_fmac_f32_e32 v181, s7, v8
	v_fmac_f32_e32 v180, s8, v92
	v_fmac_f32_e32 v26, s9, v4
	v_readlane_b32 s6, v14, s66
	v_readlane_b32 s7, v70, s66
	v_readlane_b32 s8, v66, s66
	v_readlane_b32 s9, v62, s66
	v_fmac_f32_e32 v27, s6, v90
	v_fmac_f32_e32 v181, s7, v91
	v_fmac_f32_e32 v180, s8, v88
	v_fmac_f32_e32 v26, s9, v89
	v_pk_add_f32 v[26:27], v[180:181], v[26:27]
	v_mov_b32_e32 v181, v123
	v_mov_b32_e32 v180, v123
	v_pk_add_f32 v[26:27], v[26:27], v[26:27] op_sel:[0,1] op_sel_hi:[1,0]
	s_nop 0
	v_readlane_b32 s6, v84, s14
	v_readlane_b32 s7, v82, s39
	v_readlane_b32 s8, v78, s39
	v_readlane_b32 s9, v28, s39
	v_fmac_f32_e32 v117, s6, v26
	v_fmac_f32_e32 v181, s7, v114
	v_fmac_f32_e32 v180, s8, v22
	v_fmac_f32_e32 v116, s9, v110
	v_readlane_b32 s6, v74, s39
	v_readlane_b32 s7, v82, s14
	v_readlane_b32 s8, v78, s14
	v_readlane_b32 s9, v28, s14
	v_fmac_f32_e32 v117, s6, v16
	v_fmac_f32_e32 v181, s7, v104
	v_fmac_f32_e32 v180, s8, v12
	v_fmac_f32_e32 v116, s9, v96
	v_readlane_b32 s6, v74, s14
	v_readlane_b32 s7, v14, s39
	v_readlane_b32 s8, v70, s39
	v_readlane_b32 s9, v66, s39
	v_fmac_f32_e32 v117, s6, v10
	v_fmac_f32_e32 v181, s7, v94
	v_fmac_f32_e32 v180, s8, v8
	v_fmac_f32_e32 v116, s9, v92
	v_readlane_b32 s6, v62, s39
	v_readlane_b32 s7, v14, s14
	v_readlane_b32 s8, v70, s14
	v_readlane_b32 s9, v66, s14
	v_fmac_f32_e32 v117, s6, v4
	v_fmac_f32_e32 v181, s7, v90
	v_fmac_f32_e32 v180, s8, v91
	v_fmac_f32_e32 v116, s9, v88
	v_readlane_b32 s6, v62, s14
	s_nop 1
	v_fmac_f32_e32 v117, s6, v89
	v_pk_add_f32 v[116:117], v[180:181], v[116:117]
	v_mov_b32_e32 v181, v123
	v_mov_b32_e32 v180, v123
	v_pk_add_f32 v[116:117], v[116:117], v[116:117] op_sel:[0,1] op_sel_hi:[1,0]
	s_nop 0
	v_readlane_b32 s6, v24, s11
	v_readlane_b32 s7, v84, s11
	v_readlane_b32 s8, v82, s38
	v_readlane_b32 s9, v78, s38
	v_fmac_f32_e32 v31, s6, v116
	v_fmac_f32_e32 v181, s7, v26
	v_fmac_f32_e32 v180, s8, v114
	v_fmac_f32_e32 v30, s9, v22
	v_mov_b32_e32 v117, v26
	v_readlane_b32 s6, v28, s38
	v_readlane_b32 s7, v74, s38
	v_readlane_b32 s8, v82, s11
	v_readlane_b32 s9, v78, s11
	v_fmac_f32_e32 v31, s6, v110
	v_fmac_f32_e32 v181, s7, v16
	v_fmac_f32_e32 v180, s8, v104
	v_fmac_f32_e32 v30, s9, v12
	v_readlane_b32 s6, v28, s11
	v_readlane_b32 s7, v74, s11
	v_readlane_b32 s8, v14, s38
	v_readlane_b32 s9, v70, s38
	v_fmac_f32_e32 v31, s6, v96
	v_fmac_f32_e32 v181, s7, v10
	v_fmac_f32_e32 v180, s8, v94
	v_fmac_f32_e32 v30, s9, v8
	v_readlane_b32 s6, v66, s38
	v_readlane_b32 s7, v62, s38
	v_readlane_b32 s8, v14, s11
	v_readlane_b32 s9, v70, s11
	v_fmac_f32_e32 v31, s6, v92
	v_fmac_f32_e32 v181, s7, v4
	v_fmac_f32_e32 v180, s8, v90
	v_fmac_f32_e32 v30, s9, v91
	v_readlane_b32 s6, v66, s11
	s_nop 1
	v_fmac_f32_e32 v31, s6, v88
	v_readlane_b32 s6, v62, s11
	s_nop 1
	v_fmac_f32_e32 v31, s6, v89
	v_pk_add_f32 v[30:31], v[180:181], v[30:31]
	v_mov_b32_e32 v181, v123
	v_mov_b32_e32 v180, v123
	v_pk_add_f32 v[30:31], v[30:31], v[30:31] op_sel:[0,1] op_sel_hi:[1,0]
	s_nop 0
	v_readlane_b32 s6, v142, s27
	v_readlane_b32 s7, v24, s27
	v_readlane_b32 s8, v84, s27
	v_readlane_b32 s9, v82, s43
	v_fmac_f32_e32 v119, s6, v30
	v_fmac_f32_e32 v181, s7, v116
	v_fmac_f32_e32 v180, s8, v26
	v_fmac_f32_e32 v118, s9, v114
	v_readlane_b32 s6, v78, s43
	v_readlane_b32 s7, v28, s43
	v_readlane_b32 s8, v74, s43
	v_readlane_b32 s9, v82, s27
	v_fmac_f32_e32 v119, s6, v22
	v_fmac_f32_e32 v181, s7, v110
	v_fmac_f32_e32 v180, s8, v16
	v_fmac_f32_e32 v118, s9, v104
	v_readlane_b32 s6, v78, s27
	v_readlane_b32 s7, v28, s27
	v_readlane_b32 s8, v74, s27
	v_readlane_b32 s9, v14, s43
	v_fmac_f32_e32 v119, s6, v12
	v_fmac_f32_e32 v181, s7, v96
	v_fmac_f32_e32 v180, s8, v10
	v_fmac_f32_e32 v118, s9, v94
	v_readlane_b32 s6, v70, s43
	v_readlane_b32 s7, v66, s43
	v_readlane_b32 s8, v62, s43
	v_readlane_b32 s9, v14, s27
	v_fmac_f32_e32 v119, s6, v8
	v_fmac_f32_e32 v181, s7, v92
	v_fmac_f32_e32 v180, s8, v4
	v_fmac_f32_e32 v118, s9, v90
	v_readlane_b32 s6, v70, s27
	s_nop 1
	v_fmac_f32_e32 v119, s6, v91
	v_readlane_b32 s6, v66, s27
	s_nop 1
	v_fmac_f32_e32 v119, s6, v88
	v_readlane_b32 s6, v62, s27
	s_nop 1
	v_fmac_f32_e32 v119, s6, v89
	v_pk_add_f32 v[118:119], v[180:181], v[118:119]
	v_mov_b32_e32 v181, v123
	v_mov_b32_e32 v180, v123
	v_pk_add_f32 v[118:119], v[118:119], v[118:119] op_sel:[0,1] op_sel_hi:[1,0]
	s_nop 0
	v_readlane_b32 s6, v6, s67
	v_readlane_b32 s7, v142, s67
	v_readlane_b32 s8, v24, s67
	v_readlane_b32 s9, v84, s67
	v_fmac_f32_e32 v33, s6, v118
	v_fmac_f32_e32 v181, s7, v30
	v_fmac_f32_e32 v180, s8, v116
	v_fmac_f32_e32 v32, s9, v26
	v_mov_b32_e32 v119, v30
	v_readlane_b32 s6, v82, s42
	v_readlane_b32 s7, v78, s42
	v_readlane_b32 s8, v28, s42
	v_readlane_b32 s9, v74, s42
	v_fmac_f32_e32 v33, s6, v114
	v_fmac_f32_e32 v181, s7, v22
	v_fmac_f32_e32 v180, s8, v110
	v_fmac_f32_e32 v32, s9, v16
	v_readlane_b32 s6, v82, s67
	v_readlane_b32 s7, v78, s67
	v_readlane_b32 s8, v28, s67
	v_readlane_b32 s9, v74, s67
	v_fmac_f32_e32 v33, s6, v104
	v_fmac_f32_e32 v181, s7, v12
	v_fmac_f32_e32 v180, s8, v96
	v_fmac_f32_e32 v32, s9, v10
	v_readlane_b32 s6, v14, s42
	v_readlane_b32 s7, v70, s42
	v_readlane_b32 s8, v66, s42
	v_readlane_b32 s9, v62, s42
	v_fmac_f32_e32 v33, s6, v94
	v_fmac_f32_e32 v181, s7, v8
	v_fmac_f32_e32 v180, s8, v92
	v_fmac_f32_e32 v32, s9, v4
	v_readlane_b32 s6, v14, s67
	v_readlane_b32 s7, v70, s67
	v_readlane_b32 s8, v66, s67
	v_readlane_b32 s9, v62, s67
	v_fmac_f32_e32 v33, s6, v90
	v_fmac_f32_e32 v181, s7, v91
	v_fmac_f32_e32 v180, s8, v88
	v_fmac_f32_e32 v32, s9, v89
	v_pk_add_f32 v[32:33], v[180:181], v[32:33]
	v_mov_b32_e32 v181, v123
	v_mov_b32_e32 v180, v123
	v_pk_add_f32 v[32:33], v[32:33], v[32:33] op_sel:[0,1] op_sel_hi:[1,0]
	s_nop 0
	v_readlane_b32 s6, v84, s46
	v_readlane_b32 s7, v6, s2
	v_readlane_b32 s8, v142, s2
	v_readlane_b32 s9, v24, s2
	v_fmac_f32_e32 v129, s6, v32
	v_fmac_f32_e32 v181, s7, v118
	v_fmac_f32_e32 v180, s8, v30
	v_fmac_f32_e32 v128, s9, v116
	v_readlane_b32 s6, v84, s2
	v_readlane_b32 s7, v82, s46
	v_readlane_b32 s8, v78, s46
	v_readlane_b32 s9, v28, s46
	v_fmac_f32_e32 v129, s6, v26
	v_fmac_f32_e32 v181, s7, v114
	v_fmac_f32_e32 v180, s8, v22
	v_fmac_f32_e32 v128, s9, v110
	v_readlane_b32 s6, v74, s46
	v_readlane_b32 s7, v82, s2
	v_readlane_b32 s8, v78, s2
	v_readlane_b32 s9, v28, s2
	v_fmac_f32_e32 v129, s6, v16
	v_fmac_f32_e32 v181, s7, v104
	v_fmac_f32_e32 v180, s8, v12
	v_fmac_f32_e32 v128, s9, v96
	v_readlane_b32 s6, v74, s2
	v_readlane_b32 s7, v14, s46
	v_readlane_b32 s8, v70, s46
	v_readlane_b32 s9, v66, s46
	v_fmac_f32_e32 v129, s6, v10
	v_fmac_f32_e32 v181, s7, v94
	v_fmac_f32_e32 v180, s8, v8
	v_fmac_f32_e32 v128, s9, v92
	v_readlane_b32 s6, v62, s46
	v_readlane_b32 s7, v14, s2
	v_readlane_b32 s8, v70, s2
	v_readlane_b32 s9, v66, s2
	v_fmac_f32_e32 v129, s6, v4
	v_fmac_f32_e32 v181, s7, v90
	v_fmac_f32_e32 v180, s8, v91
	v_fmac_f32_e32 v128, s9, v88
	v_readlane_b32 s6, v62, s2
	s_nop 1
	v_fmac_f32_e32 v129, s6, v89
	v_pk_add_f32 v[128:129], v[180:181], v[128:129]
	v_mov_b32_e32 v181, v123
	v_mov_b32_e32 v180, v123
	v_pk_add_f32 v[128:129], v[128:129], v[128:129] op_sel:[0,1] op_sel_hi:[1,0]
	s_nop 0
	v_readlane_b32 s6, v24, s37
	v_readlane_b32 s7, v84, s37
	v_readlane_b32 s8, v6, s18
	v_readlane_b32 s9, v142, s18
	v_fmac_f32_e32 v65, s6, v128
	v_fmac_f32_e32 v181, s7, v32
	v_fmac_f32_e32 v180, s8, v118
	v_fmac_f32_e32 v64, s9, v30
	v_mov_b32_e32 v129, v32
	v_readlane_b32 s6, v24, s18
	v_readlane_b32 s7, v84, s18
	v_readlane_b32 s8, v82, s37
	v_readlane_b32 s9, v78, s37
	v_fmac_f32_e32 v65, s6, v116
	v_fmac_f32_e32 v181, s7, v26
	v_fmac_f32_e32 v180, s8, v114
	v_fmac_f32_e32 v64, s9, v22
	v_readlane_b32 s6, v28, s37
	v_readlane_b32 s7, v74, s37
	v_readlane_b32 s8, v82, s18
	v_readlane_b32 s9, v78, s18
	v_fmac_f32_e32 v65, s6, v110
	v_fmac_f32_e32 v181, s7, v16
	v_fmac_f32_e32 v180, s8, v104
	v_fmac_f32_e32 v64, s9, v12
	v_readlane_b32 s6, v28, s18
	v_readlane_b32 s7, v74, s18
	v_readlane_b32 s8, v14, s37
	v_readlane_b32 s9, v70, s37
	v_fmac_f32_e32 v65, s6, v96
	v_fmac_f32_e32 v181, s7, v10
	v_fmac_f32_e32 v180, s8, v94
	v_fmac_f32_e32 v64, s9, v8
	v_readlane_b32 s6, v66, s37
	v_readlane_b32 s7, v62, s37
	v_readlane_b32 s8, v14, s18
	v_readlane_b32 s9, v70, s18
	v_fmac_f32_e32 v65, s6, v92
	v_fmac_f32_e32 v181, s7, v4
	v_fmac_f32_e32 v180, s8, v90
	v_fmac_f32_e32 v64, s9, v91
	v_readlane_b32 s6, v66, s18
	s_nop 1
	v_fmac_f32_e32 v65, s6, v88
	v_readlane_b32 s6, v62, s18
	s_nop 1
	v_fmac_f32_e32 v65, s6, v89
	v_pk_add_f32 v[64:65], v[180:181], v[64:65]
	v_mov_b32_e32 v181, v123
	v_mov_b32_e32 v180, v123
	v_pk_add_f32 v[64:65], v[64:65], v[64:65] op_sel:[0,1] op_sel_hi:[1,0]
	s_nop 0
	v_readlane_b32 s6, v142, s40
	v_readlane_b32 s7, v24, s40
	v_readlane_b32 s8, v84, s40
	v_readlane_b32 s9, v6, s19
	v_fmac_f32_e32 v131, s6, v64
	v_fmac_f32_e32 v181, s7, v128
	v_fmac_f32_e32 v180, s8, v32
	v_fmac_f32_e32 v130, s9, v118
	v_readlane_b32 s6, v142, s19
	v_readlane_b32 s7, v24, s19
	v_readlane_b32 s8, v84, s19
	v_readlane_b32 s9, v82, s40
	v_fmac_f32_e32 v131, s6, v30
	v_fmac_f32_e32 v181, s7, v116
	v_fmac_f32_e32 v180, s8, v26
	v_fmac_f32_e32 v130, s9, v114
	v_readlane_b32 s6, v78, s40
	v_readlane_b32 s7, v28, s40
	v_readlane_b32 s8, v74, s40
	v_readlane_b32 s9, v82, s19
	v_fmac_f32_e32 v131, s6, v22
	v_fmac_f32_e32 v181, s7, v110
	v_fmac_f32_e32 v180, s8, v16
	v_fmac_f32_e32 v130, s9, v104
	v_readlane_b32 s6, v78, s19
	v_readlane_b32 s7, v28, s19
	v_readlane_b32 s8, v74, s19
	v_readlane_b32 s9, v14, s40
	v_fmac_f32_e32 v131, s6, v12
	v_fmac_f32_e32 v181, s7, v96
	v_fmac_f32_e32 v180, s8, v10
	v_fmac_f32_e32 v130, s9, v94
	v_readlane_b32 s6, v70, s40
	v_readlane_b32 s7, v66, s40
	v_readlane_b32 s8, v62, s40
	v_readlane_b32 s9, v14, s19
	v_fmac_f32_e32 v131, s6, v8
	v_fmac_f32_e32 v181, s7, v92
	v_fmac_f32_e32 v180, s8, v4
	v_fmac_f32_e32 v130, s9, v90
	v_readlane_b32 s6, v70, s19
	s_nop 1
	v_fmac_f32_e32 v131, s6, v91
	v_readlane_b32 s6, v66, s19
	s_nop 1
	v_fmac_f32_e32 v131, s6, v88
	v_readlane_b32 s6, v62, s19
	s_nop 1
	v_fmac_f32_e32 v131, s6, v89
	v_pk_add_f32 v[130:131], v[180:181], v[130:131]
	v_mov_b32_e32 v181, v123
	v_mov_b32_e32 v180, v123
	v_pk_add_f32 v[130:131], v[130:131], v[130:131] op_sel:[0,1] op_sel_hi:[1,0]
	s_nop 0
	v_readlane_b32 s6, v6, s44
	v_readlane_b32 s7, v142, s44
	v_readlane_b32 s8, v24, s44
	v_readlane_b32 s9, v84, s44
	v_fmac_f32_e32 v69, s6, v130
	v_fmac_f32_e32 v181, s7, v64
	v_fmac_f32_e32 v180, s8, v128
	v_fmac_f32_e32 v68, s9, v32
	v_mov_b32_e32 v131, v64
	v_readlane_b32 s6, v6, s68
	v_readlane_b32 s7, v142, s68
	v_readlane_b32 s8, v24, s68
	v_readlane_b32 s9, v84, s68
	v_fmac_f32_e32 v69, s6, v118
	v_fmac_f32_e32 v181, s7, v30
	v_fmac_f32_e32 v180, s8, v116
	v_fmac_f32_e32 v68, s9, v26
	v_readlane_b32 s6, v82, s44
	v_readlane_b32 s7, v78, s44
	v_readlane_b32 s8, v28, s44
	v_readlane_b32 s9, v74, s44
	v_fmac_f32_e32 v69, s6, v114
	v_fmac_f32_e32 v181, s7, v22
	v_fmac_f32_e32 v180, s8, v110
	v_fmac_f32_e32 v68, s9, v16
	v_readlane_b32 s6, v82, s68
	v_readlane_b32 s7, v78, s68
	v_readlane_b32 s8, v28, s68
	v_readlane_b32 s9, v74, s68
	v_fmac_f32_e32 v69, s6, v104
	v_fmac_f32_e32 v181, s7, v12
	v_fmac_f32_e32 v180, s8, v96
	v_fmac_f32_e32 v68, s9, v10
	v_readlane_b32 s6, v14, s44
	v_readlane_b32 s7, v70, s44
	v_readlane_b32 s8, v66, s44
	v_readlane_b32 s9, v62, s44
	v_fmac_f32_e32 v69, s6, v94
	v_fmac_f32_e32 v181, s7, v8
	v_fmac_f32_e32 v180, s8, v92
	v_fmac_f32_e32 v68, s9, v4
	v_readlane_b32 s6, v14, s68
	v_readlane_b32 s7, v70, s68
	v_readlane_b32 s8, v66, s68
	v_readlane_b32 s9, v62, s68
	v_fmac_f32_e32 v69, s6, v90
	v_fmac_f32_e32 v181, s7, v91
	v_fmac_f32_e32 v180, s8, v88
	v_fmac_f32_e32 v68, s9, v89
	v_pk_add_f32 v[68:69], v[180:181], v[68:69]
	v_mov_b32_e32 v181, v123
	v_mov_b32_e32 v180, v123
	v_pk_add_f32 v[68:69], v[68:69], v[68:69] op_sel:[0,1] op_sel_hi:[1,0]
	s_nop 0
	v_readlane_b32 s6, v140, s3
	v_readlane_b32 s7, v6, s35
	v_readlane_b32 s8, v142, s35
	v_readlane_b32 s9, v24, s35
	v_fmac_f32_e32 v133, s6, v68
	v_fmac_f32_e32 v181, s7, v130
	v_fmac_f32_e32 v180, s8, v64
	v_fmac_f32_e32 v132, s9, v128
	v_readlane_b32 s6, v84, s35
	v_readlane_b32 s7, v6, s3
	v_readlane_b32 s8, v142, s3
	v_readlane_b32 s9, v24, s3
	v_fmac_f32_e32 v133, s6, v32
	v_fmac_f32_e32 v181, s7, v118
	v_fmac_f32_e32 v180, s8, v30
	v_fmac_f32_e32 v132, s9, v116
	v_readlane_b32 s6, v84, s3
	v_readlane_b32 s7, v82, s35
	v_readlane_b32 s8, v78, s35
	v_readlane_b32 s9, v28, s35
	v_fmac_f32_e32 v133, s6, v26
	v_fmac_f32_e32 v181, s7, v114
	v_fmac_f32_e32 v180, s8, v22
	v_fmac_f32_e32 v132, s9, v110
	v_readlane_b32 s6, v74, s35
	v_readlane_b32 s7, v82, s3
	v_readlane_b32 s8, v78, s3
	v_readlane_b32 s9, v28, s3
	v_fmac_f32_e32 v133, s6, v16
	v_fmac_f32_e32 v181, s7, v104
	v_fmac_f32_e32 v180, s8, v12
	v_fmac_f32_e32 v132, s9, v96
	v_readlane_b32 s6, v74, s3
	v_readlane_b32 s7, v14, s35
	v_readlane_b32 s8, v70, s35
	v_readlane_b32 s9, v66, s35
	v_fmac_f32_e32 v133, s6, v10
	v_fmac_f32_e32 v181, s7, v94
	v_fmac_f32_e32 v180, s8, v8
	v_fmac_f32_e32 v132, s9, v92
	v_readlane_b32 s6, v62, s35
	v_readlane_b32 s7, v14, s3
	v_readlane_b32 s8, v70, s3
	v_readlane_b32 s9, v66, s3
	v_fmac_f32_e32 v133, s6, v4
	v_fmac_f32_e32 v181, s7, v90
	v_fmac_f32_e32 v180, s8, v91
	v_fmac_f32_e32 v132, s9, v88
	v_readlane_b32 s6, v62, s3
	s_nop 1
	v_fmac_f32_e32 v133, s6, v89
	v_pk_add_f32 v[132:133], v[180:181], v[132:133]
	v_mov_b32_e32 v181, v123
	v_mov_b32_e32 v180, v123
	v_pk_add_f32 v[132:133], v[132:133], v[132:133] op_sel:[0,1] op_sel_hi:[1,0]
	s_nop 0
	v_readlane_b32 s6, v144, s16
	v_readlane_b32 s7, v140, s16
	v_readlane_b32 s8, v6, s30
	v_readlane_b32 s9, v142, s30
	v_fmac_f32_e32 v73, s6, v132
	v_fmac_f32_e32 v181, s7, v68
	v_fmac_f32_e32 v180, s8, v130
	v_fmac_f32_e32 v72, s9, v64
	v_mov_b32_e32 v133, v68
	v_readlane_b32 s6, v24, s30
	v_readlane_b32 s7, v84, s30
	v_readlane_b32 s8, v6, s16
	v_readlane_b32 s9, v142, s16
	v_fmac_f32_e32 v73, s6, v128
	v_fmac_f32_e32 v181, s7, v32
	v_fmac_f32_e32 v180, s8, v118
	v_fmac_f32_e32 v72, s9, v30
	v_readlane_b32 s6, v24, s16
	v_readlane_b32 s7, v84, s16
	v_readlane_b32 s8, v82, s30
	v_readlane_b32 s9, v78, s30
	v_fmac_f32_e32 v73, s6, v116
	v_fmac_f32_e32 v181, s7, v26
	v_fmac_f32_e32 v180, s8, v114
	v_fmac_f32_e32 v72, s9, v22
	v_readlane_b32 s6, v28, s30
	v_readlane_b32 s7, v74, s30
	v_readlane_b32 s8, v82, s16
	v_readlane_b32 s9, v78, s16
	v_fmac_f32_e32 v73, s6, v110
	v_fmac_f32_e32 v181, s7, v16
	v_fmac_f32_e32 v180, s8, v104
	v_fmac_f32_e32 v72, s9, v12
	v_readlane_b32 s6, v28, s16
	v_readlane_b32 s7, v74, s16
	v_readlane_b32 s8, v14, s30
	v_readlane_b32 s9, v70, s30
	v_fmac_f32_e32 v73, s6, v96
	v_fmac_f32_e32 v181, s7, v10
	v_fmac_f32_e32 v180, s8, v94
	v_fmac_f32_e32 v72, s9, v8
	v_readlane_b32 s6, v66, s30
	v_readlane_b32 s7, v62, s30
	v_readlane_b32 s8, v14, s16
	v_readlane_b32 s9, v70, s16
	v_fmac_f32_e32 v73, s6, v92
	v_fmac_f32_e32 v181, s7, v4
	v_fmac_f32_e32 v180, s8, v90
	v_fmac_f32_e32 v72, s9, v91
	v_readlane_b32 s6, v66, s16
	s_nop 1
	v_fmac_f32_e32 v73, s6, v88
	v_readlane_b32 s6, v62, s16
	s_nop 1
	v_fmac_f32_e32 v73, s6, v89
	v_pk_add_f32 v[72:73], v[180:181], v[72:73]
	v_mov_b32_e32 v181, v123
	v_mov_b32_e32 v180, v123
	v_pk_add_f32 v[72:73], v[72:73], v[72:73] op_sel:[0,1] op_sel_hi:[1,0]
	s_nop 0
	v_readlane_b32 s6, v146, s17
	v_readlane_b32 s7, v144, s17
	v_readlane_b32 s8, v140, s17
	v_readlane_b32 s9, v6, s36
	v_fmac_f32_e32 v135, s6, v72
	v_fmac_f32_e32 v181, s7, v132
	v_fmac_f32_e32 v180, s8, v68
	v_fmac_f32_e32 v134, s9, v130
	v_readlane_b32 s6, v142, s36
	v_readlane_b32 s7, v24, s36
	v_readlane_b32 s8, v84, s36
	v_readlane_b32 s9, v6, s17
	v_fmac_f32_e32 v135, s6, v64
	v_fmac_f32_e32 v181, s7, v128
	v_fmac_f32_e32 v180, s8, v32
	v_fmac_f32_e32 v134, s9, v118
	v_readlane_b32 s6, v142, s17
	v_readlane_b32 s7, v24, s17
	v_readlane_b32 s8, v84, s17
	v_readlane_b32 s9, v82, s36
	v_fmac_f32_e32 v135, s6, v30
	v_fmac_f32_e32 v181, s7, v116
	v_fmac_f32_e32 v180, s8, v26
	v_fmac_f32_e32 v134, s9, v114
	v_readlane_b32 s6, v78, s36
	v_readlane_b32 s7, v28, s36
	v_readlane_b32 s8, v74, s36
	v_readlane_b32 s9, v82, s17
	v_fmac_f32_e32 v135, s6, v22
	v_fmac_f32_e32 v181, s7, v110
	v_fmac_f32_e32 v180, s8, v16
	v_fmac_f32_e32 v134, s9, v104
	v_readlane_b32 s6, v78, s17
	v_readlane_b32 s7, v28, s17
	v_readlane_b32 s8, v74, s17
	v_readlane_b32 s9, v14, s36
	v_fmac_f32_e32 v135, s6, v12
	v_fmac_f32_e32 v181, s7, v96
	v_fmac_f32_e32 v180, s8, v10
	v_fmac_f32_e32 v134, s9, v94
	v_readlane_b32 s6, v70, s36
	v_readlane_b32 s7, v66, s36
	v_readlane_b32 s8, v62, s36
	v_readlane_b32 s9, v14, s17
	v_fmac_f32_e32 v135, s6, v8
	v_fmac_f32_e32 v181, s7, v92
	v_fmac_f32_e32 v180, s8, v4
	v_fmac_f32_e32 v134, s9, v90
	v_readlane_b32 s6, v70, s17
	s_nop 1
	v_fmac_f32_e32 v135, s6, v91
	v_readlane_b32 s6, v66, s17
	s_nop 1
	v_fmac_f32_e32 v135, s6, v88
	v_readlane_b32 s6, v62, s17
	s_nop 1
	v_fmac_f32_e32 v135, s6, v89
	v_pk_add_f32 v[134:135], v[180:181], v[134:135]
	v_mov_b32_e32 v181, v123
	v_mov_b32_e32 v180, v123
	v_pk_add_f32 v[134:135], v[134:135], v[134:135] op_sel:[0,1] op_sel_hi:[1,0]
	s_nop 0
	v_readlane_b32 s6, v2, s69
	v_readlane_b32 s7, v146, s69
	v_readlane_b32 s8, v144, s69
	v_readlane_b32 s9, v140, s69
	v_fmac_f32_e32 v77, s6, v134
	v_fmac_f32_e32 v181, s7, v72
	v_fmac_f32_e32 v180, s8, v132
	v_fmac_f32_e32 v76, s9, v68
	v_mov_b32_e32 v135, v72
	v_readlane_b32 s6, v6, s12
	v_readlane_b32 s7, v142, s12
	v_readlane_b32 s8, v24, s12
	v_readlane_b32 s9, v84, s12
	v_fmac_f32_e32 v77, s6, v130
	v_fmac_f32_e32 v181, s7, v64
	v_fmac_f32_e32 v180, s8, v128
	v_fmac_f32_e32 v76, s9, v32
	v_readlane_b32 s6, v6, s69
	v_readlane_b32 s7, v142, s69
	v_readlane_b32 s8, v24, s69
	v_readlane_b32 s9, v84, s69
	v_fmac_f32_e32 v77, s6, v118
	v_fmac_f32_e32 v181, s7, v30
	v_fmac_f32_e32 v180, s8, v116
	v_fmac_f32_e32 v76, s9, v26
	v_readlane_b32 s6, v82, s12
	v_readlane_b32 s7, v78, s12
	v_readlane_b32 s8, v28, s12
	v_readlane_b32 s9, v74, s12
	v_fmac_f32_e32 v77, s6, v114
	v_fmac_f32_e32 v181, s7, v22
	v_fmac_f32_e32 v180, s8, v110
	v_fmac_f32_e32 v76, s9, v16
	v_readlane_b32 s6, v82, s69
	v_readlane_b32 s7, v78, s69
	v_readlane_b32 s8, v28, s69
	v_readlane_b32 s9, v74, s69
	v_fmac_f32_e32 v77, s6, v104
	v_fmac_f32_e32 v181, s7, v12
	v_fmac_f32_e32 v180, s8, v96
	v_fmac_f32_e32 v76, s9, v10
	v_readlane_b32 s6, v14, s12
	v_readlane_b32 s7, v70, s12
	v_readlane_b32 s8, v66, s12
	v_readlane_b32 s9, v62, s12
	v_fmac_f32_e32 v77, s6, v94
	v_fmac_f32_e32 v181, s7, v8
	v_fmac_f32_e32 v180, s8, v92
	v_fmac_f32_e32 v76, s9, v4
	v_readlane_b32 s6, v14, s69
	v_readlane_b32 s7, v70, s69
	v_readlane_b32 s8, v66, s69
	v_readlane_b32 s9, v62, s69
	v_fmac_f32_e32 v77, s6, v90
	v_fmac_f32_e32 v181, s7, v91
	v_fmac_f32_e32 v180, s8, v88
	v_fmac_f32_e32 v76, s9, v89
	v_pk_add_f32 v[76:77], v[180:181], v[76:77]
	v_mov_b32_e32 v181, v123
	v_mov_b32_e32 v180, v123
	v_pk_add_f32 v[76:77], v[76:77], v[76:77] op_sel:[0,1] op_sel_hi:[1,0]
	s_nop 0
	v_readlane_b32 s6, v140, s15
	v_readlane_b32 s7, v2, s23
	v_readlane_b32 s8, v146, s23
	v_readlane_b32 s9, v144, s23
	v_fmac_f32_e32 v137, s6, v76
	v_fmac_f32_e32 v181, s7, v134
	v_fmac_f32_e32 v180, s8, v72
	v_fmac_f32_e32 v136, s9, v132
	v_readlane_b32 s6, v140, s23
	v_readlane_b32 s7, v6, s15
	v_readlane_b32 s8, v142, s15
	v_readlane_b32 s9, v24, s15
	v_fmac_f32_e32 v137, s6, v68
	v_fmac_f32_e32 v181, s7, v130
	v_fmac_f32_e32 v180, s8, v64
	v_fmac_f32_e32 v136, s9, v128
	v_readlane_b32 s6, v84, s15
	v_readlane_b32 s7, v6, s23
	v_readlane_b32 s8, v142, s23
	v_readlane_b32 s9, v24, s23
	v_fmac_f32_e32 v137, s6, v32
	v_fmac_f32_e32 v181, s7, v118
	v_fmac_f32_e32 v180, s8, v30
	v_fmac_f32_e32 v136, s9, v116
	v_readlane_b32 s6, v84, s23
	v_readlane_b32 s7, v82, s15
	v_readlane_b32 s8, v78, s15
	v_readlane_b32 s9, v28, s15
	v_fmac_f32_e32 v137, s6, v26
	v_fmac_f32_e32 v181, s7, v114
	v_fmac_f32_e32 v180, s8, v22
	v_fmac_f32_e32 v136, s9, v110
	v_readlane_b32 s6, v74, s15
	v_readlane_b32 s7, v82, s23
	v_readlane_b32 s8, v78, s23
	v_readlane_b32 s9, v28, s23
	v_fmac_f32_e32 v137, s6, v16
	v_fmac_f32_e32 v181, s7, v104
	v_fmac_f32_e32 v180, s8, v12
	v_fmac_f32_e32 v136, s9, v96
	v_readlane_b32 s6, v74, s23
	v_readlane_b32 s7, v14, s15
	v_readlane_b32 s8, v70, s15
	v_readlane_b32 s9, v66, s15
	v_fmac_f32_e32 v137, s6, v10
	v_fmac_f32_e32 v181, s7, v94
	v_fmac_f32_e32 v180, s8, v8
	v_fmac_f32_e32 v136, s9, v92
	v_readlane_b32 s6, v62, s15
	v_readlane_b32 s7, v14, s23
	v_readlane_b32 s8, v70, s23
	v_readlane_b32 s9, v66, s23
	v_fmac_f32_e32 v137, s6, v4
	v_fmac_f32_e32 v181, s7, v90
	v_fmac_f32_e32 v180, s8, v91
	v_fmac_f32_e32 v136, s9, v88
	v_readlane_b32 s6, v62, s23
	s_nop 1
	v_fmac_f32_e32 v137, s6, v89
	v_pk_add_f32 v[136:137], v[180:181], v[136:137]
	v_mov_b32_e32 v181, v123
	v_mov_b32_e32 v180, v123
	v_pk_add_f32 v[136:137], v[136:137], v[136:137] op_sel:[0,1] op_sel_hi:[1,0]
	s_nop 0
	v_readlane_b32 s6, v144, s26
	v_readlane_b32 s7, v140, s26
	v_readlane_b32 s8, v2, s10
	v_readlane_b32 s9, v146, s10
	v_fmac_f32_e32 v81, s6, v136
	v_fmac_f32_e32 v181, s7, v76
	v_fmac_f32_e32 v180, s8, v134
	v_fmac_f32_e32 v80, s9, v72
	v_mov_b32_e32 v137, v76
	v_readlane_b32 s6, v144, s10
	v_readlane_b32 s7, v140, s10
	v_readlane_b32 s8, v6, s26
	v_readlane_b32 s9, v142, s26
	v_fmac_f32_e32 v81, s6, v132
	v_fmac_f32_e32 v181, s7, v68
	v_fmac_f32_e32 v180, s8, v130
	v_fmac_f32_e32 v80, s9, v64
	v_readlane_b32 s6, v24, s26
	v_readlane_b32 s7, v84, s26
	v_readlane_b32 s8, v6, s10
	v_readlane_b32 s9, v142, s10
	v_fmac_f32_e32 v81, s6, v128
	v_fmac_f32_e32 v181, s7, v32
	v_fmac_f32_e32 v180, s8, v118
	v_fmac_f32_e32 v80, s9, v30
	v_readlane_b32 s6, v24, s10
	v_readlane_b32 s7, v84, s10
	v_readlane_b32 s8, v82, s26
	v_readlane_b32 s9, v78, s26
	v_fmac_f32_e32 v81, s6, v116
	v_fmac_f32_e32 v181, s7, v26
	v_fmac_f32_e32 v180, s8, v114
	v_fmac_f32_e32 v80, s9, v22
	v_readlane_b32 s6, v28, s26
	v_readlane_b32 s7, v74, s26
	v_readlane_b32 s8, v82, s10
	v_readlane_b32 s9, v78, s10
	v_fmac_f32_e32 v81, s6, v110
	v_fmac_f32_e32 v181, s7, v16
	v_fmac_f32_e32 v180, s8, v104
	v_fmac_f32_e32 v80, s9, v12
	v_readlane_b32 s6, v28, s10
	v_readlane_b32 s7, v74, s10
	v_readlane_b32 s8, v14, s26
	v_readlane_b32 s9, v70, s26
	v_fmac_f32_e32 v81, s6, v96
	v_fmac_f32_e32 v181, s7, v10
	v_fmac_f32_e32 v180, s8, v94
	v_fmac_f32_e32 v80, s9, v8
	v_readlane_b32 s6, v66, s26
	v_readlane_b32 s7, v62, s26
	v_readlane_b32 s8, v14, s10
	v_readlane_b32 s9, v70, s10
	v_fmac_f32_e32 v81, s6, v92
	v_fmac_f32_e32 v181, s7, v4
	v_fmac_f32_e32 v180, s8, v90
	v_fmac_f32_e32 v80, s9, v91
	v_readlane_b32 s6, v66, s10
	s_nop 1
	v_fmac_f32_e32 v81, s6, v88
	v_readlane_b32 s6, v62, s10
	s_nop 1
	v_fmac_f32_e32 v81, s6, v89
	v_pk_add_f32 v[80:81], v[180:181], v[80:81]
	v_mov_b32_e32 v181, v123
	v_mov_b32_e32 v180, v123
	v_pk_add_f32 v[80:81], v[80:81], v[80:81] op_sel:[0,1] op_sel_hi:[1,0]
	s_nop 0
	v_readlane_b32 s6, v146, s13
	v_readlane_b32 s7, v144, s13
	v_readlane_b32 s8, v140, s13
	v_readlane_b32 s9, v2, s31
	v_fmac_f32_e32 v139, s6, v80
	v_fmac_f32_e32 v181, s7, v136
	v_fmac_f32_e32 v180, s8, v76
	v_fmac_f32_e32 v138, s9, v134
	v_mov_b32_e32 v2, v123
	v_readlane_b32 s6, v146, s31
	v_readlane_b32 s7, v144, s31
	v_readlane_b32 s8, v140, s31
	v_readlane_b32 s9, v6, s13
	v_fmac_f32_e32 v139, s6, v72
	v_fmac_f32_e32 v181, s7, v132
	v_fmac_f32_e32 v180, s8, v68
	v_fmac_f32_e32 v138, s9, v130
	v_mov_b32_e32 v140, v123
	v_readlane_b32 s6, v142, s13
	v_readlane_b32 s7, v24, s13
	v_readlane_b32 s8, v84, s13
	v_readlane_b32 s9, v6, s31
	v_fmac_f32_e32 v139, s6, v64
	v_fmac_f32_e32 v181, s7, v128
	v_fmac_f32_e32 v180, s8, v32
	v_fmac_f32_e32 v138, s9, v118
	v_mov_b32_e32 v144, v123
	v_readlane_b32 s6, v142, s31
	v_readlane_b32 s7, v24, s31
	v_readlane_b32 s8, v84, s31
	v_readlane_b32 s9, v82, s13
	v_fmac_f32_e32 v139, s6, v30
	v_fmac_f32_e32 v181, s7, v116
	v_fmac_f32_e32 v180, s8, v26
	v_fmac_f32_e32 v138, s9, v114
	v_mov_b32_e32 v142, v123
	v_readlane_b32 s6, v78, s13
	v_readlane_b32 s7, v28, s13
	v_readlane_b32 s8, v74, s13
	v_readlane_b32 s9, v82, s31
	v_fmac_f32_e32 v139, s6, v22
	v_fmac_f32_e32 v181, s7, v110
	v_fmac_f32_e32 v180, s8, v16
	v_fmac_f32_e32 v138, s9, v104
	v_mov_b32_e32 v146, v123
	v_readlane_b32 s6, v78, s31
	v_readlane_b32 s7, v28, s31
	v_readlane_b32 s8, v74, s31
	v_readlane_b32 s9, v14, s13
	v_fmac_f32_e32 v139, s6, v12
	v_fmac_f32_e32 v181, s7, v96
	v_fmac_f32_e32 v180, s8, v10
	v_fmac_f32_e32 v138, s9, v94
	v_mov_b32_e32 v84, v123
	v_readlane_b32 s6, v70, s13
	v_readlane_b32 s7, v66, s13
	v_readlane_b32 s8, v62, s13
	v_readlane_b32 s9, v14, s31
	v_fmac_f32_e32 v139, s6, v8
	v_fmac_f32_e32 v181, s7, v92
	v_fmac_f32_e32 v180, s8, v4
	v_fmac_f32_e32 v138, s9, v90
	v_mov_b32_e32 v82, v123
	v_readlane_b32 s6, v70, s31
	s_nop 1
	v_fmac_f32_e32 v139, s6, v91
	v_mov_b32_e32 v78, v123
	v_readlane_b32 s6, v66, s31
	s_nop 1
	v_fmac_f32_e32 v139, s6, v88
	v_mov_b32_e32 v74, v123
	v_readlane_b32 s6, v62, s31
	s_nop 1
	v_fmac_f32_e32 v139, s6, v89
	v_mov_b32_e32 v70, v123
	v_pk_add_f32 v[138:139], v[180:181], v[138:139]
	v_mov_b32_e32 v181, v123
	v_mov_b32_e32 v180, v123
	v_pk_add_f32 v[138:139], v[138:139], v[138:139] op_sel:[0,1] op_sel_hi:[1,0]
	v_mov_b32_e32 v66, v123
	v_readlane_b32 s6, v226, s41
	v_readlane_b32 s7, v225, s41
	v_readlane_b32 s8, v224, s41
	v_readlane_b32 s9, v223, s41
	v_fmac_f32_e32 v153, s6, v138
	v_fmac_f32_e32 v181, s7, v80
	v_fmac_f32_e32 v180, s8, v136
	v_fmac_f32_e32 v152, s9, v76
	v_mov_b32_e32 v62, v123
	v_readlane_b32 s6, v226, s20
	v_readlane_b32 s7, v225, s20
	v_readlane_b32 s8, v224, s20
	v_readlane_b32 s9, v223, s20
	v_fmac_f32_e32 v153, s6, v134
	v_fmac_f32_e32 v181, s7, v72
	v_fmac_f32_e32 v180, s8, v132
	v_fmac_f32_e32 v152, s9, v68
	v_mov_b32_e32 v28, v123
	v_readlane_b32 s6, v222, s41
	v_readlane_b32 s7, v221, s41
	v_readlane_b32 s8, v220, s41
	v_readlane_b32 s9, v219, s41
	v_fmac_f32_e32 v153, s6, v130
	v_fmac_f32_e32 v181, s7, v64
	v_fmac_f32_e32 v180, s8, v128
	v_fmac_f32_e32 v152, s9, v32
	v_mov_b32_e32 v24, v123
	v_readlane_b32 s6, v222, s20
	v_readlane_b32 s7, v221, s20
	v_readlane_b32 s8, v220, s20
	v_readlane_b32 s9, v219, s20
	v_fmac_f32_e32 v153, s6, v118
	v_fmac_f32_e32 v181, s7, v30
	v_fmac_f32_e32 v180, s8, v116
	v_fmac_f32_e32 v152, s9, v26
	v_mov_b32_e32 v14, v123
	v_readlane_b32 s6, v218, s41
	v_readlane_b32 s7, v217, s41
	v_readlane_b32 s8, v216, s41
	v_readlane_b32 s9, v215, s41
	v_fmac_f32_e32 v153, s6, v114
	v_fmac_f32_e32 v181, s7, v22
	v_fmac_f32_e32 v180, s8, v110
	v_fmac_f32_e32 v152, s9, v16
	v_mov_b32_e32 v6, v123
	v_readlane_b32 s6, v218, s20
	v_readlane_b32 s7, v217, s20
	v_readlane_b32 s8, v216, s20
	v_readlane_b32 s9, v215, s20
	v_fmac_f32_e32 v153, s6, v104
	v_fmac_f32_e32 v181, s7, v12
	v_fmac_f32_e32 v180, s8, v96
	v_fmac_f32_e32 v152, s9, v10
	v_mov_b32_e32 v139, v80
	v_readlane_b32 s6, v214, s41
	v_readlane_b32 s7, v213, s41
	v_readlane_b32 s8, v212, s41
	v_readlane_b32 s9, v211, s41
	v_fmac_f32_e32 v153, s6, v94
	v_fmac_f32_e32 v181, s7, v8
	v_fmac_f32_e32 v180, s8, v92
	v_fmac_f32_e32 v152, s9, v4
	v_readlane_b32 s6, v214, s20
	v_readlane_b32 s7, v213, s20
	v_readlane_b32 s8, v212, s20
	v_readlane_b32 s9, v211, s20
	v_fmac_f32_e32 v153, s6, v90
	v_fmac_f32_e32 v181, s7, v91
	v_fmac_f32_e32 v180, s8, v88
	v_fmac_f32_e32 v152, s9, v89
	s_mov_b32 s20, 30
	v_pk_add_f32 v[152:153], v[180:181], v[152:153]
	v_mov_b32_e32 v181, v123
	v_mov_b32_e32 v180, v123
	v_pk_add_f32 v[152:153], v[152:153], v[152:153] op_sel:[0,1] op_sel_hi:[1,0]
	s_nop 0
	v_readlane_b32 s6, v209, s54
	v_readlane_b32 s7, v226, s20
	v_readlane_b32 s8, v225, s20
	v_readlane_b32 s9, v224, s20
	v_fmac_f32_e32 v141, s6, v152
	v_fmac_f32_e32 v181, s7, v138
	v_fmac_f32_e32 v180, s8, v80
	v_fmac_f32_e32 v140, s9, v136
	v_readlane_b32 s6, v223, s20
	v_readlane_b32 s7, v226, s54
	v_readlane_b32 s8, v225, s54
	v_readlane_b32 s9, v224, s54
	v_fmac_f32_e32 v141, s6, v76
	v_fmac_f32_e32 v181, s7, v134
	v_fmac_f32_e32 v180, s8, v72
	v_fmac_f32_e32 v140, s9, v132
	v_readlane_b32 s6, v223, s54
	v_readlane_b32 s7, v222, s20
	v_readlane_b32 s8, v221, s20
	v_readlane_b32 s9, v220, s20
	v_fmac_f32_e32 v141, s6, v68
	v_fmac_f32_e32 v181, s7, v130
	v_fmac_f32_e32 v180, s8, v64
	v_fmac_f32_e32 v140, s9, v128
	v_readlane_b32 s6, v219, s20
	v_readlane_b32 s7, v222, s54
	v_readlane_b32 s8, v221, s54
	v_readlane_b32 s9, v220, s54
	v_fmac_f32_e32 v141, s6, v32
	v_fmac_f32_e32 v181, s7, v118
	v_fmac_f32_e32 v180, s8, v30
	v_fmac_f32_e32 v140, s9, v116
	v_readlane_b32 s6, v219, s54
	v_readlane_b32 s7, v218, s20
	v_readlane_b32 s8, v217, s20
	v_readlane_b32 s9, v216, s20
	v_fmac_f32_e32 v141, s6, v26
	v_fmac_f32_e32 v181, s7, v114
	v_fmac_f32_e32 v180, s8, v22
	v_fmac_f32_e32 v140, s9, v110
	v_readlane_b32 s6, v215, s20
	v_readlane_b32 s7, v218, s54
	v_readlane_b32 s8, v217, s54
	v_readlane_b32 s9, v216, s54
	v_fmac_f32_e32 v141, s6, v16
	v_fmac_f32_e32 v181, s7, v104
	v_fmac_f32_e32 v180, s8, v12
	v_fmac_f32_e32 v140, s9, v96
	v_readlane_b32 s6, v215, s54
	v_readlane_b32 s7, v214, s20
	v_readlane_b32 s8, v213, s20
	v_readlane_b32 s9, v212, s20
	v_fmac_f32_e32 v141, s6, v10
	v_fmac_f32_e32 v181, s7, v94
	v_fmac_f32_e32 v180, s8, v8
	v_fmac_f32_e32 v140, s9, v92
	v_readlane_b32 s6, v211, s20
	v_readlane_b32 s7, v214, s54
	v_readlane_b32 s8, v213, s54
	v_readlane_b32 s9, v212, s54
	v_fmac_f32_e32 v141, s6, v4
	v_fmac_f32_e32 v181, s7, v90
	v_fmac_f32_e32 v180, s8, v91
	v_fmac_f32_e32 v140, s9, v88
	s_mov_b32 s20, 29
	v_readlane_b32 s6, v211, s54
	s_nop 1
	v_fmac_f32_e32 v141, s6, v89
	v_pk_add_f32 v[140:141], v[180:181], v[140:141]
	v_mov_b32_e32 v181, v123
	v_mov_b32_e32 v180, v123
	v_pk_add_f32 v[140:141], v[140:141], v[140:141] op_sel:[0,1] op_sel_hi:[1,0]
	s_nop 0
	v_readlane_b32 s6, v207, s55
	v_readlane_b32 s7, v209, s55
	v_readlane_b32 s8, v226, s20
	v_readlane_b32 s9, v225, s20
	v_fmac_f32_e32 v159, s6, v140
	v_fmac_f32_e32 v181, s7, v152
	v_fmac_f32_e32 v180, s8, v138
	v_fmac_f32_e32 v158, s9, v80
	v_mov_b32_e32 v141, v152
	v_readlane_b32 s6, v224, s20
	v_readlane_b32 s7, v223, s20
	v_readlane_b32 s8, v226, s55
	v_readlane_b32 s9, v225, s55
	v_fmac_f32_e32 v159, s6, v136
	v_fmac_f32_e32 v181, s7, v76
	v_fmac_f32_e32 v180, s8, v134
	v_fmac_f32_e32 v158, s9, v72
	v_readlane_b32 s6, v224, s55
	v_readlane_b32 s7, v223, s55
	v_readlane_b32 s8, v222, s20
	v_readlane_b32 s9, v221, s20
	v_fmac_f32_e32 v159, s6, v132
	v_fmac_f32_e32 v181, s7, v68
	v_fmac_f32_e32 v180, s8, v130
	v_fmac_f32_e32 v158, s9, v64
	v_readlane_b32 s6, v220, s20
	v_readlane_b32 s7, v219, s20
	v_readlane_b32 s8, v222, s55
	v_readlane_b32 s9, v221, s55
	v_fmac_f32_e32 v159, s6, v128
	v_fmac_f32_e32 v181, s7, v32
	v_fmac_f32_e32 v180, s8, v118
	v_fmac_f32_e32 v158, s9, v30
	v_readlane_b32 s6, v220, s55
	v_readlane_b32 s7, v219, s55
	v_readlane_b32 s8, v218, s20
	v_readlane_b32 s9, v217, s20
	v_fmac_f32_e32 v159, s6, v116
	v_fmac_f32_e32 v181, s7, v26
	v_fmac_f32_e32 v180, s8, v114
	v_fmac_f32_e32 v158, s9, v22
	v_readlane_b32 s6, v216, s20
	v_readlane_b32 s7, v215, s20
	v_readlane_b32 s8, v218, s55
	v_readlane_b32 s9, v217, s55
	v_fmac_f32_e32 v159, s6, v110
	v_fmac_f32_e32 v181, s7, v16
	v_fmac_f32_e32 v180, s8, v104
	v_fmac_f32_e32 v158, s9, v12
	v_readlane_b32 s6, v216, s55
	v_readlane_b32 s7, v215, s55
	v_readlane_b32 s8, v214, s20
	v_readlane_b32 s9, v213, s20
	v_fmac_f32_e32 v159, s6, v96
	v_fmac_f32_e32 v181, s7, v10
	v_fmac_f32_e32 v180, s8, v94
	v_fmac_f32_e32 v158, s9, v8
	v_readlane_b32 s6, v212, s20
	v_readlane_b32 s7, v211, s20
	v_readlane_b32 s8, v214, s55
	v_readlane_b32 s9, v213, s55
	v_fmac_f32_e32 v159, s6, v92
	v_fmac_f32_e32 v181, s7, v4
	v_fmac_f32_e32 v180, s8, v90
	v_fmac_f32_e32 v158, s9, v91
	s_mov_b32 s20, 28
	v_readlane_b32 s6, v212, s55
	s_nop 1
	v_fmac_f32_e32 v159, s6, v88
	v_readlane_b32 s6, v211, s55
	s_nop 1
	v_fmac_f32_e32 v159, s6, v89
	v_pk_add_f32 v[158:159], v[180:181], v[158:159]
	v_mov_b32_e32 v181, v123
	v_mov_b32_e32 v180, v123
	v_pk_add_f32 v[158:159], v[158:159], v[158:159] op_sel:[0,1] op_sel_hi:[1,0]
	s_nop 0
	v_readlane_b32 s6, v208, s56
	v_readlane_b32 s7, v207, s56
	v_readlane_b32 s8, v209, s56
	v_readlane_b32 s9, v226, s20
	v_fmac_f32_e32 v143, s6, v158
	v_fmac_f32_e32 v181, s7, v140
	v_fmac_f32_e32 v180, s8, v152
	v_fmac_f32_e32 v142, s9, v138
	v_readlane_b32 s6, v225, s20
	v_readlane_b32 s7, v224, s20
	v_readlane_b32 s8, v223, s20
	v_readlane_b32 s9, v226, s56
	v_fmac_f32_e32 v143, s6, v80
	v_fmac_f32_e32 v181, s7, v136
	v_fmac_f32_e32 v180, s8, v76
	v_fmac_f32_e32 v142, s9, v134
	v_readlane_b32 s6, v225, s56
	v_readlane_b32 s7, v224, s56
	v_readlane_b32 s8, v223, s56
	v_readlane_b32 s9, v222, s20
	v_fmac_f32_e32 v143, s6, v72
	v_fmac_f32_e32 v181, s7, v132
	v_fmac_f32_e32 v180, s8, v68
	v_fmac_f32_e32 v142, s9, v130
	v_readlane_b32 s6, v221, s20
	v_readlane_b32 s7, v220, s20
	v_readlane_b32 s8, v219, s20
	v_readlane_b32 s9, v222, s56
	v_fmac_f32_e32 v143, s6, v64
	v_fmac_f32_e32 v181, s7, v128
	v_fmac_f32_e32 v180, s8, v32
	v_fmac_f32_e32 v142, s9, v118
	v_readlane_b32 s6, v221, s56
	v_readlane_b32 s7, v220, s56
	v_readlane_b32 s8, v219, s56
	v_readlane_b32 s9, v218, s20
	v_fmac_f32_e32 v143, s6, v30
	v_fmac_f32_e32 v181, s7, v116
	v_fmac_f32_e32 v180, s8, v26
	v_fmac_f32_e32 v142, s9, v114
	v_readlane_b32 s6, v217, s20
	v_readlane_b32 s7, v216, s20
	v_readlane_b32 s8, v215, s20
	v_readlane_b32 s9, v218, s56
	v_fmac_f32_e32 v143, s6, v22
	v_fmac_f32_e32 v181, s7, v110
	v_fmac_f32_e32 v180, s8, v16
	v_fmac_f32_e32 v142, s9, v104
	v_readlane_b32 s6, v217, s56
	v_readlane_b32 s7, v216, s56
	v_readlane_b32 s8, v215, s56
	v_readlane_b32 s9, v214, s20
	v_fmac_f32_e32 v143, s6, v12
	v_fmac_f32_e32 v181, s7, v96
	v_fmac_f32_e32 v180, s8, v10
	v_fmac_f32_e32 v142, s9, v94
	v_readlane_b32 s6, v213, s20
	v_readlane_b32 s7, v212, s20
	v_readlane_b32 s8, v211, s20
	v_readlane_b32 s9, v214, s56
	v_fmac_f32_e32 v143, s6, v8
	v_fmac_f32_e32 v181, s7, v92
	v_fmac_f32_e32 v180, s8, v4
	v_fmac_f32_e32 v142, s9, v90
	s_mov_b32 s20, 27
	v_readlane_b32 s6, v213, s56
	s_nop 1
	v_fmac_f32_e32 v143, s6, v91
	v_readlane_b32 s6, v212, s56
	s_nop 1
	v_fmac_f32_e32 v143, s6, v88
	v_readlane_b32 s6, v211, s56
	s_nop 1
	v_fmac_f32_e32 v143, s6, v89
	v_pk_add_f32 v[142:143], v[180:181], v[142:143]
	v_mov_b32_e32 v181, v123
	v_mov_b32_e32 v180, v123
	v_pk_add_f32 v[142:143], v[142:143], v[142:143] op_sel:[0,1] op_sel_hi:[1,0]
	s_nop 0
	v_readlane_b32 s6, v205, s57
	v_readlane_b32 s7, v208, s57
	v_readlane_b32 s8, v207, s57
	v_readlane_b32 s9, v209, s57
	v_fmac_f32_e32 v167, s6, v142
	v_fmac_f32_e32 v181, s7, v158
	v_fmac_f32_e32 v180, s8, v140
	v_fmac_f32_e32 v166, s9, v152
	v_mov_b32_e32 v143, v158
	v_readlane_b32 s6, v226, s20
	v_readlane_b32 s7, v225, s20
	v_readlane_b32 s8, v224, s20
	v_readlane_b32 s9, v223, s20
	v_fmac_f32_e32 v167, s6, v138
	v_fmac_f32_e32 v181, s7, v80
	v_fmac_f32_e32 v180, s8, v136
	v_fmac_f32_e32 v166, s9, v76
	v_readlane_b32 s6, v226, s57
	v_readlane_b32 s7, v225, s57
	v_readlane_b32 s8, v224, s57
	v_readlane_b32 s9, v223, s57
	v_fmac_f32_e32 v167, s6, v134
	v_fmac_f32_e32 v181, s7, v72
	v_fmac_f32_e32 v180, s8, v132
	v_fmac_f32_e32 v166, s9, v68
	v_readlane_b32 s6, v222, s20
	v_readlane_b32 s7, v221, s20
	v_readlane_b32 s8, v220, s20
	v_readlane_b32 s9, v219, s20
	v_fmac_f32_e32 v167, s6, v130
	v_fmac_f32_e32 v181, s7, v64
	v_fmac_f32_e32 v180, s8, v128
	v_fmac_f32_e32 v166, s9, v32
	v_readlane_b32 s6, v222, s57
	v_readlane_b32 s7, v221, s57
	v_readlane_b32 s8, v220, s57
	v_readlane_b32 s9, v219, s57
	v_fmac_f32_e32 v167, s6, v118
	v_fmac_f32_e32 v181, s7, v30
	v_fmac_f32_e32 v180, s8, v116
	v_fmac_f32_e32 v166, s9, v26
	v_readlane_b32 s6, v218, s20
	v_readlane_b32 s7, v217, s20
	v_readlane_b32 s8, v216, s20
	v_readlane_b32 s9, v215, s20
	v_fmac_f32_e32 v167, s6, v114
	v_fmac_f32_e32 v181, s7, v22
	v_fmac_f32_e32 v180, s8, v110
	v_fmac_f32_e32 v166, s9, v16
	v_readlane_b32 s6, v218, s57
	v_readlane_b32 s7, v217, s57
	v_readlane_b32 s8, v216, s57
	v_readlane_b32 s9, v215, s57
	v_fmac_f32_e32 v167, s6, v104
	v_fmac_f32_e32 v181, s7, v12
	v_fmac_f32_e32 v180, s8, v96
	v_fmac_f32_e32 v166, s9, v10
	v_readlane_b32 s6, v214, s20
	v_readlane_b32 s7, v213, s20
	v_readlane_b32 s8, v212, s20
	v_readlane_b32 s9, v211, s20
	v_fmac_f32_e32 v167, s6, v94
	v_fmac_f32_e32 v181, s7, v8
	v_fmac_f32_e32 v180, s8, v92
	v_fmac_f32_e32 v166, s9, v4
	v_readlane_b32 s6, v214, s57
	v_readlane_b32 s7, v213, s57
	v_readlane_b32 s8, v212, s57
	v_readlane_b32 s9, v211, s57
	v_fmac_f32_e32 v167, s6, v90
	v_fmac_f32_e32 v181, s7, v91
	v_fmac_f32_e32 v180, s8, v88
	v_fmac_f32_e32 v166, s9, v89
	v_pk_add_f32 v[166:167], v[180:181], v[166:167]
	v_mov_b32_e32 v181, v123
	v_mov_b32_e32 v180, v123
	v_pk_add_f32 v[166:167], v[166:167], v[166:167] op_sel:[0,1] op_sel_hi:[1,0]
	s_nop 0
	v_readlane_b32 s6, v209, s53
	v_readlane_b32 s7, v205, s58
	v_readlane_b32 s8, v208, s58
	v_readlane_b32 s9, v207, s58
	v_fmac_f32_e32 v145, s6, v166
	v_fmac_f32_e32 v181, s7, v142
	v_fmac_f32_e32 v180, s8, v158
	v_fmac_f32_e32 v144, s9, v140
	v_readlane_b32 s6, v209, s58
	v_readlane_b32 s7, v226, s53
	v_readlane_b32 s8, v225, s53
	v_readlane_b32 s9, v224, s53
	v_fmac_f32_e32 v145, s6, v152
	v_fmac_f32_e32 v181, s7, v138
	v_fmac_f32_e32 v180, s8, v80
	v_fmac_f32_e32 v144, s9, v136
	v_readlane_b32 s6, v223, s53
	v_readlane_b32 s7, v226, s58
	v_readlane_b32 s8, v225, s58
	v_readlane_b32 s9, v224, s58
	v_fmac_f32_e32 v145, s6, v76
	v_fmac_f32_e32 v181, s7, v134
	v_fmac_f32_e32 v180, s8, v72
	v_fmac_f32_e32 v144, s9, v132
	v_readlane_b32 s6, v223, s58
	v_readlane_b32 s7, v222, s53
	v_readlane_b32 s8, v221, s53
	v_readlane_b32 s9, v220, s53
	v_fmac_f32_e32 v145, s6, v68
	v_fmac_f32_e32 v181, s7, v130
	v_fmac_f32_e32 v180, s8, v64
	v_fmac_f32_e32 v144, s9, v128
	v_readlane_b32 s6, v219, s53
	v_readlane_b32 s7, v222, s58
	v_readlane_b32 s8, v221, s58
	v_readlane_b32 s9, v220, s58
	v_fmac_f32_e32 v145, s6, v32
	v_fmac_f32_e32 v181, s7, v118
	v_fmac_f32_e32 v180, s8, v30
	v_fmac_f32_e32 v144, s9, v116
	v_readlane_b32 s6, v219, s58
	v_readlane_b32 s7, v218, s53
	v_readlane_b32 s8, v217, s53
	v_readlane_b32 s9, v216, s53
	v_fmac_f32_e32 v145, s6, v26
	v_fmac_f32_e32 v181, s7, v114
	v_fmac_f32_e32 v180, s8, v22
	v_fmac_f32_e32 v144, s9, v110
	v_readlane_b32 s6, v215, s53
	v_readlane_b32 s7, v218, s58
	v_readlane_b32 s8, v217, s58
	v_readlane_b32 s9, v216, s58
	v_fmac_f32_e32 v145, s6, v16
	v_fmac_f32_e32 v181, s7, v104
	v_fmac_f32_e32 v180, s8, v12
	v_fmac_f32_e32 v144, s9, v96
	v_readlane_b32 s6, v215, s58
	v_readlane_b32 s7, v214, s53
	v_readlane_b32 s8, v213, s53
	v_readlane_b32 s9, v212, s53
	v_fmac_f32_e32 v145, s6, v10
	v_fmac_f32_e32 v181, s7, v94
	v_fmac_f32_e32 v180, s8, v8
	v_fmac_f32_e32 v144, s9, v92
	v_readlane_b32 s6, v211, s53
	v_readlane_b32 s7, v214, s58
	v_readlane_b32 s8, v213, s58
	v_readlane_b32 s9, v212, s58
	v_fmac_f32_e32 v145, s6, v4
	v_fmac_f32_e32 v181, s7, v90
	v_fmac_f32_e32 v180, s8, v91
	v_fmac_f32_e32 v144, s9, v88
	v_readlane_b32 s6, v211, s58
	s_nop 1
	v_fmac_f32_e32 v145, s6, v89
	v_pk_add_f32 v[144:145], v[180:181], v[144:145]
	v_mov_b32_e32 v181, v123
	v_mov_b32_e32 v180, v123
	v_pk_add_f32 v[144:145], v[144:145], v[144:145] op_sel:[0,1] op_sel_hi:[1,0]
	s_nop 0
	v_readlane_b32 s6, v207, s52
	v_readlane_b32 s7, v209, s52
	v_readlane_b32 s8, v205, s59
	v_readlane_b32 s9, v208, s59
	v_fmac_f32_e32 v171, s6, v144
	v_fmac_f32_e32 v181, s7, v166
	v_fmac_f32_e32 v180, s8, v142
	v_fmac_f32_e32 v170, s9, v158
	v_mov_b32_e32 v145, v166
	v_readlane_b32 s6, v207, s59
	v_readlane_b32 s7, v209, s59
	v_readlane_b32 s8, v226, s52
	v_readlane_b32 s9, v225, s52
	v_fmac_f32_e32 v171, s6, v140
	v_fmac_f32_e32 v181, s7, v152
	v_fmac_f32_e32 v180, s8, v138
	v_fmac_f32_e32 v170, s9, v80
	v_readlane_b32 s6, v224, s52
	v_readlane_b32 s7, v223, s52
	v_readlane_b32 s8, v226, s59
	v_readlane_b32 s9, v225, s59
	v_fmac_f32_e32 v171, s6, v136
	v_fmac_f32_e32 v181, s7, v76
	v_fmac_f32_e32 v180, s8, v134
	v_fmac_f32_e32 v170, s9, v72
	v_readlane_b32 s6, v224, s59
	v_readlane_b32 s7, v223, s59
	v_readlane_b32 s8, v222, s52
	v_readlane_b32 s9, v221, s52
	v_fmac_f32_e32 v171, s6, v132
	v_fmac_f32_e32 v181, s7, v68
	v_fmac_f32_e32 v180, s8, v130
	v_fmac_f32_e32 v170, s9, v64
	v_readlane_b32 s6, v220, s52
	v_readlane_b32 s7, v219, s52
	v_readlane_b32 s8, v222, s59
	v_readlane_b32 s9, v221, s59
	v_fmac_f32_e32 v171, s6, v128
	v_fmac_f32_e32 v181, s7, v32
	v_fmac_f32_e32 v180, s8, v118
	v_fmac_f32_e32 v170, s9, v30
	v_readlane_b32 s6, v220, s59
	v_readlane_b32 s7, v219, s59
	v_readlane_b32 s8, v218, s52
	v_readlane_b32 s9, v217, s52
	v_fmac_f32_e32 v171, s6, v116
	v_fmac_f32_e32 v181, s7, v26
	v_fmac_f32_e32 v180, s8, v114
	v_fmac_f32_e32 v170, s9, v22
	v_readlane_b32 s6, v216, s52
	v_readlane_b32 s7, v215, s52
	v_readlane_b32 s8, v218, s59
	v_readlane_b32 s9, v217, s59
	v_fmac_f32_e32 v171, s6, v110
	v_fmac_f32_e32 v181, s7, v16
	v_fmac_f32_e32 v180, s8, v104
	v_fmac_f32_e32 v170, s9, v12
	v_readlane_b32 s6, v216, s59
	v_readlane_b32 s7, v215, s59
	v_readlane_b32 s8, v214, s52
	v_readlane_b32 s9, v213, s52
	v_fmac_f32_e32 v171, s6, v96
	v_fmac_f32_e32 v181, s7, v10
	v_fmac_f32_e32 v180, s8, v94
	v_fmac_f32_e32 v170, s9, v8
	v_readlane_b32 s6, v212, s52
	v_readlane_b32 s7, v211, s52
	v_readlane_b32 s8, v214, s59
	v_readlane_b32 s9, v213, s59
	v_fmac_f32_e32 v171, s6, v92
	v_fmac_f32_e32 v181, s7, v4
	v_fmac_f32_e32 v180, s8, v90
	v_fmac_f32_e32 v170, s9, v91
	v_readlane_b32 s6, v212, s59
	s_nop 1
	v_fmac_f32_e32 v171, s6, v88
	v_readlane_b32 s6, v211, s59
	s_nop 1
	v_fmac_f32_e32 v171, s6, v89
	v_pk_add_f32 v[170:171], v[180:181], v[170:171]
	v_mov_b32_e32 v181, v123
	v_mov_b32_e32 v180, v123
	v_pk_add_f32 v[170:171], v[170:171], v[170:171] op_sel:[0,1] op_sel_hi:[1,0]
	s_nop 0
	v_readlane_b32 s6, v208, s51
	v_readlane_b32 s7, v207, s51
	v_readlane_b32 s8, v209, s51
	v_readlane_b32 s9, v205, s60
	v_fmac_f32_e32 v147, s6, v170
	v_fmac_f32_e32 v181, s7, v144
	v_fmac_f32_e32 v180, s8, v166
	v_fmac_f32_e32 v146, s9, v142
	v_readlane_b32 s6, v208, s60
	v_readlane_b32 s7, v207, s60
	v_readlane_b32 s8, v209, s60
	v_readlane_b32 s9, v226, s51
	v_fmac_f32_e32 v147, s6, v158
	v_fmac_f32_e32 v181, s7, v140
	v_fmac_f32_e32 v180, s8, v152
	v_fmac_f32_e32 v146, s9, v138
	v_readlane_b32 s6, v225, s51
	v_readlane_b32 s7, v224, s51
	v_readlane_b32 s8, v223, s51
	v_readlane_b32 s9, v226, s60
	v_fmac_f32_e32 v147, s6, v80
	v_fmac_f32_e32 v181, s7, v136
	v_fmac_f32_e32 v180, s8, v76
	v_fmac_f32_e32 v146, s9, v134
	v_readlane_b32 s6, v225, s60
	v_readlane_b32 s7, v224, s60
	v_readlane_b32 s8, v223, s60
	v_readlane_b32 s9, v222, s51
	v_fmac_f32_e32 v147, s6, v72
	v_fmac_f32_e32 v181, s7, v132
	v_fmac_f32_e32 v180, s8, v68
	v_fmac_f32_e32 v146, s9, v130
	v_readlane_b32 s6, v221, s51
	v_readlane_b32 s7, v220, s51
	v_readlane_b32 s8, v219, s51
	v_readlane_b32 s9, v222, s60
	v_fmac_f32_e32 v147, s6, v64
	v_fmac_f32_e32 v181, s7, v128
	v_fmac_f32_e32 v180, s8, v32
	v_fmac_f32_e32 v146, s9, v118
	v_readlane_b32 s6, v221, s60
	v_readlane_b32 s7, v220, s60
	v_readlane_b32 s8, v219, s60
	v_readlane_b32 s9, v218, s51
	v_fmac_f32_e32 v147, s6, v30
	v_fmac_f32_e32 v181, s7, v116
	v_fmac_f32_e32 v180, s8, v26
	v_fmac_f32_e32 v146, s9, v114
	v_readlane_b32 s6, v217, s51
	v_readlane_b32 s7, v216, s51
	v_readlane_b32 s8, v215, s51
	v_readlane_b32 s9, v218, s60
	v_fmac_f32_e32 v147, s6, v22
	v_fmac_f32_e32 v181, s7, v110
	v_fmac_f32_e32 v180, s8, v16
	v_fmac_f32_e32 v146, s9, v104
	v_readlane_b32 s6, v217, s60
	v_readlane_b32 s7, v216, s60
	v_readlane_b32 s8, v215, s60
	v_readlane_b32 s9, v214, s51
	v_fmac_f32_e32 v147, s6, v12
	v_fmac_f32_e32 v181, s7, v96
	v_fmac_f32_e32 v180, s8, v10
	v_fmac_f32_e32 v146, s9, v94
	v_readlane_b32 s6, v213, s51
	v_readlane_b32 s7, v212, s51
	v_readlane_b32 s8, v211, s51
	v_readlane_b32 s9, v214, s60
	v_fmac_f32_e32 v147, s6, v8
	v_fmac_f32_e32 v181, s7, v92
	v_fmac_f32_e32 v180, s8, v4
	v_fmac_f32_e32 v146, s9, v90
	v_readlane_b32 s6, v213, s60
	s_nop 1
	v_fmac_f32_e32 v147, s6, v91
	v_readlane_b32 s6, v212, s60
	s_nop 1
	v_fmac_f32_e32 v147, s6, v88
	v_readlane_b32 s6, v211, s60
	s_nop 1
	v_fmac_f32_e32 v147, s6, v89
	v_pk_add_f32 v[146:147], v[180:181], v[146:147]
	v_mov_b32_e32 v181, v123
	v_mov_b32_e32 v180, v123
	v_pk_add_f32 v[146:147], v[146:147], v[146:147] op_sel:[0,1] op_sel_hi:[1,0]
	s_nop 0
	v_readlane_b32 s6, v205, s70
	v_readlane_b32 s7, v208, s70
	v_readlane_b32 s8, v207, s70
	v_readlane_b32 s9, v209, s70
	v_fmac_f32_e32 v175, s6, v146
	v_fmac_f32_e32 v181, s7, v170
	v_fmac_f32_e32 v180, s8, v144
	v_fmac_f32_e32 v174, s9, v166
	v_mov_b32_e32 v147, v170
	v_readlane_b32 s6, v205, s61
	v_readlane_b32 s7, v208, s61
	v_readlane_b32 s8, v207, s61
	v_readlane_b32 s9, v209, s61
	v_fmac_f32_e32 v175, s6, v142
	v_fmac_f32_e32 v181, s7, v158
	v_fmac_f32_e32 v180, s8, v140
	v_fmac_f32_e32 v174, s9, v152
	v_readlane_b32 s6, v226, s70
	v_readlane_b32 s7, v225, s70
	v_readlane_b32 s8, v224, s70
	v_readlane_b32 s9, v223, s70
	v_fmac_f32_e32 v175, s6, v138
	v_fmac_f32_e32 v181, s7, v80
	v_fmac_f32_e32 v180, s8, v136
	v_fmac_f32_e32 v174, s9, v76
	v_readlane_b32 s6, v226, s61
	v_readlane_b32 s7, v225, s61
	v_readlane_b32 s8, v224, s61
	v_readlane_b32 s9, v223, s61
	v_fmac_f32_e32 v175, s6, v134
	v_fmac_f32_e32 v181, s7, v72
	v_fmac_f32_e32 v180, s8, v132
	v_fmac_f32_e32 v174, s9, v68
	v_readlane_b32 s6, v222, s70
	v_readlane_b32 s7, v221, s70
	v_readlane_b32 s8, v220, s70
	v_readlane_b32 s9, v219, s70
	v_fmac_f32_e32 v175, s6, v130
	v_fmac_f32_e32 v181, s7, v64
	v_fmac_f32_e32 v180, s8, v128
	v_fmac_f32_e32 v174, s9, v32
	v_readlane_b32 s6, v222, s61
	v_readlane_b32 s7, v221, s61
	v_readlane_b32 s8, v220, s61
	v_readlane_b32 s9, v219, s61
	v_fmac_f32_e32 v175, s6, v118
	v_fmac_f32_e32 v181, s7, v30
	v_fmac_f32_e32 v180, s8, v116
	v_fmac_f32_e32 v174, s9, v26
	v_readlane_b32 s6, v218, s70
	v_readlane_b32 s7, v217, s70
	v_readlane_b32 s8, v216, s70
	v_readlane_b32 s9, v215, s70
	v_fmac_f32_e32 v175, s6, v114
	v_fmac_f32_e32 v181, s7, v22
	v_fmac_f32_e32 v180, s8, v110
	v_fmac_f32_e32 v174, s9, v16
	v_readlane_b32 s6, v218, s61
	v_readlane_b32 s7, v217, s61
	v_readlane_b32 s8, v216, s61
	v_readlane_b32 s9, v215, s61
	v_fmac_f32_e32 v175, s6, v104
	v_fmac_f32_e32 v181, s7, v12
	v_fmac_f32_e32 v180, s8, v96
	v_fmac_f32_e32 v174, s9, v10
	v_readlane_b32 s6, v214, s70
	v_readlane_b32 s7, v213, s70
	v_readlane_b32 s8, v212, s70
	v_readlane_b32 s9, v211, s70
	v_fmac_f32_e32 v175, s6, v94
	v_fmac_f32_e32 v181, s7, v8
	v_fmac_f32_e32 v180, s8, v92
	v_fmac_f32_e32 v174, s9, v4
	v_readlane_b32 s6, v214, s61
	v_readlane_b32 s7, v213, s61
	v_readlane_b32 s8, v212, s61
	v_readlane_b32 s9, v211, s61
	v_fmac_f32_e32 v175, s6, v90
	v_fmac_f32_e32 v181, s7, v91
	v_fmac_f32_e32 v180, s8, v88
	v_fmac_f32_e32 v174, s9, v89
	v_pk_add_f32 v[174:175], v[180:181], v[174:175]
	v_mov_b32_e32 v181, v123
	v_mov_b32_e32 v180, v123
	v_pk_add_f32 v[174:175], v[174:175], v[174:175] op_sel:[0,1] op_sel_hi:[1,0]
	s_nop 0
	v_readlane_b32 s6, v206, s62
	v_readlane_b32 s7, v205, s71
	v_readlane_b32 s8, v208, s71
	v_readlane_b32 s9, v207, s71
	v_fmac_f32_e32 v149, s6, v174
	v_fmac_f32_e32 v181, s7, v146
	v_fmac_f32_e32 v180, s8, v170
	v_fmac_f32_e32 v148, s9, v144
	v_readlane_b32 s6, v209, s71
	v_readlane_b32 s7, v205, s62
	v_readlane_b32 s8, v208, s62
	v_readlane_b32 s9, v207, s62
	v_fmac_f32_e32 v149, s6, v166
	v_fmac_f32_e32 v181, s7, v142
	v_fmac_f32_e32 v180, s8, v158
	v_fmac_f32_e32 v148, s9, v140
	v_readlane_b32 s6, v209, s62
	v_readlane_b32 s7, v226, s71
	v_readlane_b32 s8, v225, s71
	v_readlane_b32 s9, v224, s71
	v_fmac_f32_e32 v149, s6, v152
	v_fmac_f32_e32 v181, s7, v138
	v_fmac_f32_e32 v180, s8, v80
	v_fmac_f32_e32 v148, s9, v136
	v_readlane_b32 s6, v223, s71
	v_readlane_b32 s7, v226, s62
	v_readlane_b32 s8, v225, s62
	v_readlane_b32 s9, v224, s62
	v_fmac_f32_e32 v149, s6, v76
	v_fmac_f32_e32 v181, s7, v134
	v_fmac_f32_e32 v180, s8, v72
	v_fmac_f32_e32 v148, s9, v132
	v_readlane_b32 s6, v223, s62
	v_readlane_b32 s7, v222, s71
	v_readlane_b32 s8, v221, s71
	v_readlane_b32 s9, v220, s71
	v_fmac_f32_e32 v149, s6, v68
	v_fmac_f32_e32 v181, s7, v130
	v_fmac_f32_e32 v180, s8, v64
	v_fmac_f32_e32 v148, s9, v128
	v_readlane_b32 s6, v219, s71
	v_readlane_b32 s7, v222, s62
	v_readlane_b32 s8, v221, s62
	v_readlane_b32 s9, v220, s62
	v_fmac_f32_e32 v149, s6, v32
	v_fmac_f32_e32 v181, s7, v118
	v_fmac_f32_e32 v180, s8, v30
	v_fmac_f32_e32 v148, s9, v116
	v_readlane_b32 s6, v219, s62
	v_readlane_b32 s7, v218, s71
	v_readlane_b32 s8, v217, s71
	v_readlane_b32 s9, v216, s71
	v_fmac_f32_e32 v149, s6, v26
	v_fmac_f32_e32 v181, s7, v114
	v_fmac_f32_e32 v180, s8, v22
	v_fmac_f32_e32 v148, s9, v110
	v_readlane_b32 s6, v215, s71
	v_readlane_b32 s7, v218, s62
	v_readlane_b32 s8, v217, s62
	v_readlane_b32 s9, v216, s62
	v_fmac_f32_e32 v149, s6, v16
	v_fmac_f32_e32 v181, s7, v104
	v_fmac_f32_e32 v180, s8, v12
	v_fmac_f32_e32 v148, s9, v96
	v_readlane_b32 s6, v215, s62
	v_readlane_b32 s7, v214, s71
	v_readlane_b32 s8, v213, s71
	v_readlane_b32 s9, v212, s71
	v_fmac_f32_e32 v149, s6, v10
	v_fmac_f32_e32 v181, s7, v94
	v_fmac_f32_e32 v180, s8, v8
	v_fmac_f32_e32 v148, s9, v92
	v_readlane_b32 s6, v211, s71
	v_readlane_b32 s7, v214, s62
	v_readlane_b32 s8, v213, s62
	v_readlane_b32 s9, v212, s62
	v_fmac_f32_e32 v149, s6, v4
	v_fmac_f32_e32 v181, s7, v90
	v_fmac_f32_e32 v180, s8, v91
	v_fmac_f32_e32 v148, s9, v88
	v_readlane_b32 s6, v211, s62
	s_nop 1
	v_fmac_f32_e32 v149, s6, v89
	v_pk_add_f32 v[148:149], v[180:181], v[148:149]
	v_mov_b32_e32 v181, v123
	v_mov_b32_e32 v180, v123
	v_pk_add_f32 v[148:149], v[148:149], v[148:149] op_sel:[0,1] op_sel_hi:[1,0]
	s_nop 0
	v_readlane_b32 s6, v203, s63
	v_readlane_b32 s7, v206, s63
	v_readlane_b32 s8, v205, s72
	v_readlane_b32 s9, v208, s72
	v_fmac_f32_e32 v179, s6, v148
	v_fmac_f32_e32 v181, s7, v174
	v_fmac_f32_e32 v180, s8, v146
	v_fmac_f32_e32 v178, s9, v170
	v_mov_b32_e32 v149, v174
	v_readlane_b32 s6, v207, s72
	v_readlane_b32 s7, v209, s72
	v_readlane_b32 s8, v205, s63
	v_readlane_b32 s9, v208, s63
	v_fmac_f32_e32 v179, s6, v144
	v_fmac_f32_e32 v181, s7, v166
	v_fmac_f32_e32 v180, s8, v142
	v_fmac_f32_e32 v178, s9, v158
	v_readlane_b32 s6, v207, s63
	v_readlane_b32 s7, v209, s63
	v_readlane_b32 s8, v226, s72
	v_readlane_b32 s9, v225, s72
	v_fmac_f32_e32 v179, s6, v140
	v_fmac_f32_e32 v181, s7, v152
	v_fmac_f32_e32 v180, s8, v138
	v_fmac_f32_e32 v178, s9, v80
	v_readlane_b32 s6, v224, s72
	v_readlane_b32 s7, v223, s72
	v_readlane_b32 s8, v226, s63
	v_readlane_b32 s9, v225, s63
	v_fmac_f32_e32 v179, s6, v136
	v_fmac_f32_e32 v181, s7, v76
	v_fmac_f32_e32 v180, s8, v134
	v_fmac_f32_e32 v178, s9, v72
	v_readlane_b32 s6, v224, s63
	v_readlane_b32 s7, v223, s63
	v_readlane_b32 s8, v222, s72
	v_readlane_b32 s9, v221, s72
	v_fmac_f32_e32 v179, s6, v132
	v_fmac_f32_e32 v181, s7, v68
	v_fmac_f32_e32 v180, s8, v130
	v_fmac_f32_e32 v178, s9, v64
	v_readlane_b32 s6, v220, s72
	v_readlane_b32 s7, v219, s72
	v_readlane_b32 s8, v222, s63
	v_readlane_b32 s9, v221, s63
	v_fmac_f32_e32 v179, s6, v128
	v_fmac_f32_e32 v181, s7, v32
	v_fmac_f32_e32 v180, s8, v118
	v_fmac_f32_e32 v178, s9, v30
	v_readlane_b32 s6, v220, s63
	v_readlane_b32 s7, v219, s63
	v_readlane_b32 s8, v218, s72
	v_readlane_b32 s9, v217, s72
	v_fmac_f32_e32 v179, s6, v116
	v_fmac_f32_e32 v181, s7, v26
	v_fmac_f32_e32 v180, s8, v114
	v_fmac_f32_e32 v178, s9, v22
	v_readlane_b32 s6, v216, s72
	v_readlane_b32 s7, v215, s72
	v_readlane_b32 s8, v218, s63
	v_readlane_b32 s9, v217, s63
	v_fmac_f32_e32 v179, s6, v110
	v_fmac_f32_e32 v181, s7, v16
	v_fmac_f32_e32 v180, s8, v104
	v_fmac_f32_e32 v178, s9, v12
	v_readlane_b32 s6, v216, s63
	v_readlane_b32 s7, v215, s63
	v_readlane_b32 s8, v214, s72
	v_readlane_b32 s9, v213, s72
	v_fmac_f32_e32 v179, s6, v96
	v_fmac_f32_e32 v181, s7, v10
	v_fmac_f32_e32 v180, s8, v94
	v_fmac_f32_e32 v178, s9, v8
	v_readlane_b32 s6, v212, s72
	v_readlane_b32 s7, v211, s72
	v_readlane_b32 s8, v214, s63
	v_readlane_b32 s9, v213, s63
	v_fmac_f32_e32 v179, s6, v92
	v_fmac_f32_e32 v181, s7, v4
	v_fmac_f32_e32 v180, s8, v90
	v_fmac_f32_e32 v178, s9, v91
	v_readlane_b32 s6, v212, s63
	s_nop 1
	v_fmac_f32_e32 v179, s6, v88
	v_readlane_b32 s6, v211, s63
	s_nop 1
	v_fmac_f32_e32 v179, s6, v89
	v_pk_add_f32 v[178:179], v[180:181], v[178:179]
	v_mov_b32_e32 v181, v123
	v_mov_b32_e32 v180, v123
	v_pk_add_f32 v[178:179], v[178:179], v[178:179] op_sel:[0,1] op_sel_hi:[1,0]
	s_nop 0
	v_readlane_b32 s6, v204, s22
	v_readlane_b32 s7, v203, s22
	v_readlane_b32 s8, v206, s22
	v_readlane_b32 s9, v205, s73
	v_fmac_f32_e32 v151, s6, v178
	v_fmac_f32_e32 v181, s7, v148
	v_fmac_f32_e32 v180, s8, v174
	v_fmac_f32_e32 v150, s9, v146
	v_readlane_b32 s6, v208, s73
	v_readlane_b32 s7, v207, s73
	v_readlane_b32 s8, v209, s73
	v_readlane_b32 s9, v205, s22
	v_fmac_f32_e32 v151, s6, v170
	v_fmac_f32_e32 v181, s7, v144
	v_fmac_f32_e32 v180, s8, v166
	v_fmac_f32_e32 v150, s9, v142
	v_readlane_b32 s6, v208, s22
	v_readlane_b32 s7, v207, s22
	v_readlane_b32 s8, v209, s22
	v_readlane_b32 s9, v226, s73
	v_fmac_f32_e32 v151, s6, v158
	v_fmac_f32_e32 v181, s7, v140
	v_fmac_f32_e32 v180, s8, v152
	v_fmac_f32_e32 v150, s9, v138
	v_readlane_b32 s6, v225, s73
	v_readlane_b32 s7, v224, s73
	v_readlane_b32 s8, v223, s73
	v_readlane_b32 s9, v226, s22
	v_fmac_f32_e32 v151, s6, v80
	v_fmac_f32_e32 v181, s7, v136
	v_fmac_f32_e32 v180, s8, v76
	v_fmac_f32_e32 v150, s9, v134
	v_readlane_b32 s6, v225, s22
	v_readlane_b32 s7, v224, s22
	v_readlane_b32 s8, v223, s22
	v_readlane_b32 s9, v222, s73
	v_fmac_f32_e32 v151, s6, v72
	v_fmac_f32_e32 v181, s7, v132
	v_fmac_f32_e32 v180, s8, v68
	v_fmac_f32_e32 v150, s9, v130
	v_readlane_b32 s6, v221, s73
	v_readlane_b32 s7, v220, s73
	v_readlane_b32 s8, v219, s73
	v_readlane_b32 s9, v222, s22
	v_fmac_f32_e32 v151, s6, v64
	v_fmac_f32_e32 v181, s7, v128
	v_fmac_f32_e32 v180, s8, v32
	v_fmac_f32_e32 v150, s9, v118
	v_readlane_b32 s6, v221, s22
	v_readlane_b32 s7, v220, s22
	v_readlane_b32 s8, v219, s22
	v_readlane_b32 s9, v218, s73
	v_fmac_f32_e32 v151, s6, v30
	v_fmac_f32_e32 v181, s7, v116
	v_fmac_f32_e32 v180, s8, v26
	v_fmac_f32_e32 v150, s9, v114
	v_readlane_b32 s6, v217, s73
	v_readlane_b32 s7, v216, s73
	v_readlane_b32 s8, v215, s73
	v_readlane_b32 s9, v218, s22
	v_fmac_f32_e32 v151, s6, v22
	v_fmac_f32_e32 v181, s7, v110
	v_fmac_f32_e32 v180, s8, v16
	v_fmac_f32_e32 v150, s9, v104
	v_readlane_b32 s6, v217, s22
	v_readlane_b32 s7, v216, s22
	v_readlane_b32 s8, v215, s22
	v_readlane_b32 s9, v214, s73
	v_fmac_f32_e32 v151, s6, v12
	v_fmac_f32_e32 v181, s7, v96
	v_fmac_f32_e32 v180, s8, v10
	v_fmac_f32_e32 v150, s9, v94
	v_readlane_b32 s6, v213, s73
	v_readlane_b32 s7, v212, s73
	v_readlane_b32 s8, v211, s73
	v_readlane_b32 s9, v214, s22
	v_fmac_f32_e32 v151, s6, v8
	v_fmac_f32_e32 v181, s7, v92
	v_fmac_f32_e32 v180, s8, v4
	v_fmac_f32_e32 v150, s9, v90
	v_readlane_b32 s6, v213, s22
	s_nop 1
	v_fmac_f32_e32 v151, s6, v91
	v_readlane_b32 s6, v212, s22
	s_nop 1
	v_fmac_f32_e32 v151, s6, v88
	v_readlane_b32 s6, v211, s22
	s_nop 1
	v_fmac_f32_e32 v151, s6, v89
	v_pk_add_f32 v[150:151], v[180:181], v[150:151]
	v_mov_b32_e32 v181, v123
	v_mov_b32_e32 v180, v123
	v_pk_add_f32 v[150:151], v[150:151], v[150:151] op_sel:[0,1] op_sel_hi:[1,0]
	s_nop 0
	v_readlane_b32 s6, v201, s64
	v_readlane_b32 s7, v204, s64
	v_readlane_b32 s8, v203, s64
	v_readlane_b32 s9, v206, s64
	v_fmac_f32_e32 v177, s6, v150
	v_fmac_f32_e32 v181, s7, v178
	v_fmac_f32_e32 v180, s8, v148
	v_fmac_f32_e32 v176, s9, v174
	v_mov_b32_e32 v151, v178
	v_readlane_b32 s6, v205, s50
	v_readlane_b32 s7, v208, s50
	v_readlane_b32 s8, v207, s50
	v_readlane_b32 s9, v209, s50
	v_fmac_f32_e32 v177, s6, v146
	v_fmac_f32_e32 v181, s7, v170
	v_fmac_f32_e32 v180, s8, v144
	v_fmac_f32_e32 v176, s9, v166
	v_readlane_b32 s6, v205, s64
	v_readlane_b32 s7, v208, s64
	v_readlane_b32 s8, v207, s64
	v_readlane_b32 s9, v209, s64
	v_fmac_f32_e32 v177, s6, v142
	v_fmac_f32_e32 v181, s7, v158
	v_fmac_f32_e32 v180, s8, v140
	v_fmac_f32_e32 v176, s9, v152
	v_readlane_b32 s6, v226, s50
	v_readlane_b32 s7, v225, s50
	v_readlane_b32 s8, v224, s50
	v_readlane_b32 s9, v223, s50
	v_fmac_f32_e32 v177, s6, v138
	v_fmac_f32_e32 v181, s7, v80
	v_fmac_f32_e32 v180, s8, v136
	v_fmac_f32_e32 v176, s9, v76
	v_readlane_b32 s6, v226, s64
	v_readlane_b32 s7, v225, s64
	v_readlane_b32 s8, v224, s64
	v_readlane_b32 s9, v223, s64
	v_fmac_f32_e32 v177, s6, v134
	v_fmac_f32_e32 v181, s7, v72
	v_fmac_f32_e32 v180, s8, v132
	v_fmac_f32_e32 v176, s9, v68
	v_readlane_b32 s6, v222, s50
	v_readlane_b32 s7, v221, s50
	v_readlane_b32 s8, v220, s50
	v_readlane_b32 s9, v219, s50
	v_fmac_f32_e32 v177, s6, v130
	v_fmac_f32_e32 v181, s7, v64
	v_fmac_f32_e32 v180, s8, v128
	v_fmac_f32_e32 v176, s9, v32
	v_readlane_b32 s6, v222, s64
	v_readlane_b32 s7, v221, s64
	v_readlane_b32 s8, v220, s64
	v_readlane_b32 s9, v219, s64
	v_fmac_f32_e32 v177, s6, v118
	v_fmac_f32_e32 v181, s7, v30
	v_fmac_f32_e32 v180, s8, v116
	v_fmac_f32_e32 v176, s9, v26
	v_readlane_b32 s6, v218, s50
	v_readlane_b32 s7, v217, s50
	v_readlane_b32 s8, v216, s50
	v_readlane_b32 s9, v215, s50
	v_fmac_f32_e32 v177, s6, v114
	v_fmac_f32_e32 v181, s7, v22
	v_fmac_f32_e32 v180, s8, v110
	v_fmac_f32_e32 v176, s9, v16
	v_readlane_b32 s6, v218, s64
	v_readlane_b32 s7, v217, s64
	v_readlane_b32 s8, v216, s64
	v_readlane_b32 s9, v215, s64
	v_fmac_f32_e32 v177, s6, v104
	v_fmac_f32_e32 v181, s7, v12
	v_fmac_f32_e32 v180, s8, v96
	v_fmac_f32_e32 v176, s9, v10
	v_readlane_b32 s6, v214, s50
	v_readlane_b32 s7, v213, s50
	v_readlane_b32 s8, v212, s50
	v_readlane_b32 s9, v211, s50
	v_fmac_f32_e32 v177, s6, v94
	v_fmac_f32_e32 v181, s7, v8
	v_fmac_f32_e32 v180, s8, v92
	v_fmac_f32_e32 v176, s9, v4
	v_readlane_b32 s6, v214, s64
	v_readlane_b32 s7, v213, s64
	v_readlane_b32 s8, v212, s64
	v_readlane_b32 s9, v211, s64
	v_fmac_f32_e32 v177, s6, v90
	v_fmac_f32_e32 v181, s7, v91
	v_fmac_f32_e32 v180, s8, v88
	v_fmac_f32_e32 v176, s9, v89
	v_pk_add_f32 v[176:177], v[180:181], v[176:177]
	v_mov_b32_e32 v181, v123
	v_mov_b32_e32 v180, v123
	v_pk_add_f32 v[176:177], v[176:177], v[176:177] op_sel:[0,1] op_sel_hi:[1,0]
	s_nop 0
	v_readlane_b32 s6, v206, s49
	v_readlane_b32 s7, v201, s65
	v_readlane_b32 s8, v204, s65
	v_readlane_b32 s9, v203, s65
	v_fmac_f32_e32 v157, s6, v176
	v_fmac_f32_e32 v181, s7, v150
	v_fmac_f32_e32 v180, s8, v178
	v_fmac_f32_e32 v156, s9, v148
	v_readlane_b32 s6, v206, s65
	v_readlane_b32 s7, v205, s49
	v_readlane_b32 s8, v208, s49
	v_readlane_b32 s9, v207, s49
	v_fmac_f32_e32 v157, s6, v174
	v_fmac_f32_e32 v181, s7, v146
	v_fmac_f32_e32 v180, s8, v170
	v_fmac_f32_e32 v156, s9, v144
	v_readlane_b32 s6, v209, s49
	v_readlane_b32 s7, v205, s65
	v_readlane_b32 s8, v208, s65
	v_readlane_b32 s9, v207, s65
	v_fmac_f32_e32 v157, s6, v166
	v_fmac_f32_e32 v181, s7, v142
	v_fmac_f32_e32 v180, s8, v158
	v_fmac_f32_e32 v156, s9, v140
	v_readlane_b32 s6, v209, s65
	v_readlane_b32 s7, v226, s49
	v_readlane_b32 s8, v225, s49
	v_readlane_b32 s9, v224, s49
	v_fmac_f32_e32 v157, s6, v152
	v_fmac_f32_e32 v181, s7, v138
	v_fmac_f32_e32 v180, s8, v80
	v_fmac_f32_e32 v156, s9, v136
	v_readlane_b32 s6, v223, s49
	v_readlane_b32 s7, v226, s65
	v_readlane_b32 s8, v225, s65
	v_readlane_b32 s9, v224, s65
	v_fmac_f32_e32 v157, s6, v76
	v_fmac_f32_e32 v181, s7, v134
	v_fmac_f32_e32 v180, s8, v72
	v_fmac_f32_e32 v156, s9, v132
	v_readlane_b32 s6, v223, s65
	v_readlane_b32 s7, v222, s49
	v_readlane_b32 s8, v221, s49
	v_readlane_b32 s9, v220, s49
	v_fmac_f32_e32 v157, s6, v68
	v_fmac_f32_e32 v181, s7, v130
	v_fmac_f32_e32 v180, s8, v64
	v_fmac_f32_e32 v156, s9, v128
	v_readlane_b32 s6, v219, s49
	v_readlane_b32 s7, v222, s65
	v_readlane_b32 s8, v221, s65
	v_readlane_b32 s9, v220, s65
	v_fmac_f32_e32 v157, s6, v32
	v_fmac_f32_e32 v181, s7, v118
	v_fmac_f32_e32 v180, s8, v30
	v_fmac_f32_e32 v156, s9, v116
	v_readlane_b32 s6, v219, s65
	v_readlane_b32 s7, v218, s49
	v_readlane_b32 s8, v217, s49
	v_readlane_b32 s9, v216, s49
	v_fmac_f32_e32 v157, s6, v26
	v_fmac_f32_e32 v181, s7, v114
	v_fmac_f32_e32 v180, s8, v22
	v_fmac_f32_e32 v156, s9, v110
	v_readlane_b32 s6, v215, s49
	v_readlane_b32 s7, v218, s65
	v_readlane_b32 s8, v217, s65
	v_readlane_b32 s9, v216, s65
	v_fmac_f32_e32 v157, s6, v16
	v_fmac_f32_e32 v181, s7, v104
	v_fmac_f32_e32 v180, s8, v12
	v_fmac_f32_e32 v156, s9, v96
	v_readlane_b32 s6, v215, s65
	v_readlane_b32 s7, v214, s49
	v_readlane_b32 s8, v213, s49
	v_readlane_b32 s9, v212, s49
	v_fmac_f32_e32 v157, s6, v10
	v_fmac_f32_e32 v181, s7, v94
	v_fmac_f32_e32 v180, s8, v8
	v_fmac_f32_e32 v156, s9, v92
	v_readlane_b32 s6, v211, s49
	v_readlane_b32 s7, v214, s65
	v_readlane_b32 s8, v213, s65
	v_readlane_b32 s9, v212, s65
	v_fmac_f32_e32 v157, s6, v4
	v_fmac_f32_e32 v181, s7, v90
	v_fmac_f32_e32 v180, s8, v91
	v_fmac_f32_e32 v156, s9, v88
	v_readlane_b32 s6, v211, s65
	s_nop 1
	v_fmac_f32_e32 v157, s6, v89
	v_pk_add_f32 v[156:157], v[180:181], v[156:157]
	v_mov_b32_e32 v181, v123
	v_mov_b32_e32 v180, v123
	v_pk_add_f32 v[156:157], v[156:157], v[156:157] op_sel:[0,1] op_sel_hi:[1,0]
	s_nop 0
	v_readlane_b32 s6, v203, s48
	v_readlane_b32 s7, v206, s48
	v_readlane_b32 s8, v201, s21
	v_readlane_b32 s9, v204, s21
	v_fmac_f32_e32 v173, s6, v156
	v_fmac_f32_e32 v181, s7, v176
	v_fmac_f32_e32 v180, s8, v150
	v_fmac_f32_e32 v172, s9, v178
	v_mov_b32_e32 v157, v176
	v_readlane_b32 s6, v203, s21
	v_readlane_b32 s7, v206, s21
	v_readlane_b32 s8, v205, s48
	v_readlane_b32 s9, v208, s48
	v_fmac_f32_e32 v173, s6, v148
	v_fmac_f32_e32 v181, s7, v174
	v_fmac_f32_e32 v180, s8, v146
	v_fmac_f32_e32 v172, s9, v170
	v_readlane_b32 s6, v207, s48
	v_readlane_b32 s7, v209, s48
	v_readlane_b32 s8, v205, s21
	v_readlane_b32 s9, v208, s21
	v_fmac_f32_e32 v173, s6, v144
	v_fmac_f32_e32 v181, s7, v166
	v_fmac_f32_e32 v180, s8, v142
	v_fmac_f32_e32 v172, s9, v158
	v_readlane_b32 s6, v207, s21
	v_readlane_b32 s7, v209, s21
	v_readlane_b32 s8, v226, s48
	v_readlane_b32 s9, v225, s48
	v_fmac_f32_e32 v173, s6, v140
	v_fmac_f32_e32 v181, s7, v152
	v_fmac_f32_e32 v180, s8, v138
	v_fmac_f32_e32 v172, s9, v80
	v_readlane_b32 s6, v224, s48
	v_readlane_b32 s7, v223, s48
	v_readlane_b32 s8, v226, s21
	v_readlane_b32 s9, v225, s21
	v_fmac_f32_e32 v173, s6, v136
	v_fmac_f32_e32 v181, s7, v76
	v_fmac_f32_e32 v180, s8, v134
	v_fmac_f32_e32 v172, s9, v72
	v_readlane_b32 s6, v224, s21
	v_readlane_b32 s7, v223, s21
	v_readlane_b32 s8, v222, s48
	v_readlane_b32 s9, v221, s48
	v_fmac_f32_e32 v173, s6, v132
	v_fmac_f32_e32 v181, s7, v68
	v_fmac_f32_e32 v180, s8, v130
	v_fmac_f32_e32 v172, s9, v64
	v_readlane_b32 s6, v220, s48
	v_readlane_b32 s7, v219, s48
	v_readlane_b32 s8, v222, s21
	v_readlane_b32 s9, v221, s21
	v_fmac_f32_e32 v173, s6, v128
	v_fmac_f32_e32 v181, s7, v32
	v_fmac_f32_e32 v180, s8, v118
	v_fmac_f32_e32 v172, s9, v30
	v_readlane_b32 s6, v220, s21
	v_readlane_b32 s7, v219, s21
	v_readlane_b32 s8, v218, s48
	v_readlane_b32 s9, v217, s48
	v_fmac_f32_e32 v173, s6, v116
	v_fmac_f32_e32 v181, s7, v26
	v_fmac_f32_e32 v180, s8, v114
	v_fmac_f32_e32 v172, s9, v22
	v_readlane_b32 s6, v216, s48
	v_readlane_b32 s7, v215, s48
	v_readlane_b32 s8, v218, s21
	v_readlane_b32 s9, v217, s21
	v_fmac_f32_e32 v173, s6, v110
	v_fmac_f32_e32 v181, s7, v16
	v_fmac_f32_e32 v180, s8, v104
	v_fmac_f32_e32 v172, s9, v12
	v_readlane_b32 s6, v216, s21
	v_readlane_b32 s7, v215, s21
	v_readlane_b32 s8, v214, s48
	v_readlane_b32 s9, v213, s48
	v_fmac_f32_e32 v173, s6, v96
	v_fmac_f32_e32 v181, s7, v10
	v_fmac_f32_e32 v180, s8, v94
	v_fmac_f32_e32 v172, s9, v8
	v_readlane_b32 s6, v212, s48
	v_readlane_b32 s7, v211, s48
	v_readlane_b32 s8, v214, s21
	v_readlane_b32 s9, v213, s21
	v_fmac_f32_e32 v173, s6, v92
	v_fmac_f32_e32 v181, s7, v4
	v_fmac_f32_e32 v180, s8, v90
	v_fmac_f32_e32 v172, s9, v91
	v_readlane_b32 s6, v212, s21
	s_nop 1
	v_fmac_f32_e32 v173, s6, v88
	v_readlane_b32 s6, v211, s21
	s_nop 1
	v_fmac_f32_e32 v173, s6, v89
	v_pk_add_f32 v[172:173], v[180:181], v[172:173]
	v_mov_b32_e32 v181, v123
	v_mov_b32_e32 v180, v123
	v_pk_add_f32 v[172:173], v[172:173], v[172:173] op_sel:[0,1] op_sel_hi:[1,0]
	s_nop 0
	v_readlane_b32 s6, v204, s47
	v_readlane_b32 s7, v203, s47
	v_readlane_b32 s8, v206, s47
	v_readlane_b32 s9, v201, s34
	v_fmac_f32_e32 v165, s6, v172
	v_fmac_f32_e32 v181, s7, v156
	v_fmac_f32_e32 v180, s8, v176
	v_fmac_f32_e32 v164, s9, v150
	v_readlane_b32 s6, v204, s34
	v_readlane_b32 s7, v203, s34
	v_readlane_b32 s8, v206, s34
	v_readlane_b32 s9, v205, s47
	v_fmac_f32_e32 v165, s6, v178
	v_fmac_f32_e32 v181, s7, v148
	v_fmac_f32_e32 v180, s8, v174
	v_fmac_f32_e32 v164, s9, v146
	v_readlane_b32 s6, v208, s47
	v_readlane_b32 s7, v207, s47
	v_readlane_b32 s8, v209, s47
	v_readlane_b32 s9, v205, s34
	v_fmac_f32_e32 v165, s6, v170
	v_fmac_f32_e32 v181, s7, v144
	v_fmac_f32_e32 v180, s8, v166
	v_fmac_f32_e32 v164, s9, v142
	v_readlane_b32 s6, v208, s34
	v_readlane_b32 s7, v207, s34
	v_readlane_b32 s8, v209, s34
	v_readlane_b32 s9, v226, s47
	v_fmac_f32_e32 v165, s6, v158
	v_fmac_f32_e32 v181, s7, v140
	v_fmac_f32_e32 v180, s8, v152
	v_fmac_f32_e32 v164, s9, v138
	v_readlane_b32 s6, v225, s47
	v_readlane_b32 s7, v224, s47
	v_readlane_b32 s8, v223, s47
	v_readlane_b32 s9, v226, s34
	v_fmac_f32_e32 v165, s6, v80
	v_fmac_f32_e32 v181, s7, v136
	v_fmac_f32_e32 v180, s8, v76
	v_fmac_f32_e32 v164, s9, v134
	v_readlane_b32 s6, v225, s34
	v_readlane_b32 s7, v224, s34
	v_readlane_b32 s8, v223, s34
	v_readlane_b32 s9, v222, s47
	v_fmac_f32_e32 v165, s6, v72
	v_fmac_f32_e32 v181, s7, v132
	v_fmac_f32_e32 v180, s8, v68
	v_fmac_f32_e32 v164, s9, v130
	v_readlane_b32 s6, v221, s47
	v_readlane_b32 s7, v220, s47
	v_readlane_b32 s8, v219, s47
	v_readlane_b32 s9, v222, s34
	v_fmac_f32_e32 v165, s6, v64
	v_fmac_f32_e32 v181, s7, v128
	v_fmac_f32_e32 v180, s8, v32
	v_fmac_f32_e32 v164, s9, v118
	v_readlane_b32 s6, v221, s34
	v_readlane_b32 s7, v220, s34
	v_readlane_b32 s8, v219, s34
	v_readlane_b32 s9, v218, s47
	v_fmac_f32_e32 v165, s6, v30
	v_fmac_f32_e32 v181, s7, v116
	v_fmac_f32_e32 v180, s8, v26
	v_fmac_f32_e32 v164, s9, v114
	v_readlane_b32 s6, v217, s47
	v_readlane_b32 s7, v216, s47
	v_readlane_b32 s8, v215, s47
	v_readlane_b32 s9, v218, s34
	v_fmac_f32_e32 v165, s6, v22
	v_fmac_f32_e32 v181, s7, v110
	v_fmac_f32_e32 v180, s8, v16
	v_fmac_f32_e32 v164, s9, v104
	v_readlane_b32 s6, v217, s34
	v_readlane_b32 s7, v216, s34
	v_readlane_b32 s8, v215, s34
	v_readlane_b32 s9, v214, s47
	v_fmac_f32_e32 v165, s6, v12
	v_fmac_f32_e32 v181, s7, v96
	v_fmac_f32_e32 v180, s8, v10
	v_fmac_f32_e32 v164, s9, v94
	v_readlane_b32 s6, v213, s47
	v_readlane_b32 s7, v212, s47
	v_readlane_b32 s8, v211, s47
	v_readlane_b32 s9, v214, s34
	v_fmac_f32_e32 v165, s6, v8
	v_fmac_f32_e32 v181, s7, v92
	v_fmac_f32_e32 v180, s8, v4
	v_fmac_f32_e32 v164, s9, v90
	v_readlane_b32 s6, v213, s34
	s_nop 1
	v_fmac_f32_e32 v165, s6, v91
	v_readlane_b32 s6, v212, s34
	s_nop 1
	v_fmac_f32_e32 v165, s6, v88
	v_readlane_b32 s6, v211, s34
	s_nop 1
	v_fmac_f32_e32 v165, s6, v89
	v_pk_add_f32 v[164:165], v[180:181], v[164:165]
	v_mov_b32_e32 v181, v123
	v_mov_b32_e32 v180, v123
	v_pk_add_f32 v[164:165], v[164:165], v[164:165] op_sel:[0,1] op_sel_hi:[1,0]
	s_nop 0
	v_readlane_b32 s6, v201, s45
	v_readlane_b32 s7, v204, s45
	v_readlane_b32 s8, v203, s45
	v_readlane_b32 s9, v206, s45
	v_fmac_f32_e32 v169, s6, v164
	v_fmac_f32_e32 v181, s7, v172
	v_fmac_f32_e32 v180, s8, v156
	v_fmac_f32_e32 v168, s9, v176
	v_mov_b32_e32 v165, v172
	v_readlane_b32 s6, v201, s66
	v_readlane_b32 s7, v204, s66
	v_readlane_b32 s8, v203, s66
	v_readlane_b32 s9, v206, s66
	v_fmac_f32_e32 v169, s6, v150
	v_fmac_f32_e32 v181, s7, v178
	v_fmac_f32_e32 v180, s8, v148
	v_fmac_f32_e32 v168, s9, v174
	v_readlane_b32 s6, v205, s45
	v_readlane_b32 s7, v208, s45
	v_readlane_b32 s8, v207, s45
	v_readlane_b32 s9, v209, s45
	v_fmac_f32_e32 v169, s6, v146
	v_fmac_f32_e32 v181, s7, v170
	v_fmac_f32_e32 v180, s8, v144
	v_fmac_f32_e32 v168, s9, v166
	v_readlane_b32 s6, v205, s66
	v_readlane_b32 s7, v208, s66
	v_readlane_b32 s8, v207, s66
	v_readlane_b32 s9, v209, s66
	v_fmac_f32_e32 v169, s6, v142
	v_fmac_f32_e32 v181, s7, v158
	v_fmac_f32_e32 v180, s8, v140
	v_fmac_f32_e32 v168, s9, v152
	v_readlane_b32 s6, v226, s45
	v_readlane_b32 s7, v225, s45
	v_readlane_b32 s8, v224, s45
	v_readlane_b32 s9, v223, s45
	v_fmac_f32_e32 v169, s6, v138
	v_fmac_f32_e32 v181, s7, v80
	v_fmac_f32_e32 v180, s8, v136
	v_fmac_f32_e32 v168, s9, v76
	v_readlane_b32 s6, v226, s66
	v_readlane_b32 s7, v225, s66
	v_readlane_b32 s8, v224, s66
	v_readlane_b32 s9, v223, s66
	v_fmac_f32_e32 v169, s6, v134
	v_fmac_f32_e32 v181, s7, v72
	v_fmac_f32_e32 v180, s8, v132
	v_fmac_f32_e32 v168, s9, v68
	v_readlane_b32 s6, v222, s45
	v_readlane_b32 s7, v221, s45
	v_readlane_b32 s8, v220, s45
	v_readlane_b32 s9, v219, s45
	v_fmac_f32_e32 v169, s6, v130
	v_fmac_f32_e32 v181, s7, v64
	v_fmac_f32_e32 v180, s8, v128
	v_fmac_f32_e32 v168, s9, v32
	v_readlane_b32 s6, v222, s66
	v_readlane_b32 s7, v221, s66
	v_readlane_b32 s8, v220, s66
	v_readlane_b32 s9, v219, s66
	v_fmac_f32_e32 v169, s6, v118
	v_fmac_f32_e32 v181, s7, v30
	v_fmac_f32_e32 v180, s8, v116
	v_fmac_f32_e32 v168, s9, v26
	v_readlane_b32 s6, v218, s45
	v_readlane_b32 s7, v217, s45
	v_readlane_b32 s8, v216, s45
	v_readlane_b32 s9, v215, s45
	v_fmac_f32_e32 v169, s6, v114
	v_fmac_f32_e32 v181, s7, v22
	v_fmac_f32_e32 v180, s8, v110
	v_fmac_f32_e32 v168, s9, v16
	v_readlane_b32 s6, v218, s66
	v_readlane_b32 s7, v217, s66
	v_readlane_b32 s8, v216, s66
	v_readlane_b32 s9, v215, s66
	v_fmac_f32_e32 v169, s6, v104
	v_fmac_f32_e32 v181, s7, v12
	v_fmac_f32_e32 v180, s8, v96
	v_fmac_f32_e32 v168, s9, v10
	v_readlane_b32 s6, v214, s45
	v_readlane_b32 s7, v213, s45
	v_readlane_b32 s8, v212, s45
	v_readlane_b32 s9, v211, s45
	v_fmac_f32_e32 v169, s6, v94
	v_fmac_f32_e32 v181, s7, v8
	v_fmac_f32_e32 v180, s8, v92
	v_fmac_f32_e32 v168, s9, v4
	v_readlane_b32 s6, v214, s66
	v_readlane_b32 s7, v213, s66
	v_readlane_b32 s8, v212, s66
	v_readlane_b32 s9, v211, s66
	v_fmac_f32_e32 v169, s6, v90
	v_fmac_f32_e32 v181, s7, v91
	v_fmac_f32_e32 v180, s8, v88
	v_fmac_f32_e32 v168, s9, v89
	v_pk_add_f32 v[168:169], v[180:181], v[168:169]
	s_nop 0
	v_pk_add_f32 v[180:181], v[168:169], v[168:169] op_sel:[0,1] op_sel_hi:[1,0]
	v_mov_b32_e32 v169, v123
	v_mov_b32_e32 v168, v123
	v_readlane_b32 s6, v202, s14
	v_readlane_b32 s7, v201, s39
	v_readlane_b32 s8, v204, s39
	v_readlane_b32 s9, v203, s39
	v_fmac_f32_e32 v163, s6, v180
	v_fmac_f32_e32 v169, s7, v164
	v_fmac_f32_e32 v168, s8, v172
	v_fmac_f32_e32 v162, s9, v156
	v_readlane_b32 s6, v206, s39
	v_readlane_b32 s7, v201, s14
	v_readlane_b32 s8, v204, s14
	v_readlane_b32 s9, v203, s14
	v_fmac_f32_e32 v163, s6, v176
	v_fmac_f32_e32 v169, s7, v150
	v_fmac_f32_e32 v168, s8, v178
	v_fmac_f32_e32 v162, s9, v148
	v_readlane_b32 s6, v206, s14
	v_readlane_b32 s7, v205, s39
	v_readlane_b32 s8, v208, s39
	v_readlane_b32 s9, v207, s39
	v_fmac_f32_e32 v163, s6, v174
	v_fmac_f32_e32 v169, s7, v146
	v_fmac_f32_e32 v168, s8, v170
	v_fmac_f32_e32 v162, s9, v144
	v_readlane_b32 s6, v209, s39
	v_readlane_b32 s7, v205, s14
	v_readlane_b32 s8, v208, s14
	v_readlane_b32 s9, v207, s14
	v_fmac_f32_e32 v163, s6, v166
	v_fmac_f32_e32 v169, s7, v142
	v_fmac_f32_e32 v168, s8, v158
	v_fmac_f32_e32 v162, s9, v140
	v_readlane_b32 s6, v209, s14
	v_readlane_b32 s7, v226, s39
	v_readlane_b32 s8, v225, s39
	v_readlane_b32 s9, v224, s39
	v_fmac_f32_e32 v163, s6, v152
	v_fmac_f32_e32 v169, s7, v138
	v_fmac_f32_e32 v168, s8, v80
	v_fmac_f32_e32 v162, s9, v136
	v_readlane_b32 s6, v223, s39
	v_readlane_b32 s7, v226, s14
	v_readlane_b32 s8, v225, s14
	v_readlane_b32 s9, v224, s14
	v_fmac_f32_e32 v163, s6, v76
	v_fmac_f32_e32 v169, s7, v134
	v_fmac_f32_e32 v168, s8, v72
	v_fmac_f32_e32 v162, s9, v132
	v_readlane_b32 s6, v223, s14
	v_readlane_b32 s7, v222, s39
	v_readlane_b32 s8, v221, s39
	v_readlane_b32 s9, v220, s39
	v_fmac_f32_e32 v163, s6, v68
	v_fmac_f32_e32 v169, s7, v130
	v_fmac_f32_e32 v168, s8, v64
	v_fmac_f32_e32 v162, s9, v128
	v_readlane_b32 s6, v219, s39
	v_readlane_b32 s7, v222, s14
	v_readlane_b32 s8, v221, s14
	v_readlane_b32 s9, v220, s14
	v_fmac_f32_e32 v163, s6, v32
	v_fmac_f32_e32 v169, s7, v118
	v_fmac_f32_e32 v168, s8, v30
	v_fmac_f32_e32 v162, s9, v116
	v_readlane_b32 s6, v219, s14
	v_readlane_b32 s7, v218, s39
	v_readlane_b32 s8, v217, s39
	v_readlane_b32 s9, v216, s39
	v_fmac_f32_e32 v163, s6, v26
	v_fmac_f32_e32 v169, s7, v114
	v_fmac_f32_e32 v168, s8, v22
	v_fmac_f32_e32 v162, s9, v110
	v_readlane_b32 s6, v215, s39
	v_readlane_b32 s7, v218, s14
	v_readlane_b32 s8, v217, s14
	v_readlane_b32 s9, v216, s14
	v_fmac_f32_e32 v163, s6, v16
	v_fmac_f32_e32 v169, s7, v104
	v_fmac_f32_e32 v168, s8, v12
	v_fmac_f32_e32 v162, s9, v96
	v_readlane_b32 s6, v215, s14
	v_readlane_b32 s7, v214, s39
	v_readlane_b32 s8, v213, s39
	v_readlane_b32 s9, v212, s39
	v_fmac_f32_e32 v163, s6, v10
	v_fmac_f32_e32 v169, s7, v94
	v_fmac_f32_e32 v168, s8, v8
	v_fmac_f32_e32 v162, s9, v92
	v_readlane_b32 s6, v211, s39
	v_readlane_b32 s7, v214, s14
	v_readlane_b32 s8, v213, s14
	v_readlane_b32 s9, v212, s14
	v_fmac_f32_e32 v163, s6, v4
	v_fmac_f32_e32 v169, s7, v90
	v_fmac_f32_e32 v168, s8, v91
	v_fmac_f32_e32 v162, s9, v88
	v_readlane_b32 s6, v211, s14
	s_nop 1
	v_fmac_f32_e32 v163, s6, v89
	v_pk_add_f32 v[162:163], v[168:169], v[162:163]
	v_mov_b32_e32 v169, v123
	v_mov_b32_e32 v168, v123
	v_pk_add_f32 v[162:163], v[162:163], v[162:163] op_sel:[0,1] op_sel_hi:[1,0]
	s_nop 0
	v_readlane_b32 s6, v199, s11
	v_readlane_b32 s7, v202, s11
	v_readlane_b32 s8, v201, s38
	v_readlane_b32 s9, v204, s38
	v_fmac_f32_e32 v161, s6, v162
	v_fmac_f32_e32 v169, s7, v180
	v_fmac_f32_e32 v168, s8, v164
	v_fmac_f32_e32 v160, s9, v172
	v_mov_b32_e32 v163, v180
	v_readlane_b32 s6, v203, s38
	v_readlane_b32 s7, v206, s38
	v_readlane_b32 s8, v201, s11
	v_readlane_b32 s9, v204, s11
	v_fmac_f32_e32 v161, s6, v156
	v_fmac_f32_e32 v169, s7, v176
	v_fmac_f32_e32 v168, s8, v150
	v_fmac_f32_e32 v160, s9, v178
	v_readlane_b32 s6, v203, s11
	v_readlane_b32 s7, v206, s11
	v_readlane_b32 s8, v205, s38
	v_readlane_b32 s9, v208, s38
	v_fmac_f32_e32 v161, s6, v148
	v_fmac_f32_e32 v169, s7, v174
	v_fmac_f32_e32 v168, s8, v146
	v_fmac_f32_e32 v160, s9, v170
	v_readlane_b32 s6, v207, s38
	v_readlane_b32 s7, v209, s38
	v_readlane_b32 s8, v205, s11
	v_readlane_b32 s9, v208, s11
	v_fmac_f32_e32 v161, s6, v144
	v_fmac_f32_e32 v169, s7, v166
	v_fmac_f32_e32 v168, s8, v142
	v_fmac_f32_e32 v160, s9, v158
	v_readlane_b32 s6, v207, s11
	v_readlane_b32 s7, v209, s11
	v_readlane_b32 s8, v226, s38
	v_readlane_b32 s9, v225, s38
	v_fmac_f32_e32 v161, s6, v140
	v_fmac_f32_e32 v169, s7, v152
	v_fmac_f32_e32 v168, s8, v138
	v_fmac_f32_e32 v160, s9, v80
	v_readlane_b32 s6, v224, s38
	v_readlane_b32 s7, v223, s38
	v_readlane_b32 s8, v226, s11
	v_readlane_b32 s9, v225, s11
	v_fmac_f32_e32 v161, s6, v136
	v_fmac_f32_e32 v169, s7, v76
	v_fmac_f32_e32 v168, s8, v134
	v_fmac_f32_e32 v160, s9, v72
	v_readlane_b32 s6, v224, s11
	v_readlane_b32 s7, v223, s11
	v_readlane_b32 s8, v222, s38
	v_readlane_b32 s9, v221, s38
	v_fmac_f32_e32 v161, s6, v132
	v_fmac_f32_e32 v169, s7, v68
	v_fmac_f32_e32 v168, s8, v130
	v_fmac_f32_e32 v160, s9, v64
	v_readlane_b32 s6, v220, s38
	v_readlane_b32 s7, v219, s38
	v_readlane_b32 s8, v222, s11
	v_readlane_b32 s9, v221, s11
	v_fmac_f32_e32 v161, s6, v128
	v_fmac_f32_e32 v169, s7, v32
	v_fmac_f32_e32 v168, s8, v118
	v_fmac_f32_e32 v160, s9, v30
	v_readlane_b32 s6, v220, s11
	v_readlane_b32 s7, v219, s11
	v_readlane_b32 s8, v218, s38
	v_readlane_b32 s9, v217, s38
	v_fmac_f32_e32 v161, s6, v116
	v_fmac_f32_e32 v169, s7, v26
	v_fmac_f32_e32 v168, s8, v114
	v_fmac_f32_e32 v160, s9, v22
	v_readlane_b32 s6, v216, s38
	v_readlane_b32 s7, v215, s38
	v_readlane_b32 s8, v218, s11
	v_readlane_b32 s9, v217, s11
	v_fmac_f32_e32 v161, s6, v110
	v_fmac_f32_e32 v169, s7, v16
	v_fmac_f32_e32 v168, s8, v104
	v_fmac_f32_e32 v160, s9, v12
	v_readlane_b32 s6, v216, s11
	v_readlane_b32 s7, v215, s11
	v_readlane_b32 s8, v214, s38
	v_readlane_b32 s9, v213, s38
	v_fmac_f32_e32 v161, s6, v96
	v_fmac_f32_e32 v169, s7, v10
	v_fmac_f32_e32 v168, s8, v94
	v_fmac_f32_e32 v160, s9, v8
	v_readlane_b32 s6, v212, s38
	v_readlane_b32 s7, v211, s38
	v_readlane_b32 s8, v214, s11
	v_readlane_b32 s9, v213, s11
	v_fmac_f32_e32 v161, s6, v92
	v_fmac_f32_e32 v169, s7, v4
	v_fmac_f32_e32 v168, s8, v90
	v_fmac_f32_e32 v160, s9, v91
	v_readlane_b32 s6, v212, s11
	s_nop 1
	v_fmac_f32_e32 v161, s6, v88
	v_readlane_b32 s6, v211, s11
	s_nop 1
	v_fmac_f32_e32 v161, s6, v89
	v_pk_add_f32 v[160:161], v[168:169], v[160:161]
	s_nop 0
	v_pk_add_f32 v[184:185], v[160:161], v[160:161] op_sel:[0,1] op_sel_hi:[1,0]
	v_mov_b32_e32 v161, v123
	v_mov_b32_e32 v160, v123
	v_readlane_b32 s6, v200, s27
	v_readlane_b32 s7, v199, s27
	v_readlane_b32 s8, v202, s27
	v_readlane_b32 s9, v201, s43
	v_fmac_f32_e32 v155, s6, v184
	v_fmac_f32_e32 v161, s7, v162
	v_fmac_f32_e32 v160, s8, v180
	v_fmac_f32_e32 v154, s9, v164
	v_readlane_b32 s6, v204, s43
	v_readlane_b32 s7, v203, s43
	v_readlane_b32 s8, v206, s43
	v_readlane_b32 s9, v201, s27
	v_fmac_f32_e32 v155, s6, v172
	v_fmac_f32_e32 v161, s7, v156
	v_fmac_f32_e32 v160, s8, v176
	v_fmac_f32_e32 v154, s9, v150
	v_readlane_b32 s6, v204, s27
	v_readlane_b32 s7, v203, s27
	v_readlane_b32 s8, v206, s27
	v_readlane_b32 s9, v205, s43
	v_fmac_f32_e32 v155, s6, v178
	v_fmac_f32_e32 v161, s7, v148
	v_fmac_f32_e32 v160, s8, v174
	v_fmac_f32_e32 v154, s9, v146
	v_readlane_b32 s6, v208, s43
	v_readlane_b32 s7, v207, s43
	v_readlane_b32 s8, v209, s43
	v_readlane_b32 s9, v205, s27
	v_fmac_f32_e32 v155, s6, v170
	v_fmac_f32_e32 v161, s7, v144
	v_fmac_f32_e32 v160, s8, v166
	v_fmac_f32_e32 v154, s9, v142
	v_readlane_b32 s6, v208, s27
	v_readlane_b32 s7, v207, s27
	v_readlane_b32 s8, v209, s27
	v_readlane_b32 s9, v226, s43
	v_fmac_f32_e32 v155, s6, v158
	v_fmac_f32_e32 v161, s7, v140
	v_fmac_f32_e32 v160, s8, v152
	v_fmac_f32_e32 v154, s9, v138
	v_readlane_b32 s6, v225, s43
	v_readlane_b32 s7, v224, s43
	v_readlane_b32 s8, v223, s43
	v_readlane_b32 s9, v226, s27
	v_fmac_f32_e32 v155, s6, v80
	v_fmac_f32_e32 v161, s7, v136
	v_fmac_f32_e32 v160, s8, v76
	v_fmac_f32_e32 v154, s9, v134
	v_readlane_b32 s6, v225, s27
	v_readlane_b32 s7, v224, s27
	v_readlane_b32 s8, v223, s27
	v_readlane_b32 s9, v222, s43
	v_fmac_f32_e32 v155, s6, v72
	v_fmac_f32_e32 v161, s7, v132
	v_fmac_f32_e32 v160, s8, v68
	v_fmac_f32_e32 v154, s9, v130
	v_readlane_b32 s6, v221, s43
	v_readlane_b32 s7, v220, s43
	v_readlane_b32 s8, v219, s43
	v_readlane_b32 s9, v222, s27
	v_fmac_f32_e32 v155, s6, v64
	v_fmac_f32_e32 v161, s7, v128
	v_fmac_f32_e32 v160, s8, v32
	v_fmac_f32_e32 v154, s9, v118
	v_readlane_b32 s6, v221, s27
	v_readlane_b32 s7, v220, s27
	v_readlane_b32 s8, v219, s27
	v_readlane_b32 s9, v218, s43
	v_fmac_f32_e32 v155, s6, v30
	v_fmac_f32_e32 v161, s7, v116
	v_fmac_f32_e32 v160, s8, v26
	v_fmac_f32_e32 v154, s9, v114
	v_readlane_b32 s6, v217, s43
	v_readlane_b32 s7, v216, s43
	v_readlane_b32 s8, v215, s43
	v_readlane_b32 s9, v218, s27
	v_fmac_f32_e32 v155, s6, v22
	v_fmac_f32_e32 v161, s7, v110
	v_fmac_f32_e32 v160, s8, v16
	v_fmac_f32_e32 v154, s9, v104
	v_readlane_b32 s6, v217, s27
	v_readlane_b32 s7, v216, s27
	v_readlane_b32 s8, v215, s27
	v_readlane_b32 s9, v214, s43
	v_fmac_f32_e32 v155, s6, v12
	v_fmac_f32_e32 v161, s7, v96
	v_fmac_f32_e32 v160, s8, v10
	v_fmac_f32_e32 v154, s9, v94
	v_readlane_b32 s6, v213, s43
	v_readlane_b32 s7, v212, s43
	v_readlane_b32 s8, v211, s43
	v_readlane_b32 s9, v214, s27
	v_fmac_f32_e32 v155, s6, v8
	v_fmac_f32_e32 v161, s7, v92
	v_fmac_f32_e32 v160, s8, v4
	v_fmac_f32_e32 v154, s9, v90
	v_readlane_b32 s6, v213, s27
	s_nop 1
	v_fmac_f32_e32 v155, s6, v91
	v_readlane_b32 s6, v212, s27
	s_nop 1
	v_fmac_f32_e32 v155, s6, v88
	v_readlane_b32 s6, v211, s27
	s_nop 1
	v_fmac_f32_e32 v155, s6, v89
	v_pk_add_f32 v[154:155], v[160:161], v[154:155]
	v_mov_b32_e32 v161, v123
	v_mov_b32_e32 v160, v123
	v_pk_add_f32 v[154:155], v[154:155], v[154:155] op_sel:[0,1] op_sel_hi:[1,0]
	s_nop 0
	v_readlane_b32 s6, v197, s67
	v_readlane_b32 s7, v200, s67
	v_readlane_b32 s8, v199, s67
	v_readlane_b32 s9, v202, s67
	v_fmac_f32_e32 v85, s6, v154
	v_fmac_f32_e32 v161, s7, v184
	v_fmac_f32_e32 v160, s8, v162
	v_fmac_f32_e32 v84, s9, v180
	v_mov_b32_e32 v155, v184
	v_readlane_b32 s6, v201, s42
	v_readlane_b32 s7, v204, s42
	v_readlane_b32 s8, v203, s42
	v_readlane_b32 s9, v206, s42
	v_fmac_f32_e32 v85, s6, v164
	v_fmac_f32_e32 v161, s7, v172
	v_fmac_f32_e32 v160, s8, v156
	v_fmac_f32_e32 v84, s9, v176
	v_readlane_b32 s6, v201, s67
	v_readlane_b32 s7, v204, s67
	v_readlane_b32 s8, v203, s67
	v_readlane_b32 s9, v206, s67
	v_fmac_f32_e32 v85, s6, v150
	v_fmac_f32_e32 v161, s7, v178
	v_fmac_f32_e32 v160, s8, v148
	v_fmac_f32_e32 v84, s9, v174
	v_readlane_b32 s6, v205, s42
	v_readlane_b32 s7, v208, s42
	v_readlane_b32 s8, v207, s42
	v_readlane_b32 s9, v209, s42
	v_fmac_f32_e32 v85, s6, v146
	v_fmac_f32_e32 v161, s7, v170
	v_fmac_f32_e32 v160, s8, v144
	v_fmac_f32_e32 v84, s9, v166
	v_readlane_b32 s6, v205, s67
	v_readlane_b32 s7, v208, s67
	v_readlane_b32 s8, v207, s67
	v_readlane_b32 s9, v209, s67
	v_fmac_f32_e32 v85, s6, v142
	v_fmac_f32_e32 v161, s7, v158
	v_fmac_f32_e32 v160, s8, v140
	v_fmac_f32_e32 v84, s9, v152
	v_readlane_b32 s6, v226, s42
	v_readlane_b32 s7, v225, s42
	v_readlane_b32 s8, v224, s42
	v_readlane_b32 s9, v223, s42
	v_fmac_f32_e32 v85, s6, v138
	v_fmac_f32_e32 v161, s7, v80
	v_fmac_f32_e32 v160, s8, v136
	v_fmac_f32_e32 v84, s9, v76
	v_readlane_b32 s6, v226, s67
	v_readlane_b32 s7, v225, s67
	v_readlane_b32 s8, v224, s67
	v_readlane_b32 s9, v223, s67
	v_fmac_f32_e32 v85, s6, v134
	v_fmac_f32_e32 v161, s7, v72
	v_fmac_f32_e32 v160, s8, v132
	v_fmac_f32_e32 v84, s9, v68
	v_readlane_b32 s6, v222, s42
	v_readlane_b32 s7, v221, s42
	v_readlane_b32 s8, v220, s42
	v_readlane_b32 s9, v219, s42
	v_fmac_f32_e32 v85, s6, v130
	v_fmac_f32_e32 v161, s7, v64
	v_fmac_f32_e32 v160, s8, v128
	v_fmac_f32_e32 v84, s9, v32
	v_readlane_b32 s6, v222, s67
	v_readlane_b32 s7, v221, s67
	v_readlane_b32 s8, v220, s67
	v_readlane_b32 s9, v219, s67
	v_fmac_f32_e32 v85, s6, v118
	v_fmac_f32_e32 v161, s7, v30
	v_fmac_f32_e32 v160, s8, v116
	v_fmac_f32_e32 v84, s9, v26
	v_readlane_b32 s6, v218, s42
	v_readlane_b32 s7, v217, s42
	v_readlane_b32 s8, v216, s42
	v_readlane_b32 s9, v215, s42
	v_fmac_f32_e32 v85, s6, v114
	v_fmac_f32_e32 v161, s7, v22
	v_fmac_f32_e32 v160, s8, v110
	v_fmac_f32_e32 v84, s9, v16
	v_readlane_b32 s6, v218, s67
	v_readlane_b32 s7, v217, s67
	v_readlane_b32 s8, v216, s67
	v_readlane_b32 s9, v215, s67
	v_fmac_f32_e32 v85, s6, v104
	v_fmac_f32_e32 v161, s7, v12
	v_fmac_f32_e32 v160, s8, v96
	v_fmac_f32_e32 v84, s9, v10
	v_readlane_b32 s6, v214, s42
	v_readlane_b32 s7, v213, s42
	v_readlane_b32 s8, v212, s42
	v_readlane_b32 s9, v211, s42
	v_fmac_f32_e32 v85, s6, v94
	v_fmac_f32_e32 v161, s7, v8
	v_fmac_f32_e32 v160, s8, v92
	v_fmac_f32_e32 v84, s9, v4
	v_readlane_b32 s6, v214, s67
	v_readlane_b32 s7, v213, s67
	v_readlane_b32 s8, v212, s67
	v_readlane_b32 s9, v211, s67
	v_fmac_f32_e32 v85, s6, v90
	v_fmac_f32_e32 v161, s7, v91
	v_fmac_f32_e32 v160, s8, v88
	v_fmac_f32_e32 v84, s9, v89
	v_pk_add_f32 v[84:85], v[160:161], v[84:85]
	v_mov_b32_e32 v161, v123
	v_mov_b32_e32 v160, v123
	v_pk_add_f32 v[84:85], v[84:85], v[84:85] op_sel:[0,1] op_sel_hi:[1,0]
	s_nop 0
	v_readlane_b32 s6, v202, s46
	v_readlane_b32 s7, v197, s2
	v_readlane_b32 s8, v200, s2
	v_readlane_b32 s9, v199, s2
	v_fmac_f32_e32 v83, s6, v84
	v_fmac_f32_e32 v161, s7, v154
	v_fmac_f32_e32 v160, s8, v184
	v_fmac_f32_e32 v82, s9, v162
	v_readlane_b32 s6, v202, s2
	v_readlane_b32 s7, v201, s46
	v_readlane_b32 s8, v204, s46
	v_readlane_b32 s9, v203, s46
	v_fmac_f32_e32 v83, s6, v180
	v_fmac_f32_e32 v161, s7, v164
	v_fmac_f32_e32 v160, s8, v172
	v_fmac_f32_e32 v82, s9, v156
	v_readlane_b32 s6, v206, s46
	v_readlane_b32 s7, v201, s2
	v_readlane_b32 s8, v204, s2
	v_readlane_b32 s9, v203, s2
	v_fmac_f32_e32 v83, s6, v176
	v_fmac_f32_e32 v161, s7, v150
	v_fmac_f32_e32 v160, s8, v178
	v_fmac_f32_e32 v82, s9, v148
	v_readlane_b32 s6, v206, s2
	v_readlane_b32 s7, v205, s46
	v_readlane_b32 s8, v208, s46
	v_readlane_b32 s9, v207, s46
	v_fmac_f32_e32 v83, s6, v174
	v_fmac_f32_e32 v161, s7, v146
	v_fmac_f32_e32 v160, s8, v170
	v_fmac_f32_e32 v82, s9, v144
	v_readlane_b32 s6, v209, s46
	v_readlane_b32 s7, v205, s2
	v_readlane_b32 s8, v208, s2
	v_readlane_b32 s9, v207, s2
	v_fmac_f32_e32 v83, s6, v166
	v_fmac_f32_e32 v161, s7, v142
	v_fmac_f32_e32 v160, s8, v158
	v_fmac_f32_e32 v82, s9, v140
	v_readlane_b32 s6, v209, s2
	v_readlane_b32 s7, v226, s46
	v_readlane_b32 s8, v225, s46
	v_readlane_b32 s9, v224, s46
	v_fmac_f32_e32 v83, s6, v152
	v_fmac_f32_e32 v161, s7, v138
	v_fmac_f32_e32 v160, s8, v80
	v_fmac_f32_e32 v82, s9, v136
	v_readlane_b32 s6, v223, s46
	v_readlane_b32 s7, v226, s2
	v_readlane_b32 s8, v225, s2
	v_readlane_b32 s9, v224, s2
	v_fmac_f32_e32 v83, s6, v76
	v_fmac_f32_e32 v161, s7, v134
	v_fmac_f32_e32 v160, s8, v72
	v_fmac_f32_e32 v82, s9, v132
	v_readlane_b32 s6, v223, s2
	v_readlane_b32 s7, v222, s46
	v_readlane_b32 s8, v221, s46
	v_readlane_b32 s9, v220, s46
	v_fmac_f32_e32 v83, s6, v68
	v_fmac_f32_e32 v161, s7, v130
	v_fmac_f32_e32 v160, s8, v64
	v_fmac_f32_e32 v82, s9, v128
	v_readlane_b32 s6, v219, s46
	v_readlane_b32 s7, v222, s2
	v_readlane_b32 s8, v221, s2
	v_readlane_b32 s9, v220, s2
	v_fmac_f32_e32 v83, s6, v32
	v_fmac_f32_e32 v161, s7, v118
	v_fmac_f32_e32 v160, s8, v30
	v_fmac_f32_e32 v82, s9, v116
	v_readlane_b32 s6, v219, s2
	v_readlane_b32 s7, v218, s46
	v_readlane_b32 s8, v217, s46
	v_readlane_b32 s9, v216, s46
	v_fmac_f32_e32 v83, s6, v26
	v_fmac_f32_e32 v161, s7, v114
	v_fmac_f32_e32 v160, s8, v22
	v_fmac_f32_e32 v82, s9, v110
	v_readlane_b32 s6, v215, s46
	v_readlane_b32 s7, v218, s2
	v_readlane_b32 s8, v217, s2
	v_readlane_b32 s9, v216, s2
	v_fmac_f32_e32 v83, s6, v16
	v_fmac_f32_e32 v161, s7, v104
	v_fmac_f32_e32 v160, s8, v12
	v_fmac_f32_e32 v82, s9, v96
	v_readlane_b32 s6, v215, s2
	v_readlane_b32 s7, v214, s46
	v_readlane_b32 s8, v213, s46
	v_readlane_b32 s9, v212, s46
	v_fmac_f32_e32 v83, s6, v10
	v_fmac_f32_e32 v161, s7, v94
	v_fmac_f32_e32 v160, s8, v8
	v_fmac_f32_e32 v82, s9, v92
	v_readlane_b32 s6, v211, s46
	v_readlane_b32 s7, v214, s2
	v_readlane_b32 s8, v213, s2
	v_readlane_b32 s9, v212, s2
	v_fmac_f32_e32 v83, s6, v4
	v_fmac_f32_e32 v161, s7, v90
	v_fmac_f32_e32 v160, s8, v91
	v_fmac_f32_e32 v82, s9, v88
	v_readlane_b32 s6, v211, s2
	s_nop 1
	v_fmac_f32_e32 v83, s6, v89
	v_pk_add_f32 v[82:83], v[160:161], v[82:83]
	s_nop 0
	v_pk_add_f32 v[160:161], v[82:83], v[82:83] op_sel:[0,1] op_sel_hi:[1,0]
	v_mov_b32_e32 v83, v123
	v_mov_b32_e32 v82, v123
	v_readlane_b32 s6, v199, s37
	v_readlane_b32 s7, v202, s37
	v_readlane_b32 s8, v197, s18
	v_readlane_b32 s9, v200, s18
	v_fmac_f32_e32 v79, s6, v160
	v_fmac_f32_e32 v83, s7, v84
	v_fmac_f32_e32 v82, s8, v154
	v_fmac_f32_e32 v78, s9, v184
	v_mov_b32_e32 v161, v84
	v_readlane_b32 s6, v199, s18
	v_readlane_b32 s7, v202, s18
	v_readlane_b32 s8, v201, s37
	v_readlane_b32 s9, v204, s37
	v_fmac_f32_e32 v79, s6, v162
	v_fmac_f32_e32 v83, s7, v180
	v_fmac_f32_e32 v82, s8, v164
	v_fmac_f32_e32 v78, s9, v172
	v_readlane_b32 s6, v203, s37
	v_readlane_b32 s7, v206, s37
	v_readlane_b32 s8, v201, s18
	v_readlane_b32 s9, v204, s18
	v_fmac_f32_e32 v79, s6, v156
	v_fmac_f32_e32 v83, s7, v176
	v_fmac_f32_e32 v82, s8, v150
	v_fmac_f32_e32 v78, s9, v178
	v_readlane_b32 s6, v203, s18
	v_readlane_b32 s7, v206, s18
	v_readlane_b32 s8, v205, s37
	v_readlane_b32 s9, v208, s37
	v_fmac_f32_e32 v79, s6, v148
	v_fmac_f32_e32 v83, s7, v174
	v_fmac_f32_e32 v82, s8, v146
	v_fmac_f32_e32 v78, s9, v170
	v_readlane_b32 s6, v207, s37
	v_readlane_b32 s7, v209, s37
	v_readlane_b32 s8, v205, s18
	v_readlane_b32 s9, v208, s18
	v_fmac_f32_e32 v79, s6, v144
	v_fmac_f32_e32 v83, s7, v166
	v_fmac_f32_e32 v82, s8, v142
	v_fmac_f32_e32 v78, s9, v158
	v_readlane_b32 s6, v207, s18
	v_readlane_b32 s7, v209, s18
	v_readlane_b32 s8, v226, s37
	v_readlane_b32 s9, v225, s37
	v_fmac_f32_e32 v79, s6, v140
	v_fmac_f32_e32 v83, s7, v152
	v_fmac_f32_e32 v82, s8, v138
	v_fmac_f32_e32 v78, s9, v80
	v_readlane_b32 s6, v224, s37
	v_readlane_b32 s7, v223, s37
	v_readlane_b32 s8, v226, s18
	v_readlane_b32 s9, v225, s18
	v_fmac_f32_e32 v79, s6, v136
	v_fmac_f32_e32 v83, s7, v76
	v_fmac_f32_e32 v82, s8, v134
	v_fmac_f32_e32 v78, s9, v72
	v_readlane_b32 s6, v224, s18
	v_readlane_b32 s7, v223, s18
	v_readlane_b32 s8, v222, s37
	v_readlane_b32 s9, v221, s37
	v_fmac_f32_e32 v79, s6, v132
	v_fmac_f32_e32 v83, s7, v68
	v_fmac_f32_e32 v82, s8, v130
	v_fmac_f32_e32 v78, s9, v64
	v_readlane_b32 s6, v220, s37
	v_readlane_b32 s7, v219, s37
	v_readlane_b32 s8, v222, s18
	v_readlane_b32 s9, v221, s18
	v_fmac_f32_e32 v79, s6, v128
	v_fmac_f32_e32 v83, s7, v32
	v_fmac_f32_e32 v82, s8, v118
	v_fmac_f32_e32 v78, s9, v30
	v_readlane_b32 s6, v220, s18
	v_readlane_b32 s7, v219, s18
	v_readlane_b32 s8, v218, s37
	v_readlane_b32 s9, v217, s37
	v_fmac_f32_e32 v79, s6, v116
	v_fmac_f32_e32 v83, s7, v26
	v_fmac_f32_e32 v82, s8, v114
	v_fmac_f32_e32 v78, s9, v22
	v_readlane_b32 s6, v216, s37
	v_readlane_b32 s7, v215, s37
	v_readlane_b32 s8, v218, s18
	v_readlane_b32 s9, v217, s18
	v_fmac_f32_e32 v79, s6, v110
	v_fmac_f32_e32 v83, s7, v16
	v_fmac_f32_e32 v82, s8, v104
	v_fmac_f32_e32 v78, s9, v12
	v_readlane_b32 s6, v216, s18
	v_readlane_b32 s7, v215, s18
	v_readlane_b32 s8, v214, s37
	v_readlane_b32 s9, v213, s37
	v_fmac_f32_e32 v79, s6, v96
	v_fmac_f32_e32 v83, s7, v10
	v_fmac_f32_e32 v82, s8, v94
	v_fmac_f32_e32 v78, s9, v8
	v_readlane_b32 s6, v212, s37
	v_readlane_b32 s7, v211, s37
	v_readlane_b32 s8, v214, s18
	v_readlane_b32 s9, v213, s18
	v_fmac_f32_e32 v79, s6, v92
	v_fmac_f32_e32 v83, s7, v4
	v_fmac_f32_e32 v82, s8, v90
	v_fmac_f32_e32 v78, s9, v91
	v_readlane_b32 s6, v212, s18
	s_nop 1
	v_fmac_f32_e32 v79, s6, v88
	v_readlane_b32 s6, v211, s18
	s_nop 1
	v_fmac_f32_e32 v79, s6, v89
	v_pk_add_f32 v[78:79], v[82:83], v[78:79]
	v_mov_b32_e32 v83, v123
	v_mov_b32_e32 v82, v123
	v_pk_add_f32 v[78:79], v[78:79], v[78:79] op_sel:[0,1] op_sel_hi:[1,0]
	s_nop 0
	v_readlane_b32 s6, v200, s40
	v_readlane_b32 s7, v199, s40
	v_readlane_b32 s8, v202, s40
	v_readlane_b32 s9, v197, s19
	v_fmac_f32_e32 v75, s6, v78
	v_fmac_f32_e32 v83, s7, v160
	v_fmac_f32_e32 v82, s8, v84
	v_fmac_f32_e32 v74, s9, v154
	v_readlane_b32 s6, v200, s19
	v_readlane_b32 s7, v199, s19
	v_readlane_b32 s8, v202, s19
	v_readlane_b32 s9, v201, s40
	v_fmac_f32_e32 v75, s6, v184
	v_fmac_f32_e32 v83, s7, v162
	v_fmac_f32_e32 v82, s8, v180
	v_fmac_f32_e32 v74, s9, v164
	v_readlane_b32 s6, v204, s40
	v_readlane_b32 s7, v203, s40
	v_readlane_b32 s8, v206, s40
	v_readlane_b32 s9, v201, s19
	v_fmac_f32_e32 v75, s6, v172
	v_fmac_f32_e32 v83, s7, v156
	v_fmac_f32_e32 v82, s8, v176
	v_fmac_f32_e32 v74, s9, v150
	v_readlane_b32 s6, v204, s19
	v_readlane_b32 s7, v203, s19
	v_readlane_b32 s8, v206, s19
	v_readlane_b32 s9, v205, s40
	v_fmac_f32_e32 v75, s6, v178
	v_fmac_f32_e32 v83, s7, v148
	v_fmac_f32_e32 v82, s8, v174
	v_fmac_f32_e32 v74, s9, v146
	v_readlane_b32 s6, v208, s40
	v_readlane_b32 s7, v207, s40
	v_readlane_b32 s8, v209, s40
	v_readlane_b32 s9, v205, s19
	v_fmac_f32_e32 v75, s6, v170
	v_fmac_f32_e32 v83, s7, v144
	v_fmac_f32_e32 v82, s8, v166
	v_fmac_f32_e32 v74, s9, v142
	v_readlane_b32 s6, v208, s19
	v_readlane_b32 s7, v207, s19
	v_readlane_b32 s8, v209, s19
	v_readlane_b32 s9, v226, s40
	v_fmac_f32_e32 v75, s6, v158
	v_fmac_f32_e32 v83, s7, v140
	v_fmac_f32_e32 v82, s8, v152
	v_fmac_f32_e32 v74, s9, v138
	v_readlane_b32 s6, v225, s40
	v_readlane_b32 s7, v224, s40
	v_readlane_b32 s8, v223, s40
	v_readlane_b32 s9, v226, s19
	v_fmac_f32_e32 v75, s6, v80
	v_fmac_f32_e32 v83, s7, v136
	v_fmac_f32_e32 v82, s8, v76
	v_fmac_f32_e32 v74, s9, v134
	v_readlane_b32 s6, v225, s19
	v_readlane_b32 s7, v224, s19
	v_readlane_b32 s8, v223, s19
	v_readlane_b32 s9, v222, s40
	v_fmac_f32_e32 v75, s6, v72
	v_fmac_f32_e32 v83, s7, v132
	v_fmac_f32_e32 v82, s8, v68
	v_fmac_f32_e32 v74, s9, v130
	v_readlane_b32 s6, v221, s40
	v_readlane_b32 s7, v220, s40
	v_readlane_b32 s8, v219, s40
	v_readlane_b32 s9, v222, s19
	v_fmac_f32_e32 v75, s6, v64
	v_fmac_f32_e32 v83, s7, v128
	v_fmac_f32_e32 v82, s8, v32
	v_fmac_f32_e32 v74, s9, v118
	v_readlane_b32 s6, v221, s19
	v_readlane_b32 s7, v220, s19
	v_readlane_b32 s8, v219, s19
	v_readlane_b32 s9, v218, s40
	v_fmac_f32_e32 v75, s6, v30
	v_fmac_f32_e32 v83, s7, v116
	v_fmac_f32_e32 v82, s8, v26
	v_fmac_f32_e32 v74, s9, v114
	v_readlane_b32 s6, v217, s40
	v_readlane_b32 s7, v216, s40
	v_readlane_b32 s8, v215, s40
	v_readlane_b32 s9, v218, s19
	v_fmac_f32_e32 v75, s6, v22
	v_fmac_f32_e32 v83, s7, v110
	v_fmac_f32_e32 v82, s8, v16
	v_fmac_f32_e32 v74, s9, v104
	v_readlane_b32 s6, v217, s19
	v_readlane_b32 s7, v216, s19
	v_readlane_b32 s8, v215, s19
	v_readlane_b32 s9, v214, s40
	v_fmac_f32_e32 v75, s6, v12
	v_fmac_f32_e32 v83, s7, v96
	v_fmac_f32_e32 v82, s8, v10
	v_fmac_f32_e32 v74, s9, v94
	v_readlane_b32 s6, v213, s40
	v_readlane_b32 s7, v212, s40
	v_readlane_b32 s8, v211, s40
	v_readlane_b32 s9, v214, s19
	v_fmac_f32_e32 v75, s6, v8
	v_fmac_f32_e32 v83, s7, v92
	v_fmac_f32_e32 v82, s8, v4
	v_fmac_f32_e32 v74, s9, v90
	v_readlane_b32 s6, v213, s19
	s_nop 1
	v_fmac_f32_e32 v75, s6, v91
	v_readlane_b32 s6, v212, s19
	s_nop 1
	v_fmac_f32_e32 v75, s6, v88
	v_readlane_b32 s6, v211, s19
	s_nop 1
	v_fmac_f32_e32 v75, s6, v89
	v_pk_add_f32 v[74:75], v[82:83], v[74:75]
	s_nop 0
	v_pk_add_f32 v[168:169], v[74:75], v[74:75] op_sel:[0,1] op_sel_hi:[1,0]
	v_mov_b32_e32 v75, v123
	v_mov_b32_e32 v74, v123
	v_readlane_b32 s6, v197, s44
	v_readlane_b32 s7, v200, s44
	v_readlane_b32 s8, v199, s44
	v_readlane_b32 s9, v202, s44
	v_fmac_f32_e32 v71, s6, v168
	v_fmac_f32_e32 v75, s7, v78
	v_fmac_f32_e32 v74, s8, v160
	v_fmac_f32_e32 v70, s9, v84
	v_mov_b32_e32 v169, v78
	v_readlane_b32 s6, v197, s68
	v_readlane_b32 s7, v200, s68
	v_readlane_b32 s8, v199, s68
	v_readlane_b32 s9, v202, s68
	v_fmac_f32_e32 v71, s6, v154
	v_fmac_f32_e32 v75, s7, v184
	v_fmac_f32_e32 v74, s8, v162
	v_fmac_f32_e32 v70, s9, v180
	v_readlane_b32 s6, v201, s44
	v_readlane_b32 s7, v204, s44
	v_readlane_b32 s8, v203, s44
	v_readlane_b32 s9, v206, s44
	v_fmac_f32_e32 v71, s6, v164
	v_fmac_f32_e32 v75, s7, v172
	v_fmac_f32_e32 v74, s8, v156
	v_fmac_f32_e32 v70, s9, v176
	v_readlane_b32 s6, v201, s68
	v_readlane_b32 s7, v204, s68
	v_readlane_b32 s8, v203, s68
	v_readlane_b32 s9, v206, s68
	v_fmac_f32_e32 v71, s6, v150
	v_fmac_f32_e32 v75, s7, v178
	v_fmac_f32_e32 v74, s8, v148
	v_fmac_f32_e32 v70, s9, v174
	v_readlane_b32 s6, v205, s44
	v_readlane_b32 s7, v208, s44
	v_readlane_b32 s8, v207, s44
	v_readlane_b32 s9, v209, s44
	v_fmac_f32_e32 v71, s6, v146
	v_fmac_f32_e32 v75, s7, v170
	v_fmac_f32_e32 v74, s8, v144
	v_fmac_f32_e32 v70, s9, v166
	v_readlane_b32 s6, v205, s68
	v_readlane_b32 s7, v208, s68
	v_readlane_b32 s8, v207, s68
	v_readlane_b32 s9, v209, s68
	v_fmac_f32_e32 v71, s6, v142
	v_fmac_f32_e32 v75, s7, v158
	v_fmac_f32_e32 v74, s8, v140
	v_fmac_f32_e32 v70, s9, v152
	v_readlane_b32 s6, v226, s44
	v_readlane_b32 s7, v225, s44
	v_readlane_b32 s8, v224, s44
	v_readlane_b32 s9, v223, s44
	v_fmac_f32_e32 v71, s6, v138
	v_fmac_f32_e32 v75, s7, v80
	v_fmac_f32_e32 v74, s8, v136
	v_fmac_f32_e32 v70, s9, v76
	v_readlane_b32 s6, v226, s68
	v_readlane_b32 s7, v225, s68
	v_readlane_b32 s8, v224, s68
	v_readlane_b32 s9, v223, s68
	v_fmac_f32_e32 v71, s6, v134
	v_fmac_f32_e32 v75, s7, v72
	v_fmac_f32_e32 v74, s8, v132
	v_fmac_f32_e32 v70, s9, v68
	v_readlane_b32 s6, v222, s44
	v_readlane_b32 s7, v221, s44
	v_readlane_b32 s8, v220, s44
	v_readlane_b32 s9, v219, s44
	v_fmac_f32_e32 v71, s6, v130
	v_fmac_f32_e32 v75, s7, v64
	v_fmac_f32_e32 v74, s8, v128
	v_fmac_f32_e32 v70, s9, v32
	v_readlane_b32 s6, v222, s68
	v_readlane_b32 s7, v221, s68
	v_readlane_b32 s8, v220, s68
	v_readlane_b32 s9, v219, s68
	v_fmac_f32_e32 v71, s6, v118
	v_fmac_f32_e32 v75, s7, v30
	v_fmac_f32_e32 v74, s8, v116
	v_fmac_f32_e32 v70, s9, v26
	v_readlane_b32 s6, v218, s44
	v_readlane_b32 s7, v217, s44
	v_readlane_b32 s8, v216, s44
	v_readlane_b32 s9, v215, s44
	v_fmac_f32_e32 v71, s6, v114
	v_fmac_f32_e32 v75, s7, v22
	v_fmac_f32_e32 v74, s8, v110
	v_fmac_f32_e32 v70, s9, v16
	v_readlane_b32 s6, v218, s68
	v_readlane_b32 s7, v217, s68
	v_readlane_b32 s8, v216, s68
	v_readlane_b32 s9, v215, s68
	v_fmac_f32_e32 v71, s6, v104
	v_fmac_f32_e32 v75, s7, v12
	v_fmac_f32_e32 v74, s8, v96
	v_fmac_f32_e32 v70, s9, v10
	v_readlane_b32 s6, v214, s44
	v_readlane_b32 s7, v213, s44
	v_readlane_b32 s8, v212, s44
	v_readlane_b32 s9, v211, s44
	v_fmac_f32_e32 v71, s6, v94
	v_fmac_f32_e32 v75, s7, v8
	v_fmac_f32_e32 v74, s8, v92
	v_fmac_f32_e32 v70, s9, v4
	v_readlane_b32 s6, v214, s68
	v_readlane_b32 s7, v213, s68
	v_readlane_b32 s8, v212, s68
	v_readlane_b32 s9, v211, s68
	v_fmac_f32_e32 v71, s6, v90
	v_fmac_f32_e32 v75, s7, v91
	v_fmac_f32_e32 v74, s8, v88
	v_fmac_f32_e32 v70, s9, v89
	v_pk_add_f32 v[70:71], v[74:75], v[70:71]
	v_mov_b32_e32 v75, v123
	v_mov_b32_e32 v74, v123
	v_pk_add_f32 v[70:71], v[70:71], v[70:71] op_sel:[0,1] op_sel_hi:[1,0]
	s_nop 0
	v_readlane_b32 s6, v198, s3
	v_readlane_b32 s7, v197, s35
	v_readlane_b32 s8, v200, s35
	v_readlane_b32 s9, v199, s35
	v_fmac_f32_e32 v67, s6, v70
	v_fmac_f32_e32 v75, s7, v168
	v_fmac_f32_e32 v74, s8, v78
	v_fmac_f32_e32 v66, s9, v160
	v_readlane_b32 s6, v202, s35
	v_readlane_b32 s7, v197, s3
	v_readlane_b32 s8, v200, s3
	v_readlane_b32 s9, v199, s3
	v_fmac_f32_e32 v67, s6, v84
	v_fmac_f32_e32 v75, s7, v154
	v_fmac_f32_e32 v74, s8, v184
	v_fmac_f32_e32 v66, s9, v162
	v_readlane_b32 s6, v202, s3
	v_readlane_b32 s7, v201, s35
	v_readlane_b32 s8, v204, s35
	v_readlane_b32 s9, v203, s35
	v_fmac_f32_e32 v67, s6, v180
	v_fmac_f32_e32 v75, s7, v164
	v_fmac_f32_e32 v74, s8, v172
	v_fmac_f32_e32 v66, s9, v156
	v_readlane_b32 s6, v206, s35
	v_readlane_b32 s7, v201, s3
	v_readlane_b32 s8, v204, s3
	v_readlane_b32 s9, v203, s3
	v_fmac_f32_e32 v67, s6, v176
	v_fmac_f32_e32 v75, s7, v150
	v_fmac_f32_e32 v74, s8, v178
	v_fmac_f32_e32 v66, s9, v148
	v_readlane_b32 s6, v206, s3
	v_readlane_b32 s7, v205, s35
	v_readlane_b32 s8, v208, s35
	v_readlane_b32 s9, v207, s35
	v_fmac_f32_e32 v67, s6, v174
	v_fmac_f32_e32 v75, s7, v146
	v_fmac_f32_e32 v74, s8, v170
	v_fmac_f32_e32 v66, s9, v144
	v_readlane_b32 s6, v209, s35
	v_readlane_b32 s7, v205, s3
	v_readlane_b32 s8, v208, s3
	v_readlane_b32 s9, v207, s3
	v_fmac_f32_e32 v67, s6, v166
	v_fmac_f32_e32 v75, s7, v142
	v_fmac_f32_e32 v74, s8, v158
	v_fmac_f32_e32 v66, s9, v140
	v_readlane_b32 s6, v209, s3
	v_readlane_b32 s7, v226, s35
	v_readlane_b32 s8, v225, s35
	v_readlane_b32 s9, v224, s35
	v_fmac_f32_e32 v67, s6, v152
	v_fmac_f32_e32 v75, s7, v138
	v_fmac_f32_e32 v74, s8, v80
	v_fmac_f32_e32 v66, s9, v136
	v_readlane_b32 s6, v223, s35
	v_readlane_b32 s7, v226, s3
	v_readlane_b32 s8, v225, s3
	v_readlane_b32 s9, v224, s3
	v_fmac_f32_e32 v67, s6, v76
	v_fmac_f32_e32 v75, s7, v134
	v_fmac_f32_e32 v74, s8, v72
	v_fmac_f32_e32 v66, s9, v132
	v_readlane_b32 s6, v223, s3
	v_readlane_b32 s7, v222, s35
	v_readlane_b32 s8, v221, s35
	v_readlane_b32 s9, v220, s35
	v_fmac_f32_e32 v67, s6, v68
	v_fmac_f32_e32 v75, s7, v130
	v_fmac_f32_e32 v74, s8, v64
	v_fmac_f32_e32 v66, s9, v128
	v_readlane_b32 s6, v219, s35
	v_readlane_b32 s7, v222, s3
	v_readlane_b32 s8, v221, s3
	v_readlane_b32 s9, v220, s3
	v_fmac_f32_e32 v67, s6, v32
	v_fmac_f32_e32 v75, s7, v118
	v_fmac_f32_e32 v74, s8, v30
	v_fmac_f32_e32 v66, s9, v116
	v_readlane_b32 s6, v219, s3
	v_readlane_b32 s7, v218, s35
	v_readlane_b32 s8, v217, s35
	v_readlane_b32 s9, v216, s35
	v_fmac_f32_e32 v67, s6, v26
	v_fmac_f32_e32 v75, s7, v114
	v_fmac_f32_e32 v74, s8, v22
	v_fmac_f32_e32 v66, s9, v110
	v_readlane_b32 s6, v215, s35
	v_readlane_b32 s7, v218, s3
	v_readlane_b32 s8, v217, s3
	v_readlane_b32 s9, v216, s3
	v_fmac_f32_e32 v67, s6, v16
	v_fmac_f32_e32 v75, s7, v104
	v_fmac_f32_e32 v74, s8, v12
	v_fmac_f32_e32 v66, s9, v96
	v_readlane_b32 s6, v215, s3
	v_readlane_b32 s7, v214, s35
	v_readlane_b32 s8, v213, s35
	v_readlane_b32 s9, v212, s35
	v_fmac_f32_e32 v67, s6, v10
	v_fmac_f32_e32 v75, s7, v94
	v_fmac_f32_e32 v74, s8, v8
	v_fmac_f32_e32 v66, s9, v92
	v_readlane_b32 s6, v211, s35
	v_readlane_b32 s7, v214, s3
	v_readlane_b32 s8, v213, s3
	v_readlane_b32 s9, v212, s3
	v_fmac_f32_e32 v67, s6, v4
	v_fmac_f32_e32 v75, s7, v90
	v_fmac_f32_e32 v74, s8, v91
	v_fmac_f32_e32 v66, s9, v88
	v_readlane_b32 s6, v211, s3
	s_nop 1
	v_fmac_f32_e32 v67, s6, v89
	v_pk_add_f32 v[66:67], v[74:75], v[66:67]
	s_nop 0
	v_pk_add_f32 v[182:183], v[66:67], v[66:67] op_sel:[0,1] op_sel_hi:[1,0]
	v_mov_b32_e32 v67, v123
	v_mov_b32_e32 v66, v123
	v_readlane_b32 s6, v195, s16
	v_readlane_b32 s7, v198, s16
	v_readlane_b32 s8, v197, s30
	v_readlane_b32 s9, v200, s30
	v_fmac_f32_e32 v63, s6, v182
	v_fmac_f32_e32 v67, s7, v70
	v_fmac_f32_e32 v66, s8, v168
	v_fmac_f32_e32 v62, s9, v78
	v_mov_b32_e32 v183, v70
	v_readlane_b32 s6, v199, s30
	v_readlane_b32 s7, v202, s30
	v_readlane_b32 s8, v197, s16
	v_readlane_b32 s9, v200, s16
	v_fmac_f32_e32 v63, s6, v160
	v_fmac_f32_e32 v67, s7, v84
	v_fmac_f32_e32 v66, s8, v154
	v_fmac_f32_e32 v62, s9, v184
	v_readlane_b32 s6, v199, s16
	v_readlane_b32 s7, v202, s16
	v_readlane_b32 s8, v201, s30
	v_readlane_b32 s9, v204, s30
	v_fmac_f32_e32 v63, s6, v162
	v_fmac_f32_e32 v67, s7, v180
	v_fmac_f32_e32 v66, s8, v164
	v_fmac_f32_e32 v62, s9, v172
	v_readlane_b32 s6, v203, s30
	v_readlane_b32 s7, v206, s30
	v_readlane_b32 s8, v201, s16
	v_readlane_b32 s9, v204, s16
	v_fmac_f32_e32 v63, s6, v156
	v_fmac_f32_e32 v67, s7, v176
	v_fmac_f32_e32 v66, s8, v150
	v_fmac_f32_e32 v62, s9, v178
	v_readlane_b32 s6, v203, s16
	v_readlane_b32 s7, v206, s16
	v_readlane_b32 s8, v205, s30
	v_readlane_b32 s9, v208, s30
	v_fmac_f32_e32 v63, s6, v148
	v_fmac_f32_e32 v67, s7, v174
	v_fmac_f32_e32 v66, s8, v146
	v_fmac_f32_e32 v62, s9, v170
	v_readlane_b32 s6, v207, s30
	v_readlane_b32 s7, v209, s30
	v_readlane_b32 s8, v205, s16
	v_readlane_b32 s9, v208, s16
	v_fmac_f32_e32 v63, s6, v144
	v_fmac_f32_e32 v67, s7, v166
	v_fmac_f32_e32 v66, s8, v142
	v_fmac_f32_e32 v62, s9, v158
	v_readlane_b32 s6, v207, s16
	v_readlane_b32 s7, v209, s16
	v_readlane_b32 s8, v226, s30
	v_readlane_b32 s9, v225, s30
	v_fmac_f32_e32 v63, s6, v140
	v_fmac_f32_e32 v67, s7, v152
	v_fmac_f32_e32 v66, s8, v138
	v_fmac_f32_e32 v62, s9, v80
	v_readlane_b32 s6, v224, s30
	v_readlane_b32 s7, v223, s30
	v_readlane_b32 s8, v226, s16
	v_readlane_b32 s9, v225, s16
	v_fmac_f32_e32 v63, s6, v136
	v_fmac_f32_e32 v67, s7, v76
	v_fmac_f32_e32 v66, s8, v134
	v_fmac_f32_e32 v62, s9, v72
	v_readlane_b32 s6, v224, s16
	v_readlane_b32 s7, v223, s16
	v_readlane_b32 s8, v222, s30
	v_readlane_b32 s9, v221, s30
	v_fmac_f32_e32 v63, s6, v132
	v_fmac_f32_e32 v67, s7, v68
	v_fmac_f32_e32 v66, s8, v130
	v_fmac_f32_e32 v62, s9, v64
	v_readlane_b32 s6, v220, s30
	v_readlane_b32 s7, v219, s30
	v_readlane_b32 s8, v222, s16
	v_readlane_b32 s9, v221, s16
	v_fmac_f32_e32 v63, s6, v128
	v_fmac_f32_e32 v67, s7, v32
	v_fmac_f32_e32 v66, s8, v118
	v_fmac_f32_e32 v62, s9, v30
	v_readlane_b32 s6, v220, s16
	v_readlane_b32 s7, v219, s16
	v_readlane_b32 s8, v218, s30
	v_readlane_b32 s9, v217, s30
	v_fmac_f32_e32 v63, s6, v116
	v_fmac_f32_e32 v67, s7, v26
	v_fmac_f32_e32 v66, s8, v114
	v_fmac_f32_e32 v62, s9, v22
	v_readlane_b32 s6, v216, s30
	v_readlane_b32 s7, v215, s30
	v_readlane_b32 s8, v218, s16
	v_readlane_b32 s9, v217, s16
	v_fmac_f32_e32 v63, s6, v110
	v_fmac_f32_e32 v67, s7, v16
	v_fmac_f32_e32 v66, s8, v104
	v_fmac_f32_e32 v62, s9, v12
	v_readlane_b32 s6, v216, s16
	v_readlane_b32 s7, v215, s16
	v_readlane_b32 s8, v214, s30
	v_readlane_b32 s9, v213, s30
	v_fmac_f32_e32 v63, s6, v96
	v_fmac_f32_e32 v67, s7, v10
	v_fmac_f32_e32 v66, s8, v94
	v_fmac_f32_e32 v62, s9, v8
	v_readlane_b32 s6, v212, s30
	v_readlane_b32 s7, v211, s30
	v_readlane_b32 s8, v214, s16
	v_readlane_b32 s9, v213, s16
	v_fmac_f32_e32 v63, s6, v92
	v_fmac_f32_e32 v67, s7, v4
	v_fmac_f32_e32 v66, s8, v90
	v_fmac_f32_e32 v62, s9, v91
	v_readlane_b32 s6, v212, s16
	s_nop 1
	v_fmac_f32_e32 v63, s6, v88
	v_readlane_b32 s6, v211, s16
	s_nop 1
	v_fmac_f32_e32 v63, s6, v89
	v_pk_add_f32 v[62:63], v[66:67], v[62:63]
	v_mov_b32_e32 v67, v123
	v_mov_b32_e32 v66, v123
	v_pk_add_f32 v[62:63], v[62:63], v[62:63] op_sel:[0,1] op_sel_hi:[1,0]
	s_nop 0
	v_readlane_b32 s6, v196, s17
	v_readlane_b32 s7, v195, s17
	v_readlane_b32 s8, v198, s17
	v_readlane_b32 s9, v197, s36
	v_fmac_f32_e32 v29, s6, v62
	v_fmac_f32_e32 v67, s7, v182
	v_fmac_f32_e32 v66, s8, v70
	v_fmac_f32_e32 v28, s9, v168
	v_readlane_b32 s6, v200, s36
	v_readlane_b32 s7, v199, s36
	v_readlane_b32 s8, v202, s36
	v_readlane_b32 s9, v197, s17
	v_fmac_f32_e32 v29, s6, v78
	v_fmac_f32_e32 v67, s7, v160
	v_fmac_f32_e32 v66, s8, v84
	v_fmac_f32_e32 v28, s9, v154
	v_readlane_b32 s6, v200, s17
	v_readlane_b32 s7, v199, s17
	v_readlane_b32 s8, v202, s17
	v_readlane_b32 s9, v201, s36
	v_fmac_f32_e32 v29, s6, v184
	v_fmac_f32_e32 v67, s7, v162
	v_fmac_f32_e32 v66, s8, v180
	v_fmac_f32_e32 v28, s9, v164
	v_readlane_b32 s6, v204, s36
	v_readlane_b32 s7, v203, s36
	v_readlane_b32 s8, v206, s36
	v_readlane_b32 s9, v201, s17
	v_fmac_f32_e32 v29, s6, v172
	v_fmac_f32_e32 v67, s7, v156
	v_fmac_f32_e32 v66, s8, v176
	v_fmac_f32_e32 v28, s9, v150
	v_readlane_b32 s6, v204, s17
	v_readlane_b32 s7, v203, s17
	v_readlane_b32 s8, v206, s17
	v_readlane_b32 s9, v205, s36
	v_fmac_f32_e32 v29, s6, v178
	v_fmac_f32_e32 v67, s7, v148
	v_fmac_f32_e32 v66, s8, v174
	v_fmac_f32_e32 v28, s9, v146
	v_readlane_b32 s6, v208, s36
	v_readlane_b32 s7, v207, s36
	v_readlane_b32 s8, v209, s36
	v_readlane_b32 s9, v205, s17
	v_fmac_f32_e32 v29, s6, v170
	v_fmac_f32_e32 v67, s7, v144
	v_fmac_f32_e32 v66, s8, v166
	v_fmac_f32_e32 v28, s9, v142
	v_readlane_b32 s6, v208, s17
	v_readlane_b32 s7, v207, s17
	v_readlane_b32 s8, v209, s17
	v_readlane_b32 s9, v226, s36
	v_fmac_f32_e32 v29, s6, v158
	v_fmac_f32_e32 v67, s7, v140
	v_fmac_f32_e32 v66, s8, v152
	v_fmac_f32_e32 v28, s9, v138
	v_readlane_b32 s6, v225, s36
	v_readlane_b32 s7, v224, s36
	v_readlane_b32 s8, v223, s36
	v_readlane_b32 s9, v226, s17
	v_fmac_f32_e32 v29, s6, v80
	v_fmac_f32_e32 v67, s7, v136
	v_fmac_f32_e32 v66, s8, v76
	v_fmac_f32_e32 v28, s9, v134
	v_readlane_b32 s6, v225, s17
	v_readlane_b32 s7, v224, s17
	v_readlane_b32 s8, v223, s17
	v_readlane_b32 s9, v222, s36
	v_fmac_f32_e32 v29, s6, v72
	v_fmac_f32_e32 v67, s7, v132
	v_fmac_f32_e32 v66, s8, v68
	v_fmac_f32_e32 v28, s9, v130
	v_readlane_b32 s6, v221, s36
	v_readlane_b32 s7, v220, s36
	v_readlane_b32 s8, v219, s36
	v_readlane_b32 s9, v222, s17
	v_fmac_f32_e32 v29, s6, v64
	v_fmac_f32_e32 v67, s7, v128
	v_fmac_f32_e32 v66, s8, v32
	v_fmac_f32_e32 v28, s9, v118
	v_readlane_b32 s6, v221, s17
	v_readlane_b32 s7, v220, s17
	v_readlane_b32 s8, v219, s17
	v_readlane_b32 s9, v218, s36
	v_fmac_f32_e32 v29, s6, v30
	v_fmac_f32_e32 v67, s7, v116
	v_fmac_f32_e32 v66, s8, v26
	v_fmac_f32_e32 v28, s9, v114
	v_readlane_b32 s6, v217, s36
	v_readlane_b32 s7, v216, s36
	v_readlane_b32 s8, v215, s36
	v_readlane_b32 s9, v218, s17
	v_fmac_f32_e32 v29, s6, v22
	v_fmac_f32_e32 v67, s7, v110
	v_fmac_f32_e32 v66, s8, v16
	v_fmac_f32_e32 v28, s9, v104
	v_readlane_b32 s6, v217, s17
	v_readlane_b32 s7, v216, s17
	v_readlane_b32 s8, v215, s17
	v_readlane_b32 s9, v214, s36
	v_fmac_f32_e32 v29, s6, v12
	v_fmac_f32_e32 v67, s7, v96
	v_fmac_f32_e32 v66, s8, v10
	v_fmac_f32_e32 v28, s9, v94
	v_readlane_b32 s6, v213, s36
	v_readlane_b32 s7, v212, s36
	v_readlane_b32 s8, v211, s36
	v_readlane_b32 s9, v214, s17
	v_fmac_f32_e32 v29, s6, v8
	v_fmac_f32_e32 v67, s7, v92
	v_fmac_f32_e32 v66, s8, v4
	v_fmac_f32_e32 v28, s9, v90
	v_readlane_b32 s6, v213, s17
	s_nop 1
	v_fmac_f32_e32 v29, s6, v91
	v_readlane_b32 s6, v212, s17
	s_nop 1
	v_fmac_f32_e32 v29, s6, v88
	v_readlane_b32 s6, v211, s17
	s_nop 1
	v_fmac_f32_e32 v29, s6, v89
	v_pk_add_f32 v[28:29], v[66:67], v[28:29]
	s_nop 0
	v_pk_add_f32 v[186:187], v[28:29], v[28:29] op_sel:[0,1] op_sel_hi:[1,0]
	v_mov_b32_e32 v29, v123
	v_mov_b32_e32 v28, v123
	v_readlane_b32 s6, v194, s69
	v_readlane_b32 s7, v196, s69
	v_readlane_b32 s8, v195, s69
	v_readlane_b32 s9, v198, s69
	v_fmac_f32_e32 v25, s6, v186
	v_fmac_f32_e32 v29, s7, v62
	v_fmac_f32_e32 v28, s8, v182
	v_fmac_f32_e32 v24, s9, v70
	v_mov_b32_e32 v187, v62
	v_readlane_b32 s6, v197, s12
	v_readlane_b32 s7, v200, s12
	v_readlane_b32 s8, v199, s12
	v_readlane_b32 s9, v202, s12
	v_fmac_f32_e32 v25, s6, v168
	v_fmac_f32_e32 v29, s7, v78
	v_fmac_f32_e32 v28, s8, v160
	v_fmac_f32_e32 v24, s9, v84
	v_readlane_b32 s6, v197, s69
	v_readlane_b32 s7, v200, s69
	v_readlane_b32 s8, v199, s69
	v_readlane_b32 s9, v202, s69
	v_fmac_f32_e32 v25, s6, v154
	v_fmac_f32_e32 v29, s7, v184
	v_fmac_f32_e32 v28, s8, v162
	v_fmac_f32_e32 v24, s9, v180
	v_readlane_b32 s6, v201, s12
	v_readlane_b32 s7, v204, s12
	v_readlane_b32 s8, v203, s12
	v_readlane_b32 s9, v206, s12
	v_fmac_f32_e32 v25, s6, v164
	v_fmac_f32_e32 v29, s7, v172
	v_fmac_f32_e32 v28, s8, v156
	v_fmac_f32_e32 v24, s9, v176
	v_readlane_b32 s6, v201, s69
	v_readlane_b32 s7, v204, s69
	v_readlane_b32 s8, v203, s69
	v_readlane_b32 s9, v206, s69
	v_fmac_f32_e32 v25, s6, v150
	v_fmac_f32_e32 v29, s7, v178
	v_fmac_f32_e32 v28, s8, v148
	v_fmac_f32_e32 v24, s9, v174
	v_readlane_b32 s6, v205, s12
	v_readlane_b32 s7, v208, s12
	v_readlane_b32 s8, v207, s12
	v_readlane_b32 s9, v209, s12
	v_fmac_f32_e32 v25, s6, v146
	v_fmac_f32_e32 v29, s7, v170
	v_fmac_f32_e32 v28, s8, v144
	v_fmac_f32_e32 v24, s9, v166
	v_readlane_b32 s6, v205, s69
	v_readlane_b32 s7, v208, s69
	v_readlane_b32 s8, v207, s69
	v_readlane_b32 s9, v209, s69
	v_fmac_f32_e32 v25, s6, v142
	v_fmac_f32_e32 v29, s7, v158
	v_fmac_f32_e32 v28, s8, v140
	v_fmac_f32_e32 v24, s9, v152
	v_readlane_b32 s6, v226, s12
	v_readlane_b32 s7, v225, s12
	v_readlane_b32 s8, v224, s12
	v_readlane_b32 s9, v223, s12
	v_fmac_f32_e32 v25, s6, v138
	v_fmac_f32_e32 v29, s7, v80
	v_fmac_f32_e32 v28, s8, v136
	v_fmac_f32_e32 v24, s9, v76
	v_readlane_b32 s6, v226, s69
	v_readlane_b32 s7, v225, s69
	v_readlane_b32 s8, v224, s69
	v_readlane_b32 s9, v223, s69
	v_fmac_f32_e32 v25, s6, v134
	v_fmac_f32_e32 v29, s7, v72
	v_fmac_f32_e32 v28, s8, v132
	v_fmac_f32_e32 v24, s9, v68
	v_readlane_b32 s6, v222, s12
	v_readlane_b32 s7, v221, s12
	v_readlane_b32 s8, v220, s12
	v_readlane_b32 s9, v219, s12
	v_fmac_f32_e32 v25, s6, v130
	v_fmac_f32_e32 v29, s7, v64
	v_fmac_f32_e32 v28, s8, v128
	v_fmac_f32_e32 v24, s9, v32
	v_readlane_b32 s6, v222, s69
	v_readlane_b32 s7, v221, s69
	v_readlane_b32 s8, v220, s69
	v_readlane_b32 s9, v219, s69
	v_fmac_f32_e32 v25, s6, v118
	v_fmac_f32_e32 v29, s7, v30
	v_fmac_f32_e32 v28, s8, v116
	v_fmac_f32_e32 v24, s9, v26
	v_readlane_b32 s6, v218, s12
	v_readlane_b32 s7, v217, s12
	v_readlane_b32 s8, v216, s12
	v_readlane_b32 s9, v215, s12
	v_fmac_f32_e32 v25, s6, v114
	v_fmac_f32_e32 v29, s7, v22
	v_fmac_f32_e32 v28, s8, v110
	v_fmac_f32_e32 v24, s9, v16
	v_readlane_b32 s6, v218, s69
	v_readlane_b32 s7, v217, s69
	v_readlane_b32 s8, v216, s69
	v_readlane_b32 s9, v215, s69
	v_fmac_f32_e32 v25, s6, v104
	v_fmac_f32_e32 v29, s7, v12
	v_fmac_f32_e32 v28, s8, v96
	v_fmac_f32_e32 v24, s9, v10
	v_readlane_b32 s6, v214, s12
	v_readlane_b32 s7, v213, s12
	v_readlane_b32 s8, v212, s12
	v_readlane_b32 s9, v211, s12
	v_fmac_f32_e32 v25, s6, v94
	v_fmac_f32_e32 v29, s7, v8
	v_fmac_f32_e32 v28, s8, v92
	v_fmac_f32_e32 v24, s9, v4
	v_readlane_b32 s6, v214, s69
	v_readlane_b32 s7, v213, s69
	v_readlane_b32 s8, v212, s69
	v_readlane_b32 s9, v211, s69
	v_fmac_f32_e32 v25, s6, v90
	v_fmac_f32_e32 v29, s7, v91
	v_fmac_f32_e32 v28, s8, v88
	v_fmac_f32_e32 v24, s9, v89
	v_pk_add_f32 v[24:25], v[28:29], v[24:25]
	v_mov_b32_e32 v29, v123
	v_mov_b32_e32 v28, v123
	v_pk_add_f32 v[24:25], v[24:25], v[24:25] op_sel:[0,1] op_sel_hi:[1,0]
	s_nop 0
	v_readlane_b32 s6, v198, s15
	v_readlane_b32 s7, v194, s23
	v_readlane_b32 s8, v196, s23
	v_readlane_b32 s9, v195, s23
	v_fmac_f32_e32 v15, s6, v24
	v_fmac_f32_e32 v29, s7, v186
	v_fmac_f32_e32 v28, s8, v62
	v_fmac_f32_e32 v14, s9, v182
	v_readlane_b32 s6, v198, s23
	v_readlane_b32 s7, v197, s15
	v_readlane_b32 s8, v200, s15
	v_readlane_b32 s9, v199, s15
	v_fmac_f32_e32 v15, s6, v70
	v_fmac_f32_e32 v29, s7, v168
	v_fmac_f32_e32 v28, s8, v78
	v_fmac_f32_e32 v14, s9, v160
	v_readlane_b32 s6, v202, s15
	v_readlane_b32 s7, v197, s23
	v_readlane_b32 s8, v200, s23
	v_readlane_b32 s9, v199, s23
	v_fmac_f32_e32 v15, s6, v84
	v_fmac_f32_e32 v29, s7, v154
	v_fmac_f32_e32 v28, s8, v184
	v_fmac_f32_e32 v14, s9, v162
	v_readlane_b32 s6, v202, s23
	v_readlane_b32 s7, v201, s15
	v_readlane_b32 s8, v204, s15
	v_readlane_b32 s9, v203, s15
	v_fmac_f32_e32 v15, s6, v180
	v_fmac_f32_e32 v29, s7, v164
	v_fmac_f32_e32 v28, s8, v172
	v_fmac_f32_e32 v14, s9, v156
	v_readlane_b32 s6, v206, s15
	v_readlane_b32 s7, v201, s23
	v_readlane_b32 s8, v204, s23
	v_readlane_b32 s9, v203, s23
	v_fmac_f32_e32 v15, s6, v176
	v_fmac_f32_e32 v29, s7, v150
	v_fmac_f32_e32 v28, s8, v178
	v_fmac_f32_e32 v14, s9, v148
	v_readlane_b32 s6, v206, s23
	v_readlane_b32 s7, v205, s15
	v_readlane_b32 s8, v208, s15
	v_readlane_b32 s9, v207, s15
	v_fmac_f32_e32 v15, s6, v174
	v_fmac_f32_e32 v29, s7, v146
	v_fmac_f32_e32 v28, s8, v170
	v_fmac_f32_e32 v14, s9, v144
	v_readlane_b32 s6, v209, s15
	v_readlane_b32 s7, v205, s23
	v_readlane_b32 s8, v208, s23
	v_readlane_b32 s9, v207, s23
	v_fmac_f32_e32 v15, s6, v166
	v_fmac_f32_e32 v29, s7, v142
	v_fmac_f32_e32 v28, s8, v158
	v_fmac_f32_e32 v14, s9, v140
	v_readlane_b32 s6, v209, s23
	v_readlane_b32 s7, v226, s15
	v_readlane_b32 s8, v225, s15
	v_readlane_b32 s9, v224, s15
	v_fmac_f32_e32 v15, s6, v152
	v_fmac_f32_e32 v29, s7, v138
	v_fmac_f32_e32 v28, s8, v80
	v_fmac_f32_e32 v14, s9, v136
	v_readlane_b32 s6, v223, s15
	v_readlane_b32 s7, v226, s23
	v_readlane_b32 s8, v225, s23
	v_readlane_b32 s9, v224, s23
	v_fmac_f32_e32 v15, s6, v76
	v_fmac_f32_e32 v29, s7, v134
	v_fmac_f32_e32 v28, s8, v72
	v_fmac_f32_e32 v14, s9, v132
	v_readlane_b32 s6, v223, s23
	v_readlane_b32 s7, v222, s15
	v_readlane_b32 s8, v221, s15
	v_readlane_b32 s9, v220, s15
	v_fmac_f32_e32 v15, s6, v68
	v_fmac_f32_e32 v29, s7, v130
	v_fmac_f32_e32 v28, s8, v64
	v_fmac_f32_e32 v14, s9, v128
	v_readlane_b32 s6, v219, s15
	v_readlane_b32 s7, v222, s23
	v_readlane_b32 s8, v221, s23
	v_readlane_b32 s9, v220, s23
	v_fmac_f32_e32 v15, s6, v32
	v_fmac_f32_e32 v29, s7, v118
	v_fmac_f32_e32 v28, s8, v30
	v_fmac_f32_e32 v14, s9, v116
	v_readlane_b32 s6, v219, s23
	v_readlane_b32 s7, v218, s15
	v_readlane_b32 s8, v217, s15
	v_readlane_b32 s9, v216, s15
	v_fmac_f32_e32 v15, s6, v26
	v_fmac_f32_e32 v29, s7, v114
	v_fmac_f32_e32 v28, s8, v22
	v_fmac_f32_e32 v14, s9, v110
	v_readlane_b32 s6, v215, s15
	v_readlane_b32 s7, v218, s23
	v_readlane_b32 s8, v217, s23
	v_readlane_b32 s9, v216, s23
	v_fmac_f32_e32 v15, s6, v16
	v_fmac_f32_e32 v29, s7, v104
	v_fmac_f32_e32 v28, s8, v12
	v_fmac_f32_e32 v14, s9, v96
	v_readlane_b32 s6, v215, s23
	v_readlane_b32 s7, v214, s15
	v_readlane_b32 s8, v213, s15
	v_readlane_b32 s9, v212, s15
	v_fmac_f32_e32 v15, s6, v10
	v_fmac_f32_e32 v29, s7, v94
	v_fmac_f32_e32 v28, s8, v8
	v_fmac_f32_e32 v14, s9, v92
	v_readlane_b32 s6, v211, s15
	v_readlane_b32 s7, v214, s23
	v_readlane_b32 s8, v213, s23
	v_readlane_b32 s9, v212, s23
	v_fmac_f32_e32 v15, s6, v4
	v_fmac_f32_e32 v29, s7, v90
	v_fmac_f32_e32 v28, s8, v91
	v_fmac_f32_e32 v14, s9, v88
	v_readlane_b32 s6, v211, s23
	s_nop 1
	v_fmac_f32_e32 v15, s6, v89
	v_pk_add_f32 v[14:15], v[28:29], v[14:15]
	s_nop 0
	v_pk_add_f32 v[188:189], v[14:15], v[14:15] op_sel:[0,1] op_sel_hi:[1,0]
	v_mov_b32_e32 v15, v123
	v_mov_b32_e32 v14, v123
	v_readlane_b32 s6, v195, s26
	v_readlane_b32 s7, v198, s26
	v_readlane_b32 s8, v194, s10
	v_readlane_b32 s9, v196, s10
	v_fmac_f32_e32 v7, s6, v188
	v_fmac_f32_e32 v15, s7, v24
	v_fmac_f32_e32 v14, s8, v186
	v_fmac_f32_e32 v6, s9, v62
	v_mov_b32_e32 v189, v24
	v_readlane_b32 s6, v195, s10
	v_readlane_b32 s7, v198, s10
	v_readlane_b32 s8, v197, s26
	v_readlane_b32 s9, v200, s26
	v_fmac_f32_e32 v7, s6, v182
	v_fmac_f32_e32 v15, s7, v70
	v_fmac_f32_e32 v14, s8, v168
	v_fmac_f32_e32 v6, s9, v78
	v_readlane_b32 s6, v199, s26
	v_readlane_b32 s7, v202, s26
	v_readlane_b32 s8, v197, s10
	v_readlane_b32 s9, v200, s10
	v_fmac_f32_e32 v7, s6, v160
	v_fmac_f32_e32 v15, s7, v84
	v_fmac_f32_e32 v14, s8, v154
	v_fmac_f32_e32 v6, s9, v184
	v_readlane_b32 s6, v199, s10
	v_readlane_b32 s7, v202, s10
	v_readlane_b32 s8, v201, s26
	v_readlane_b32 s9, v204, s26
	v_fmac_f32_e32 v7, s6, v162
	v_fmac_f32_e32 v15, s7, v180
	v_fmac_f32_e32 v14, s8, v164
	v_fmac_f32_e32 v6, s9, v172
	v_readlane_b32 s6, v203, s26
	v_readlane_b32 s7, v206, s26
	v_readlane_b32 s8, v201, s10
	v_readlane_b32 s9, v204, s10
	v_fmac_f32_e32 v7, s6, v156
	v_fmac_f32_e32 v15, s7, v176
	v_fmac_f32_e32 v14, s8, v150
	v_fmac_f32_e32 v6, s9, v178
	v_readlane_b32 s6, v203, s10
	v_readlane_b32 s7, v206, s10
	v_readlane_b32 s8, v205, s26
	v_readlane_b32 s9, v208, s26
	v_fmac_f32_e32 v7, s6, v148
	v_fmac_f32_e32 v15, s7, v174
	v_fmac_f32_e32 v14, s8, v146
	v_fmac_f32_e32 v6, s9, v170
	v_readlane_b32 s6, v207, s26
	v_readlane_b32 s7, v209, s26
	v_readlane_b32 s8, v205, s10
	v_readlane_b32 s9, v208, s10
	v_fmac_f32_e32 v7, s6, v144
	v_fmac_f32_e32 v15, s7, v166
	v_fmac_f32_e32 v14, s8, v142
	v_fmac_f32_e32 v6, s9, v158
	v_readlane_b32 s6, v207, s10
	v_readlane_b32 s7, v209, s10
	v_readlane_b32 s8, v226, s26
	v_readlane_b32 s9, v225, s26
	v_fmac_f32_e32 v7, s6, v140
	v_fmac_f32_e32 v15, s7, v152
	v_fmac_f32_e32 v14, s8, v138
	v_fmac_f32_e32 v6, s9, v80
	v_readlane_b32 s6, v224, s26
	v_readlane_b32 s7, v223, s26
	v_readlane_b32 s8, v226, s10
	v_readlane_b32 s9, v225, s10
	v_fmac_f32_e32 v7, s6, v136
	v_fmac_f32_e32 v15, s7, v76
	v_fmac_f32_e32 v14, s8, v134
	v_fmac_f32_e32 v6, s9, v72
	v_readlane_b32 s6, v224, s10
	v_readlane_b32 s7, v223, s10
	v_readlane_b32 s8, v222, s26
	v_readlane_b32 s9, v221, s26
	v_fmac_f32_e32 v7, s6, v132
	v_fmac_f32_e32 v15, s7, v68
	v_fmac_f32_e32 v14, s8, v130
	v_fmac_f32_e32 v6, s9, v64
	v_readlane_b32 s6, v220, s26
	v_readlane_b32 s7, v219, s26
	v_readlane_b32 s8, v222, s10
	v_readlane_b32 s9, v221, s10
	v_fmac_f32_e32 v7, s6, v128
	v_fmac_f32_e32 v15, s7, v32
	v_fmac_f32_e32 v14, s8, v118
	v_fmac_f32_e32 v6, s9, v30
	v_readlane_b32 s6, v220, s10
	v_readlane_b32 s7, v219, s10
	v_readlane_b32 s8, v218, s26
	v_readlane_b32 s9, v217, s26
	v_fmac_f32_e32 v7, s6, v116
	v_fmac_f32_e32 v15, s7, v26
	v_fmac_f32_e32 v14, s8, v114
	v_fmac_f32_e32 v6, s9, v22
	v_readlane_b32 s6, v216, s26
	v_readlane_b32 s7, v215, s26
	v_readlane_b32 s8, v218, s10
	v_readlane_b32 s9, v217, s10
	v_fmac_f32_e32 v7, s6, v110
	v_fmac_f32_e32 v15, s7, v16
	v_fmac_f32_e32 v14, s8, v104
	v_fmac_f32_e32 v6, s9, v12
	v_readlane_b32 s6, v216, s10
	v_readlane_b32 s7, v215, s10
	v_readlane_b32 s8, v214, s26
	v_readlane_b32 s9, v213, s26
	v_fmac_f32_e32 v7, s6, v96
	v_fmac_f32_e32 v15, s7, v10
	v_fmac_f32_e32 v14, s8, v94
	v_fmac_f32_e32 v6, s9, v8
	v_readlane_b32 s6, v212, s26
	v_readlane_b32 s7, v211, s26
	v_readlane_b32 s8, v214, s10
	v_readlane_b32 s9, v213, s10
	v_fmac_f32_e32 v7, s6, v92
	v_fmac_f32_e32 v15, s7, v4
	v_fmac_f32_e32 v14, s8, v90
	v_fmac_f32_e32 v6, s9, v91
	v_readlane_b32 s6, v212, s10
	s_nop 1
	v_fmac_f32_e32 v7, s6, v88
	v_readlane_b32 s6, v211, s10
	s_nop 1
	v_fmac_f32_e32 v7, s6, v89
	v_pk_add_f32 v[6:7], v[14:15], v[6:7]
	v_mov_b32_e32 v15, v123
	v_mov_b32_e32 v14, v123
	v_pk_add_f32 v[6:7], v[6:7], v[6:7] op_sel:[0,1] op_sel_hi:[1,0]
	s_nop 0
	v_readlane_b32 s6, v196, s13
	v_readlane_b32 s7, v195, s13
	v_readlane_b32 s8, v198, s13
	v_readlane_b32 s9, v194, s31
	v_fmac_f32_e32 v3, s6, v6
	v_fmac_f32_e32 v15, s7, v188
	v_fmac_f32_e32 v14, s8, v24
	v_fmac_f32_e32 v2, s9, v186
	v_readlane_b32 s6, v196, s31
	v_readlane_b32 s7, v195, s31
	v_readlane_b32 s8, v198, s31
	v_readlane_b32 s9, v197, s13
	v_fmac_f32_e32 v3, s6, v62
	v_fmac_f32_e32 v15, s7, v182
	v_fmac_f32_e32 v14, s8, v70
	v_fmac_f32_e32 v2, s9, v168
	v_readlane_b32 s6, v200, s13
	v_readlane_b32 s7, v199, s13
	v_readlane_b32 s8, v202, s13
	v_readlane_b32 s9, v197, s31
	v_fmac_f32_e32 v3, s6, v78
	v_fmac_f32_e32 v15, s7, v160
	v_fmac_f32_e32 v14, s8, v84
	v_fmac_f32_e32 v2, s9, v154
	v_readlane_b32 s6, v200, s31
	v_readlane_b32 s7, v199, s31
	v_readlane_b32 s8, v202, s31
	v_readlane_b32 s9, v201, s13
	v_fmac_f32_e32 v3, s6, v184
	v_fmac_f32_e32 v15, s7, v162
	v_fmac_f32_e32 v14, s8, v180
	v_fmac_f32_e32 v2, s9, v164
	v_readlane_b32 s6, v204, s13
	v_readlane_b32 s7, v203, s13
	v_readlane_b32 s8, v206, s13
	v_readlane_b32 s9, v201, s31
	v_fmac_f32_e32 v3, s6, v172
	v_fmac_f32_e32 v15, s7, v156
	v_fmac_f32_e32 v14, s8, v176
	v_fmac_f32_e32 v2, s9, v150
	v_readlane_b32 s6, v204, s31
	v_readlane_b32 s7, v203, s31
	v_readlane_b32 s8, v206, s31
	v_readlane_b32 s9, v205, s13
	v_fmac_f32_e32 v3, s6, v178
	v_fmac_f32_e32 v15, s7, v148
	v_fmac_f32_e32 v14, s8, v174
	v_fmac_f32_e32 v2, s9, v146
	v_readlane_b32 s6, v208, s13
	v_readlane_b32 s7, v207, s13
	v_readlane_b32 s8, v209, s13
	v_readlane_b32 s9, v205, s31
	v_fmac_f32_e32 v3, s6, v170
	v_fmac_f32_e32 v15, s7, v144
	v_fmac_f32_e32 v14, s8, v166
	v_fmac_f32_e32 v2, s9, v142
	v_readlane_b32 s6, v208, s31
	v_readlane_b32 s7, v207, s31
	v_readlane_b32 s8, v209, s31
	v_readlane_b32 s9, v226, s13
	v_fmac_f32_e32 v3, s6, v158
	v_fmac_f32_e32 v15, s7, v140
	v_fmac_f32_e32 v14, s8, v152
	v_fmac_f32_e32 v2, s9, v138
	v_readlane_b32 s6, v225, s13
	v_readlane_b32 s7, v224, s13
	v_readlane_b32 s8, v223, s13
	v_readlane_b32 s9, v226, s31
	v_fmac_f32_e32 v3, s6, v80
	v_fmac_f32_e32 v15, s7, v136
	v_fmac_f32_e32 v14, s8, v76
	v_fmac_f32_e32 v2, s9, v134
	v_readlane_b32 s6, v225, s31
	v_readlane_b32 s7, v224, s31
	v_readlane_b32 s8, v223, s31
	v_readlane_b32 s9, v222, s13
	v_fmac_f32_e32 v3, s6, v72
	v_fmac_f32_e32 v15, s7, v132
	v_fmac_f32_e32 v14, s8, v68
	v_fmac_f32_e32 v2, s9, v130
	v_readlane_b32 s6, v221, s13
	v_readlane_b32 s7, v220, s13
	v_readlane_b32 s8, v219, s13
	v_readlane_b32 s9, v222, s31
	v_fmac_f32_e32 v3, s6, v64
	v_fmac_f32_e32 v15, s7, v128
	v_fmac_f32_e32 v14, s8, v32
	v_fmac_f32_e32 v2, s9, v118
	v_readlane_b32 s6, v221, s31
	v_readlane_b32 s7, v220, s31
	v_readlane_b32 s8, v219, s31
	v_readlane_b32 s9, v218, s13
	v_fmac_f32_e32 v3, s6, v30
	v_fmac_f32_e32 v15, s7, v116
	v_fmac_f32_e32 v14, s8, v26
	v_fmac_f32_e32 v2, s9, v114
	v_readlane_b32 s6, v217, s13
	v_readlane_b32 s7, v216, s13
	v_readlane_b32 s8, v215, s13
	v_readlane_b32 s9, v218, s31
	v_fmac_f32_e32 v3, s6, v22
	v_fmac_f32_e32 v15, s7, v110
	v_fmac_f32_e32 v14, s8, v16
	v_fmac_f32_e32 v2, s9, v104
	v_readlane_b32 s6, v217, s31
	v_readlane_b32 s7, v216, s31
	v_readlane_b32 s8, v215, s31
	v_readlane_b32 s9, v214, s13
	v_fmac_f32_e32 v3, s6, v12
	v_fmac_f32_e32 v15, s7, v96
	v_fmac_f32_e32 v14, s8, v10
	v_fmac_f32_e32 v2, s9, v94
	v_readlane_b32 s6, v213, s13
	v_readlane_b32 s7, v212, s13
	v_readlane_b32 s8, v211, s13
	v_readlane_b32 s9, v214, s31
	v_fmac_f32_e32 v3, s6, v8
	v_fmac_f32_e32 v15, s7, v92
	v_fmac_f32_e32 v14, s8, v4
	v_fmac_f32_e32 v2, s9, v90
	v_readlane_b32 s6, v213, s31
	s_nop 1
	v_fmac_f32_e32 v3, s6, v91
	v_readlane_b32 s6, v212, s31
	s_nop 1
	v_fmac_f32_e32 v3, s6, v88
	v_readlane_b32 s6, v211, s31
	s_nop 1
	v_fmac_f32_e32 v3, s6, v89
	s_nop 0
	v_pk_add_f32 v[2:3], v[14:15], v[2:3]
	s_nop 0
	v_pk_add_f32 v[152:153], v[2:3], v[2:3] op_sel:[0,1] op_sel_hi:[1,0]
	v_readlane_b32 s6, v193, 0
	v_readlane_b32 s7, v193, 1
	v_mov_b32_e32 v153, v6
	s_nop 0
	v_pk_mul_f32 v[2:3], v[152:153], s[6:7]
	v_readlane_b32 s6, v193, 8
	v_readlane_b32 s7, v193, 9
	v_cvt_pk_bf16_f32 v62, v2, v3
	s_nop 0
	v_pk_mul_f32 v[4:5], v[168:169], s[6:7]
	v_readlane_b32 s6, v193, 2
	v_readlane_b32 s7, v193, 3
	v_cvt_pk_bf16_f32 v66, v4, v5
	s_nop 1
	v_permlane32_swap_b32_e32 v62, v66
	v_pk_mul_f32 v[6:7], v[188:189], s[6:7]
	v_readlane_b32 s6, v193, 10
	v_readlane_b32 s7, v193, 11
	v_cvt_pk_bf16_f32 v63, v6, v7
	s_nop 0
	v_pk_mul_f32 v[8:9], v[160:161], s[6:7]
	v_readlane_b32 s6, v193, 4
	v_readlane_b32 s7, v193, 5
	v_cvt_pk_bf16_f32 v67, v8, v9
	s_nop 1
	v_permlane32_swap_b32_e32 v63, v67
	v_pk_mul_f32 v[10:11], v[186:187], s[6:7]
	v_readlane_b32 s6, v193, 12
	v_readlane_b32 s7, v193, 13
	v_cvt_pk_bf16_f32 v64, v10, v11
	s_nop 0
	v_pk_mul_f32 v[12:13], v[154:155], s[6:7]
	v_readlane_b32 s6, v193, 6
	v_readlane_b32 s7, v193, 7
	v_cvt_pk_bf16_f32 v68, v12, v13
	s_nop 1
	v_permlane32_swap_b32_e32 v64, v68
	v_pk_mul_f32 v[14:15], v[182:183], s[6:7]
	v_readlane_b32 s6, v193, 14
	v_readlane_b32 s7, v193, 15
	v_cvt_pk_bf16_f32 v65, v14, v15
	s_nop 0
	v_pk_mul_f32 v[16:17], v[162:163], s[6:7]
	v_readlane_b32 s6, v193, 16
	v_readlane_b32 s7, v193, 17
	v_cvt_pk_bf16_f32 v69, v16, v17
	s_nop 1
	v_permlane32_swap_b32_e32 v65, v69
	v_pk_mul_f32 v[2:3], v[164:165], s[6:7]
	v_readlane_b32 s6, v193, 24
	v_readlane_b32 s7, v193, 25
	v_cvt_pk_bf16_f32 v70, v2, v3
	s_nop 0
	v_pk_mul_f32 v[4:5], v[146:147], s[6:7]
	v_readlane_b32 s6, v193, 18
	v_readlane_b32 s7, v193, 19
	v_cvt_pk_bf16_f32 v74, v4, v5
	s_nop 1
	v_permlane32_swap_b32_e32 v70, v74
	v_pk_mul_f32 v[6:7], v[156:157], s[6:7]
	v_readlane_b32 s6, v193, 26
	v_readlane_b32 s7, v193, 27
	v_cvt_pk_bf16_f32 v71, v6, v7
	s_nop 0
	v_pk_mul_f32 v[8:9], v[144:145], s[6:7]
	v_readlane_b32 s6, v193, 20
	v_readlane_b32 s7, v193, 21
	v_cvt_pk_bf16_f32 v75, v8, v9
	s_nop 1
	v_permlane32_swap_b32_e32 v71, v75
	v_pk_mul_f32 v[10:11], v[150:151], s[6:7]
	v_readlane_b32 s6, v193, 28
	v_readlane_b32 s7, v193, 29
	v_cvt_pk_bf16_f32 v72, v10, v11
	s_nop 0
	v_pk_mul_f32 v[12:13], v[142:143], s[6:7]
	v_readlane_b32 s6, v193, 22
	v_readlane_b32 s7, v193, 23
	v_cvt_pk_bf16_f32 v76, v12, v13
	s_nop 1
	v_permlane32_swap_b32_e32 v72, v76
	v_pk_mul_f32 v[14:15], v[148:149], s[6:7]
	v_readlane_b32 s6, v193, 30
	v_readlane_b32 s7, v193, 31
	v_cvt_pk_bf16_f32 v73, v14, v15
	s_nop 0
	v_pk_mul_f32 v[16:17], v[140:141], s[6:7]
	v_readlane_b32 s6, v193, 32
	v_readlane_b32 s7, v193, 33
	v_cvt_pk_bf16_f32 v77, v16, v17
	s_nop 1
	v_permlane32_swap_b32_e32 v73, v77
	v_pk_mul_f32 v[2:3], v[138:139], s[6:7]
	v_readlane_b32 s6, v193, 40
	v_readlane_b32 s7, v193, 41
	v_cvt_pk_bf16_f32 v2, v2, v3
	s_nop 0
	v_pk_mul_f32 v[4:5], v[130:131], s[6:7]
	v_readlane_b32 s6, v193, 34
	v_readlane_b32 s7, v193, 35
	v_cvt_pk_bf16_f32 v78, v4, v5
	s_nop 1
	v_permlane32_swap_b32_e32 v2, v78
	v_pk_mul_f32 v[6:7], v[136:137], s[6:7]
	v_readlane_b32 s6, v193, 42
	v_readlane_b32 s7, v193, 43
	v_cvt_pk_bf16_f32 v3, v6, v7
	s_nop 0
	v_pk_mul_f32 v[8:9], v[128:129], s[6:7]
	v_readlane_b32 s6, v193, 36
	v_readlane_b32 s7, v193, 37
	v_cvt_pk_bf16_f32 v79, v8, v9
	s_nop 1
	v_permlane32_swap_b32_e32 v3, v79
	v_pk_mul_f32 v[10:11], v[134:135], s[6:7]
	v_readlane_b32 s6, v193, 44
	v_readlane_b32 s7, v193, 45
	v_cvt_pk_bf16_f32 v6, v10, v11
	s_nop 0
	v_pk_mul_f32 v[12:13], v[118:119], s[6:7]
	v_readlane_b32 s6, v193, 38
	v_readlane_b32 s7, v193, 39
	v_cvt_pk_bf16_f32 v80, v12, v13
	s_nop 1
	v_permlane32_swap_b32_e32 v6, v80
	v_pk_mul_f32 v[14:15], v[132:133], s[6:7]
	v_readlane_b32 s6, v193, 46
	v_readlane_b32 s7, v193, 47
	v_cvt_pk_bf16_f32 v7, v14, v15
	s_nop 0
	v_pk_mul_f32 v[16:17], v[116:117], s[6:7]
	v_readlane_b32 s6, v193, 48
	v_readlane_b32 s7, v193, 49
	v_cvt_pk_bf16_f32 v81, v16, v17
	s_nop 1
	v_permlane32_swap_b32_e32 v7, v81
	v_pk_mul_f32 v[2:3], v[114:115], s[6:7]
	v_readlane_b32 s6, v193, 56
	v_readlane_b32 s7, v193, 57
	v_cvt_pk_bf16_f32 v2, v2, v3
	s_nop 0
	v_pk_mul_f32 v[4:5], v[94:95], s[6:7]
	v_readlane_b32 s6, v193, 50
	v_readlane_b32 s7, v193, 51
	v_cvt_pk_bf16_f32 v82, v4, v5
	s_nop 1
	v_permlane32_swap_b32_e32 v2, v82
	v_pk_mul_f32 v[6:7], v[110:111], s[6:7]
	v_readlane_b32 s6, v193, 58
	v_readlane_b32 s7, v193, 59
	v_cvt_pk_bf16_f32 v3, v6, v7
	s_nop 0
	v_pk_mul_f32 v[8:9], v[92:93], s[6:7]
	v_readlane_b32 s6, v193, 52
	v_readlane_b32 s7, v193, 53
	v_cvt_pk_bf16_f32 v83, v8, v9
	s_nop 1
	v_permlane32_swap_b32_e32 v3, v83
	v_pk_mul_f32 v[10:11], v[104:105], s[6:7]
	v_readlane_b32 s6, v193, 60
	v_readlane_b32 s7, v193, 61
	v_cvt_pk_bf16_f32 v6, v10, v11
	s_nop 0
	v_pk_mul_f32 v[12:13], v[90:91], s[6:7]
	v_readlane_b32 s6, v193, 54
	v_readlane_b32 s7, v193, 55
	v_cvt_pk_bf16_f32 v84, v12, v13
	s_nop 1
	v_permlane32_swap_b32_e32 v6, v84
	v_pk_mul_f32 v[14:15], v[96:97], s[6:7]
	v_readlane_b32 s6, v193, 62
	v_readlane_b32 s7, v193, 63
	v_cvt_pk_bf16_f32 v7, v14, v15
	s_nop 0
	v_pk_mul_f32 v[16:17], v[88:89], s[6:7]
	s_mov_b32 s7, 0x26400000
	v_cvt_pk_bf16_f32 v85, v16, v17
	s_nop 1
	v_permlane32_swap_b32_e32 v7, v85
	s_waitcnt vmcnt(5)
	v_mfma_f32_32x32x16_bf16 v[2:17], v[62:65], v[18:21], 0
	s_mov_b32 s6, 0x9002000
	v_mfma_f32_32x32x16_bf16 v[18:33], v[66:69], v[18:21], 0
	v_mfma_f32_32x32x16_bf16 v[18:33], v[74:77], v[58:61], v[18:33]
	v_mfma_f32_32x32x16_bf16 v[18:33], v[78:81], v[54:57], v[18:33]
	v_mfma_f32_32x32x16_bf16 v[2:17], v[70:73], v[58:61], v[2:17]
	s_waitcnt vmcnt(4)
	v_mfma_f32_32x32x16_bf16 v[18:33], v[82:85], v[50:53], v[18:33]
	v_add_co_u32_e32 v50, vcc, s7, v126
	s_nop 8
	v_cvt_pk_bf16_f32 v2, v2, v3
	v_cvt_pk_bf16_f32 v3, v4, v5
	v_cvt_pk_bf16_f32 v4, v6, v7
	v_cvt_pk_bf16_f32 v5, v8, v9
	v_addc_co_u32_e32 v51, vcc, 0, v127, vcc
	global_store_dwordx4 v[50:51], v[2:5], off
	v_add_co_u32_e32 v6, vcc, s7, v120
	s_nop 0
	v_cvt_pk_bf16_f32 v2, v10, v11
	v_cvt_pk_bf16_f32 v3, v12, v13
	v_cvt_pk_bf16_f32 v4, v14, v15
	v_cvt_pk_bf16_f32 v5, v16, v17
	global_store_dwordx4 v[50:51], v[2:5], off offset:16
	v_addc_co_u32_e32 v7, vcc, 0, v121, vcc
	s_nop 0
	v_cvt_pk_bf16_f32 v2, v18, v19
	v_cvt_pk_bf16_f32 v3, v20, v21
	v_cvt_pk_bf16_f32 v4, v22, v23
	v_cvt_pk_bf16_f32 v5, v24, v25
	global_store_dwordx4 v[6:7], v[2:5], off
	s_nop 1
	v_cvt_pk_bf16_f32 v2, v26, v27
	v_cvt_pk_bf16_f32 v3, v28, v29
	v_cvt_pk_bf16_f32 v4, v30, v31
	v_cvt_pk_bf16_f32 v5, v32, v33
	global_store_dwordx4 v[6:7], v[2:5], off offset:16
	s_waitcnt vmcnt(7)
	v_mfma_f32_32x32x16_bf16 v[18:33], v[62:65], v[46:49], 0
	v_mfma_f32_32x32x16_bf16 v[2:17], v[66:69], v[46:49], 0
	s_waitcnt vmcnt(6)
	v_mfma_f32_32x32x16_bf16 v[2:17], v[74:77], v[42:45], v[2:17]
	s_waitcnt vmcnt(5)
	v_mfma_f32_32x32x16_bf16 v[2:17], v[78:81], v[38:41], v[2:17]
	s_waitcnt vmcnt(4)
	v_mfma_f32_32x32x16_bf16 v[2:17], v[82:85], v[34:37], v[2:17]
	v_mfma_f32_32x32x16_bf16 v[18:33], v[70:73], v[42:45], v[18:33]
	s_nop 10
	v_cvt_pk_bf16_f32 v2, v2, v3
	v_cvt_pk_bf16_f32 v3, v4, v5
	v_cvt_pk_bf16_f32 v4, v6, v7
	v_add_co_u32_e32 v6, vcc, s7, v112
	v_cvt_pk_bf16_f32 v5, v8, v9
	s_nop 0
	v_addc_co_u32_e32 v7, vcc, 0, v113, vcc
	v_cvt_pk_bf16_f32 v18, v18, v19
	v_cvt_pk_bf16_f32 v19, v20, v21
	v_cvt_pk_bf16_f32 v20, v22, v23
	v_cvt_pk_bf16_f32 v21, v24, v25
	v_add_co_u32_e32 v38, vcc, s6, v98
	global_store_dwordx4 v[50:51], v[18:21], off offset:2048
	s_nop 0
	v_addc_co_u32_e32 v39, vcc, 0, v99, vcc
	v_cvt_pk_bf16_f32 v18, v26, v27
	v_cvt_pk_bf16_f32 v19, v28, v29
	v_cvt_pk_bf16_f32 v20, v30, v31
	v_cvt_pk_bf16_f32 v21, v32, v33
	s_mov_b32 s6, 0x9003000
	global_store_dwordx4 v[50:51], v[18:21], off offset:2064
	global_store_dwordx4 v[6:7], v[2:5], off
	v_add_co_u32_e32 v40, vcc, s6, v98
	s_nop 0
	v_cvt_pk_bf16_f32 v2, v10, v11
	v_cvt_pk_bf16_f32 v3, v12, v13
	v_cvt_pk_bf16_f32 v4, v14, v15
	v_cvt_pk_bf16_f32 v5, v16, v17
	global_store_dwordx4 v[6:7], v[2:5], off offset:16
	v_addc_co_u32_e32 v41, vcc, 0, v99, vcc
	global_load_dwordx4 v[2:5], v[40:41], off offset:-4096
	global_load_dwordx4 v[34:37], v[38:39], off offset:32
	s_waitcnt vmcnt(1)
	v_mfma_f32_32x32x16_bf16 v[18:33], v[62:65], v[2:5], 0
	v_mfma_f32_32x32x16_bf16 v[2:17], v[66:69], v[2:5], 0
	s_waitcnt vmcnt(0)
	v_mfma_f32_32x32x16_bf16 v[18:33], v[70:73], v[34:37], v[18:33]
	v_mfma_f32_32x32x16_bf16 v[2:17], v[74:77], v[34:37], v[2:17]
	global_load_dwordx4 v[34:37], v[38:39], off offset:64
	s_nop 9
	v_cvt_pk_bf16_f32 v18, v18, v19
	v_cvt_pk_bf16_f32 v19, v20, v21
	v_cvt_pk_bf16_f32 v20, v22, v23
	v_add_co_u32_e32 v22, vcc, s7, v108
	v_cvt_pk_bf16_f32 v21, v24, v25
	s_waitcnt vmcnt(0)
	v_mfma_f32_32x32x16_bf16 v[2:17], v[78:81], v[34:37], v[2:17]
	global_load_dwordx4 v[34:37], v[38:39], off offset:96
	v_addc_co_u32_e32 v23, vcc, 0, v109, vcc
	global_store_dwordx4 v[22:23], v[18:21], off
	s_nop 1
	v_cvt_pk_bf16_f32 v18, v26, v27
	s_waitcnt vmcnt(1)
	v_mfma_f32_32x32x16_bf16 v[2:17], v[82:85], v[34:37], v[2:17]
	v_cvt_pk_bf16_f32 v19, v28, v29
	v_cvt_pk_bf16_f32 v20, v30, v31
	v_cvt_pk_bf16_f32 v21, v32, v33
	global_store_dwordx4 v[22:23], v[18:21], off offset:16
	s_nop 7
	v_cvt_pk_bf16_f32 v2, v2, v3
	v_cvt_pk_bf16_f32 v3, v4, v5
	v_cvt_pk_bf16_f32 v4, v6, v7
	v_add_co_u32_e32 v6, vcc, s7, v106
	v_cvt_pk_bf16_f32 v5, v8, v9
	s_nop 0
	v_addc_co_u32_e32 v7, vcc, 0, v107, vcc
	global_store_dwordx4 v[6:7], v[2:5], off
	s_nop 1
	v_cvt_pk_bf16_f32 v2, v10, v11
	v_cvt_pk_bf16_f32 v3, v12, v13
	v_cvt_pk_bf16_f32 v4, v14, v15
	v_cvt_pk_bf16_f32 v5, v16, v17
	global_store_dwordx4 v[6:7], v[2:5], off offset:16
	global_load_dwordx4 v[2:5], v[40:41], off
	s_nop 0
	global_load_dwordx4 v[34:37], v[40:41], off offset:32
	s_waitcnt vmcnt(1)
	v_mfma_f32_32x32x16_bf16 v[18:33], v[62:65], v[2:5], 0
	v_mfma_f32_32x32x16_bf16 v[2:17], v[66:69], v[2:5], 0
	s_waitcnt vmcnt(0)
	v_mfma_f32_32x32x16_bf16 v[18:33], v[70:73], v[34:37], v[18:33]
	v_mfma_f32_32x32x16_bf16 v[2:17], v[74:77], v[34:37], v[2:17]
	global_load_dwordx4 v[34:37], v[40:41], off offset:64
	s_nop 9
	v_cvt_pk_bf16_f32 v18, v18, v19
	v_cvt_pk_bf16_f32 v19, v20, v21
	v_cvt_pk_bf16_f32 v20, v22, v23
	v_add_co_u32_e32 v22, vcc, s7, v102
	v_cvt_pk_bf16_f32 v21, v24, v25
	s_waitcnt vmcnt(0)
	v_mfma_f32_32x32x16_bf16 v[2:17], v[78:81], v[34:37], v[2:17]
	global_load_dwordx4 v[34:37], v[40:41], off offset:96
	v_addc_co_u32_e32 v23, vcc, 0, v103, vcc
	global_store_dwordx4 v[22:23], v[18:21], off
	s_nop 1
	v_cvt_pk_bf16_f32 v18, v26, v27
	s_waitcnt vmcnt(1)
	v_mfma_f32_32x32x16_bf16 v[2:17], v[82:85], v[34:37], v[2:17]
	v_cvt_pk_bf16_f32 v19, v28, v29
	v_cvt_pk_bf16_f32 v20, v30, v31
	v_cvt_pk_bf16_f32 v21, v32, v33
	global_store_dwordx4 v[22:23], v[18:21], off offset:16
	s_nop 7
	v_cvt_pk_bf16_f32 v2, v2, v3
	v_cvt_pk_bf16_f32 v3, v4, v5
	v_cvt_pk_bf16_f32 v4, v6, v7
	v_add_co_u32_e32 v6, vcc, s7, v100
	v_cvt_pk_bf16_f32 v5, v8, v9
	s_nop 0
	v_addc_co_u32_e32 v7, vcc, 0, v101, vcc
	global_store_dwordx4 v[6:7], v[2:5], off
	s_nop 1
	v_cvt_pk_bf16_f32 v2, v10, v11
	v_cvt_pk_bf16_f32 v3, v12, v13
	v_cvt_pk_bf16_f32 v4, v14, v15
	v_cvt_pk_bf16_f32 v5, v16, v17
	global_store_dwordx4 v[6:7], v[2:5], off offset:16
	v_readlane_b32 s6, v210, 0
	v_readlane_b32 s7, v210, 1
	s_lshl_b64 s[4:5], s[4:5], 20
	v_readlane_b32 s8, v250, 17
	v_pk_mul_f32 v[2:3], v[152:153], s[6:7]
	v_readlane_b32 s6, v210, 8
	v_readlane_b32 s7, v210, 9
	v_cvt_pk_bf16_f32 v34, v2, v3
	s_nop 0
	v_pk_mul_f32 v[4:5], v[168:169], s[6:7]
	v_readlane_b32 s6, v210, 2
	v_readlane_b32 s7, v210, 3
	v_cvt_pk_bf16_f32 v38, v4, v5
	s_nop 1
	v_permlane32_swap_b32_e32 v34, v38
	v_pk_mul_f32 v[6:7], v[188:189], s[6:7]
	v_readlane_b32 s6, v210, 10
	v_readlane_b32 s7, v210, 11
	v_cvt_pk_bf16_f32 v35, v6, v7
	s_nop 0
	v_pk_mul_f32 v[8:9], v[160:161], s[6:7]
	v_readlane_b32 s6, v210, 4
	v_readlane_b32 s7, v210, 5
	v_cvt_pk_bf16_f32 v39, v8, v9
	s_nop 1
	v_permlane32_swap_b32_e32 v35, v39
	v_pk_mul_f32 v[10:11], v[186:187], s[6:7]
	v_readlane_b32 s6, v210, 12
	v_readlane_b32 s7, v210, 13
	v_cvt_pk_bf16_f32 v36, v10, v11
	s_nop 0
	v_pk_mul_f32 v[12:13], v[154:155], s[6:7]
	v_readlane_b32 s6, v210, 6
	v_readlane_b32 s7, v210, 7
	v_cvt_pk_bf16_f32 v40, v12, v13
	s_nop 1
	v_permlane32_swap_b32_e32 v36, v40
	v_pk_mul_f32 v[14:15], v[182:183], s[6:7]
	v_readlane_b32 s6, v210, 14
	v_readlane_b32 s7, v210, 15
	v_cvt_pk_bf16_f32 v37, v14, v15
	s_nop 0
	v_pk_mul_f32 v[16:17], v[162:163], s[6:7]
	v_readlane_b32 s6, v210, 16
	v_readlane_b32 s7, v210, 17
	v_cvt_pk_bf16_f32 v41, v16, v17
	s_nop 1
	v_permlane32_swap_b32_e32 v37, v41
	v_pk_mul_f32 v[2:3], v[164:165], s[6:7]
	v_readlane_b32 s6, v210, 24
	v_readlane_b32 s7, v210, 25
	v_cvt_pk_bf16_f32 v42, v2, v3
	s_nop 0
	v_pk_mul_f32 v[4:5], v[146:147], s[6:7]
	v_readlane_b32 s6, v210, 18
	v_readlane_b32 s7, v210, 19
	v_cvt_pk_bf16_f32 v46, v4, v5
	s_nop 1
	v_permlane32_swap_b32_e32 v42, v46
	v_pk_mul_f32 v[6:7], v[156:157], s[6:7]
	v_readlane_b32 s6, v210, 26
	v_readlane_b32 s7, v210, 27
	v_cvt_pk_bf16_f32 v43, v6, v7
	s_nop 0
	v_pk_mul_f32 v[8:9], v[144:145], s[6:7]
	v_readlane_b32 s6, v210, 20
	v_readlane_b32 s7, v210, 21
	v_cvt_pk_bf16_f32 v47, v8, v9
	s_nop 1
	v_permlane32_swap_b32_e32 v43, v47
	v_pk_mul_f32 v[10:11], v[150:151], s[6:7]
	v_readlane_b32 s6, v210, 28
	v_readlane_b32 s7, v210, 29
	v_cvt_pk_bf16_f32 v44, v10, v11
	s_nop 0
	v_pk_mul_f32 v[12:13], v[142:143], s[6:7]
	v_readlane_b32 s6, v210, 22
	v_readlane_b32 s7, v210, 23
	v_cvt_pk_bf16_f32 v48, v12, v13
	s_nop 1
	v_permlane32_swap_b32_e32 v44, v48
	v_pk_mul_f32 v[14:15], v[148:149], s[6:7]
	v_readlane_b32 s6, v210, 30
	v_readlane_b32 s7, v210, 31
	v_cvt_pk_bf16_f32 v45, v14, v15
	s_nop 0
	v_pk_mul_f32 v[16:17], v[140:141], s[6:7]
	v_readlane_b32 s6, v210, 32
	v_readlane_b32 s7, v210, 33
	v_cvt_pk_bf16_f32 v49, v16, v17
	s_nop 1
	v_permlane32_swap_b32_e32 v45, v49
	v_pk_mul_f32 v[2:3], v[138:139], s[6:7]
	v_readlane_b32 s6, v210, 40
	v_readlane_b32 s7, v210, 41
	v_cvt_pk_bf16_f32 v2, v2, v3
	s_nop 0
	v_pk_mul_f32 v[4:5], v[130:131], s[6:7]
	v_readlane_b32 s6, v210, 34
	v_readlane_b32 s7, v210, 35
	v_cvt_pk_bf16_f32 v50, v4, v5
	s_nop 1
	v_permlane32_swap_b32_e32 v2, v50
	v_pk_mul_f32 v[6:7], v[136:137], s[6:7]
	v_readlane_b32 s6, v210, 42
	v_readlane_b32 s7, v210, 43
	v_cvt_pk_bf16_f32 v3, v6, v7
	s_nop 0
	v_pk_mul_f32 v[8:9], v[128:129], s[6:7]
	v_readlane_b32 s6, v210, 36
	v_readlane_b32 s7, v210, 37
	v_cvt_pk_bf16_f32 v51, v8, v9
	s_nop 1
	v_permlane32_swap_b32_e32 v3, v51
	v_pk_mul_f32 v[10:11], v[134:135], s[6:7]
	v_readlane_b32 s6, v210, 44
	v_readlane_b32 s7, v210, 45
	v_cvt_pk_bf16_f32 v6, v10, v11
	s_nop 0
	v_pk_mul_f32 v[12:13], v[118:119], s[6:7]
	v_readlane_b32 s6, v210, 38
	v_readlane_b32 s7, v210, 39
	v_cvt_pk_bf16_f32 v52, v12, v13
	s_nop 1
	v_permlane32_swap_b32_e32 v6, v52
	v_pk_mul_f32 v[14:15], v[132:133], s[6:7]
	v_readlane_b32 s6, v210, 46
	v_readlane_b32 s7, v210, 47
	v_cvt_pk_bf16_f32 v7, v14, v15
	s_nop 0
	v_pk_mul_f32 v[16:17], v[116:117], s[6:7]
	v_readlane_b32 s6, v210, 48
	v_readlane_b32 s7, v210, 49
	v_cvt_pk_bf16_f32 v53, v16, v17
	s_nop 1
	v_permlane32_swap_b32_e32 v7, v53
	v_pk_mul_f32 v[2:3], v[114:115], s[6:7]
	v_readlane_b32 s6, v210, 56
	v_readlane_b32 s7, v210, 57
	v_cvt_pk_bf16_f32 v2, v2, v3
	s_nop 0
	v_pk_mul_f32 v[4:5], v[94:95], s[6:7]
	v_readlane_b32 s6, v210, 50
	v_readlane_b32 s7, v210, 51
	v_cvt_pk_bf16_f32 v54, v4, v5
	s_nop 1
	v_permlane32_swap_b32_e32 v2, v54
	v_pk_mul_f32 v[6:7], v[110:111], s[6:7]
	v_readlane_b32 s6, v210, 58
	v_readlane_b32 s7, v210, 59
	v_cvt_pk_bf16_f32 v3, v6, v7
	v_lshlrev_b32_e32 v2, 8, v192
	v_pk_mul_f32 v[8:9], v[92:93], s[6:7]
	v_readlane_b32 s6, v210, 52
	v_readlane_b32 s7, v210, 53
	v_cvt_pk_bf16_f32 v55, v8, v9
	s_nop 1
	v_permlane32_swap_b32_e32 v3, v55
	v_pk_mul_f32 v[10:11], v[104:105], s[6:7]
	v_readlane_b32 s6, v210, 60
	v_readlane_b32 s7, v210, 61
	v_mov_b32_e32 v3, v123
	v_lshl_add_u64 v[2:3], v[2:3], 0, v[124:125]
	v_pk_mul_f32 v[12:13], v[90:91], s[6:7]
	v_readlane_b32 s6, v210, 54
	v_readlane_b32 s7, v210, 55
	v_lshl_add_u64 v[64:65], s[0:1], 0, v[2:3]
	v_cvt_pk_bf16_f32 v6, v10, v11
	v_pk_mul_f32 v[14:15], v[96:97], s[6:7]
	v_readlane_b32 s6, v210, 62
	v_readlane_b32 s7, v210, 63
	v_cvt_pk_bf16_f32 v7, v14, v15
	v_cvt_pk_bf16_f32 v56, v12, v13
	v_pk_mul_f32 v[16:17], v[88:89], s[6:7]
	v_readlane_b32 s6, v250, 3
	s_add_u32 s4, s6, s4
	v_readlane_b32 s6, v250, 4
	s_addc_u32 s5, s6, s5
	v_readlane_b32 s6, v250, 13
	s_lshl_b32 s6, s6, 14
	s_add_u32 s4, s4, s6
	s_addc_u32 s5, s5, 0
	v_lshl_add_u64 v[62:63], s[4:5], 0, v[86:87]
	v_lshl_add_u64 v[66:67], v[62:63], 0, v[122:123]
	v_mov_b32_e32 v142, 0x1000
	v_mov_b32_e32 v143, 0
	v_lshl_add_u64 v[130:131], v[66:67], 0, v[142:143]
	v_lshl_add_u64 v[134:135], v[130:131], 0, v[142:143]
	v_lshl_add_u64 v[138:139], v[134:135], 0, v[142:143]
	global_load_dwordx4 v[202:205], v[66:67], off
	global_load_dwordx4 v[208:211], v[66:67], off offset:32
	global_load_dwordx4 v[212:215], v[66:67], off offset:64
	global_load_dwordx4 v[216:219], v[66:67], off offset:96
	global_load_dwordx4 v[220:223], v[130:131], off
	global_load_dwordx4 v[234:237], v[130:131], off offset:32
	global_load_dwordx4 v[238:241], v[130:131], off offset:64
	global_load_dwordx4 v[242:245], v[130:131], off offset:96
	s_nop 0
	s_nop 0
	v_cvt_pk_bf16_f32 v57, v16, v17
	v_permlane32_swap_b32_e32 v6, v56
	s_nop 0
	v_permlane32_swap_b32_e32 v7, v57
	s_nop 0
	s_waitcnt vmcnt(7)
	v_mfma_f32_32x32x16_bf16 v[18:33], v[202:205], v[34:37], 0
	s_mov_b32 s0, 0x2e400000
	v_readlane_b32 s7, v250, 15
	v_mfma_f32_32x32x16_bf16 v[2:17], v[202:205], v[38:41], 0
	s_nop 0
	s_waitcnt vmcnt(6)
	v_mfma_f32_32x32x16_bf16 v[18:33], v[208:211], v[42:45], v[18:33]
	v_mfma_f32_32x32x16_bf16 v[2:17], v[208:211], v[46:49], v[2:17]
	s_nop 0
	s_nop 9
	v_cvt_pk_bf16_f32 v18, v18, v19
	v_cvt_pk_bf16_f32 v19, v20, v21
	s_nop 0
	s_waitcnt vmcnt(5)
	v_mfma_f32_32x32x16_bf16 v[2:17], v[212:215], v[50:53], v[2:17]
	s_nop 0
	s_nop 0
	s_waitcnt vmcnt(4)
	v_mfma_f32_32x32x16_bf16 v[2:17], v[216:219], v[54:57], v[2:17]
	v_add_co_u32_e32 v58, vcc, s0, v64
	s_mov_b32 s0, 0x2e402000
	s_nop 0
	v_addc_co_u32_e32 v59, vcc, 0, v65, vcc
	v_add_co_u32_e32 v60, vcc, s0, v64
	s_nop 6
	v_cvt_pk_bf16_f32 v2, v2, v3
	v_cvt_pk_bf16_f32 v3, v4, v5
	v_addc_co_u32_e32 v61, vcc, 0, v65, vcc
	global_store_dwordx2 v[60:61], v[2:3], off
	v_cvt_pk_bf16_f32 v2, v22, v23
	v_cvt_pk_bf16_f32 v3, v24, v25
	global_store_dwordx2 v[58:59], v[2:3], off offset:16
	v_cvt_pk_bf16_f32 v2, v6, v7
	v_cvt_pk_bf16_f32 v3, v8, v9
	global_store_dwordx2 v[60:61], v[2:3], off offset:16
	v_cvt_pk_bf16_f32 v2, v26, v27
	v_cvt_pk_bf16_f32 v3, v28, v29
	global_store_dwordx2 v[58:59], v[2:3], off offset:32
	v_cvt_pk_bf16_f32 v2, v10, v11
	v_cvt_pk_bf16_f32 v3, v12, v13
	global_store_dwordx2 v[60:61], v[2:3], off offset:32
	v_cvt_pk_bf16_f32 v2, v30, v31
	v_cvt_pk_bf16_f32 v3, v32, v33
	global_store_dwordx2 v[58:59], v[2:3], off offset:48
	v_cvt_pk_bf16_f32 v2, v14, v15
	v_cvt_pk_bf16_f32 v3, v16, v17
	global_store_dwordx2 v[60:61], v[2:3], off offset:48
	v_or_b32_e32 v2, 0x1000, v122
	v_mov_b32_e32 v3, v123
	global_store_dwordx2 v[58:59], v[18:19], off
	v_lshl_add_u64 v[68:69], v[62:63], 0, v[2:3]
	global_load_dwordx4 v[202:205], v[134:135], off
	global_load_dwordx4 v[208:211], v[134:135], off offset:32
	global_load_dwordx4 v[212:215], v[134:135], off offset:64
	global_load_dwordx4 v[216:219], v[134:135], off offset:96
	s_nop 0
	s_nop 0
	s_nop 0
	s_waitcnt vmcnt(15)
	v_mfma_f32_32x32x16_bf16 v[18:33], v[220:223], v[34:37], 0
	v_readlane_b32 s0, v250, 9
	v_readlane_b32 s1, v250, 10
	s_add_i32 s33, s33, s0
	v_readlane_b32 s0, v250, 5
	v_readlane_b32 s1, v250, 6
	s_add_u32 s24, s24, s0
	s_addc_u32 s25, s25, s1
	v_mfma_f32_32x32x16_bf16 v[2:17], v[220:223], v[38:41], 0
	v_readlane_b32 s0, v250, 7
	v_readlane_b32 s1, v250, 8
	s_add_u32 s28, s28, s0
	s_addc_u32 s29, s29, s1
	v_readlane_b32 s0, v250, 11
	v_readlane_b32 s1, v250, 12
	s_add_u32 s7, s7, s0
	s_nop 0
	s_waitcnt vmcnt(14)
	v_mfma_f32_32x32x16_bf16 v[18:33], v[234:237], v[42:45], v[18:33]
	s_addc_u32 s8, s8, s1
	s_cmpk_lt_i32 s33, 0x2000
	v_mfma_f32_32x32x16_bf16 v[2:17], v[234:237], v[46:49], v[2:17]
	s_nop 0
	s_nop 7
	v_cvt_pk_bf16_f32 v18, v18, v19
	v_cvt_pk_bf16_f32 v19, v20, v21
	s_nop 0
	s_waitcnt vmcnt(13)
	v_mfma_f32_32x32x16_bf16 v[2:17], v[238:241], v[50:53], v[2:17]
	s_nop 0
	s_nop 0
	global_store_dwordx2 v[58:59], v[18:19], off offset:64
	s_nop 0
	s_waitcnt vmcnt(13)
	v_mfma_f32_32x32x16_bf16 v[2:17], v[242:245], v[54:57], v[2:17]
	s_nop 11
	v_cvt_pk_bf16_f32 v2, v2, v3
	v_cvt_pk_bf16_f32 v3, v4, v5
	global_store_dwordx2 v[60:61], v[2:3], off offset:64
	v_cvt_pk_bf16_f32 v2, v22, v23
	v_cvt_pk_bf16_f32 v3, v24, v25
	global_store_dwordx2 v[58:59], v[2:3], off offset:80
	v_cvt_pk_bf16_f32 v2, v6, v7
	v_cvt_pk_bf16_f32 v3, v8, v9
	global_store_dwordx2 v[60:61], v[2:3], off offset:80
	v_cvt_pk_bf16_f32 v2, v26, v27
	v_cvt_pk_bf16_f32 v3, v28, v29
	global_store_dwordx2 v[58:59], v[2:3], off offset:96
	v_cvt_pk_bf16_f32 v2, v10, v11
	v_cvt_pk_bf16_f32 v3, v12, v13
	global_store_dwordx2 v[60:61], v[2:3], off offset:96
	v_cvt_pk_bf16_f32 v2, v30, v31
	v_cvt_pk_bf16_f32 v3, v32, v33
	global_store_dwordx2 v[58:59], v[2:3], off offset:112
	v_cvt_pk_bf16_f32 v2, v14, v15
	v_cvt_pk_bf16_f32 v3, v16, v17
	global_store_dwordx2 v[60:61], v[2:3], off offset:112
	v_or_b32_e32 v2, 0x2000, v122
	v_mov_b32_e32 v3, v123
	v_lshl_add_u64 v[68:69], v[62:63], 0, v[2:3]
	global_load_dwordx4 v[220:223], v[138:139], off
	global_load_dwordx4 v[234:237], v[138:139], off offset:32
	global_load_dwordx4 v[238:241], v[138:139], off offset:64
	global_load_dwordx4 v[242:245], v[138:139], off offset:96
	s_nop 0
	s_nop 0
	s_nop 0
	s_waitcnt vmcnt(15)
	v_mfma_f32_32x32x16_bf16 v[18:33], v[202:205], v[34:37], 0
	v_or_b32_e32 v122, 0x3000, v122
	v_lshl_add_u64 v[62:63], v[62:63], 0, v[122:123]
	v_mfma_f32_32x32x16_bf16 v[2:17], v[202:205], v[38:41], 0
	s_nop 0
	s_waitcnt vmcnt(14)
	v_mfma_f32_32x32x16_bf16 v[18:33], v[208:211], v[42:45], v[18:33]
	v_mfma_f32_32x32x16_bf16 v[2:17], v[208:211], v[46:49], v[2:17]
	s_nop 0
	s_nop 9
	v_cvt_pk_bf16_f32 v18, v18, v19
	v_cvt_pk_bf16_f32 v19, v20, v21
	s_nop 0
	s_waitcnt vmcnt(13)
	v_mfma_f32_32x32x16_bf16 v[2:17], v[212:215], v[50:53], v[2:17]
	s_nop 0
	s_nop 0
	global_store_dwordx2 v[58:59], v[18:19], off offset:128
	s_nop 0
	s_waitcnt vmcnt(13)
	v_mfma_f32_32x32x16_bf16 v[2:17], v[216:219], v[54:57], v[2:17]
	s_nop 11
	v_cvt_pk_bf16_f32 v2, v2, v3
	v_cvt_pk_bf16_f32 v3, v4, v5
	global_store_dwordx2 v[60:61], v[2:3], off offset:128
	v_cvt_pk_bf16_f32 v2, v22, v23
	v_cvt_pk_bf16_f32 v3, v24, v25
	global_store_dwordx2 v[58:59], v[2:3], off offset:144
	v_cvt_pk_bf16_f32 v2, v6, v7
	v_cvt_pk_bf16_f32 v3, v8, v9
	global_store_dwordx2 v[60:61], v[2:3], off offset:144
	v_cvt_pk_bf16_f32 v2, v26, v27
	v_cvt_pk_bf16_f32 v3, v28, v29
	global_store_dwordx2 v[58:59], v[2:3], off offset:160
	v_cvt_pk_bf16_f32 v2, v10, v11
	v_cvt_pk_bf16_f32 v3, v12, v13
	global_store_dwordx2 v[60:61], v[2:3], off offset:160
	v_cvt_pk_bf16_f32 v2, v30, v31
	v_cvt_pk_bf16_f32 v3, v32, v33
	global_store_dwordx2 v[58:59], v[2:3], off offset:176
	v_cvt_pk_bf16_f32 v2, v14, v15
	v_cvt_pk_bf16_f32 v3, v16, v17
	global_store_dwordx2 v[60:61], v[2:3], off offset:176
	s_nop 0
	s_nop 0
	s_waitcnt vmcnt(11)
	v_mfma_f32_32x32x16_bf16 v[18:33], v[220:223], v[34:37], 0
	s_nop 0
	v_mfma_f32_32x32x16_bf16 v[2:17], v[220:223], v[38:41], 0
	s_nop 0
	s_waitcnt vmcnt(10)
	v_mfma_f32_32x32x16_bf16 v[18:33], v[234:237], v[42:45], v[18:33]
	s_nop 11
	v_cvt_pk_bf16_f32 v18, v18, v19
	v_mfma_f32_32x32x16_bf16 v[2:17], v[234:237], v[46:49], v[2:17]
	s_nop 0
	v_cvt_pk_bf16_f32 v19, v20, v21
	s_nop 0
	s_waitcnt vmcnt(9)
	v_mfma_f32_32x32x16_bf16 v[2:17], v[238:241], v[50:53], v[2:17]
	s_nop 0
	s_nop 0
	global_store_dwordx2 v[58:59], v[18:19], off offset:192
	s_nop 0
	s_waitcnt vmcnt(9)
	v_mfma_f32_32x32x16_bf16 v[2:17], v[242:245], v[54:57], v[2:17]
	s_nop 11
	v_cvt_pk_bf16_f32 v2, v2, v3
	v_cvt_pk_bf16_f32 v3, v4, v5
	global_store_dwordx2 v[60:61], v[2:3], off offset:192
	v_cvt_pk_bf16_f32 v2, v22, v23
	v_cvt_pk_bf16_f32 v3, v24, v25
	global_store_dwordx2 v[58:59], v[2:3], off offset:208
	v_cvt_pk_bf16_f32 v2, v6, v7
	v_cvt_pk_bf16_f32 v3, v8, v9
	global_store_dwordx2 v[60:61], v[2:3], off offset:208
	v_cvt_pk_bf16_f32 v2, v26, v27
	v_cvt_pk_bf16_f32 v3, v28, v29
	global_store_dwordx2 v[58:59], v[2:3], off offset:224
	v_cvt_pk_bf16_f32 v2, v10, v11
	v_cvt_pk_bf16_f32 v3, v12, v13
	global_store_dwordx2 v[60:61], v[2:3], off offset:224
	v_cvt_pk_bf16_f32 v2, v30, v31
	v_cvt_pk_bf16_f32 v3, v32, v33
	global_store_dwordx2 v[58:59], v[2:3], off offset:240
	v_cvt_pk_bf16_f32 v2, v14, v15
	v_cvt_pk_bf16_f32 v3, v16, v17
	global_store_dwordx2 v[60:61], v[2:3], off offset:240
	s_waitcnt lgkmcnt(0)
	s_cbranch_scc0 .LBB0_782

	.amdhsa_kernel _Z3fwd4Args
		.amdhsa_group_segment_fixed_size 0
		.amdhsa_private_segment_fixed_size 0
		.amdhsa_kernarg_size 448
		.amdhsa_user_sgpr_count 2
		.amdhsa_user_sgpr_dispatch_ptr 0
		.amdhsa_user_sgpr_queue_ptr 0
		.amdhsa_user_sgpr_kernarg_segment_ptr 1
		.amdhsa_user_sgpr_dispatch_id 0
		.amdhsa_user_sgpr_kernarg_preload_length 0
		.amdhsa_user_sgpr_kernarg_preload_offset 0
		.amdhsa_user_sgpr_private_segment_size 0
		.amdhsa_uses_dynamic_stack 0
		.amdhsa_enable_private_segment 0
		.amdhsa_system_sgpr_workgroup_id_x 1
		.amdhsa_system_sgpr_workgroup_id_y 0
		.amdhsa_system_sgpr_workgroup_id_z 0
		.amdhsa_system_sgpr_workgroup_info 0
		.amdhsa_system_vgpr_workitem_id 0
		.amdhsa_next_free_vgpr 253
		.amdhsa_next_free_sgpr 99
		.amdhsa_accum_offset 256
		.amdhsa_reserve_vcc 1
		.amdhsa_float_round_mode_32 0
		.amdhsa_float_round_mode_16_64 0
		.amdhsa_float_denorm_mode_32 3
		.amdhsa_float_denorm_mode_16_64 3
		.amdhsa_dx10_clamp 1
		.amdhsa_ieee_mode 1
		.amdhsa_fp16_overflow 0
		.amdhsa_tg_split 0
		.amdhsa_exception_fp_ieee_invalid_op 0
		.amdhsa_exception_fp_denorm_src 0
		.amdhsa_exception_fp_ieee_div_zero 0
		.amdhsa_exception_fp_ieee_overflow 0
		.amdhsa_exception_fp_ieee_underflow 0
		.amdhsa_exception_fp_ieee_inexact 0
		.amdhsa_exception_int_div_zero 0
	.end_amdhsa_kernel

amdhsa.kernels:
  - .agpr_count:     0
    .args:
      - .offset:         0
        .size:           192
        .value_kind:     by_value
      - .offset:         192
        .size:           4
        .value_kind:     hidden_block_count_x
      - .offset:         196
        .size:           4
        .value_kind:     hidden_block_count_y
      - .offset:         200
        .size:           4
        .value_kind:     hidden_block_count_z
      - .offset:         204
        .size:           2
        .value_kind:     hidden_group_size_x
      - .offset:         206
        .size:           2
        .value_kind:     hidden_group_size_y
      - .offset:         208
        .size:           2
        .value_kind:     hidden_group_size_z
      - .offset:         210
        .size:           2
        .value_kind:     hidden_remainder_x
      - .offset:         212
        .size:           2
        .value_kind:     hidden_remainder_y
      - .offset:         214
        .size:           2
        .value_kind:     hidden_remainder_z
      - .offset:         232
        .size:           8
        .value_kind:     hidden_global_offset_x
      - .offset:         240
        .size:           8
        .value_kind:     hidden_global_offset_y
      - .offset:         248
        .size:           8
        .value_kind:     hidden_global_offset_z
      - .offset:         256
        .size:           2
        .value_kind:     hidden_grid_dims
      - .offset:         312
        .size:           4
        .value_kind:     hidden_dynamic_lds_size
    .group_segment_fixed_size: 0
    .kernarg_segment_align: 8
    .kernarg_segment_size: 448
    .language:       OpenCL C
    .language_version:
      - 2
      - 0
    .max_flat_workgroup_size: 512
    .name:           _Z3fwd4Args
    .private_segment_fixed_size: 0
    .sgpr_count:     105
    .sgpr_spill_count: 171
    .symbol:         _Z3fwd4Args.kd
    .uniform_work_group_size: 1
    .uses_dynamic_stack: false
    .vgpr_count:     253
    .vgpr_spill_count: 0
    .wavefront_size: 64
